# P0 prologue: non-temporal (nt) policy on the once-read f32 input and weight loads
# speedup vs baseline: 1.0042x; 1.0032x over previous
.LBB0_15:
	v_readlane_b32 s4, v236, 4
	v_readlane_b32 s5, v236, 5
	s_cmp_lt_i32 s4, 1
	s_cselect_b64 s[0:1], -1, 0
	s_cmp_gt_i32 s5, 0
	s_cselect_b64 s[4:5], -1, 0
	s_and_b64 s[0:1], s[0:1], s[4:5]
	s_andn2_b64 vcc, exec, s[0:1]
	s_cbranch_vccnz .LBB0_106
	v_mov_b32_e32 v44, v182
	s_movk_i32 s4, 0x1000
	s_nop 0
	v_readfirstlane_b32 s3, v44
	v_cmp_gt_i32_e32 vcc, s4, v44
	s_and_saveexec_b64 s[6:7], vcc
	s_cbranch_execz .LBB0_19
	v_lshlrev_b32_e32 v1, 2, v44
	s_movk_i32 s4, 0x3040
	s_waitcnt lgkmcnt(0)
	v_mov_b64_e32 v[2:3], s[58:59]
	v_mov_b32_e32 v5, 0
	v_ashrrev_i32_e32 v8, 2, v44
	v_and_b32_e32 v7, 12, v1
	v_mad_i64_i32 v[10:11], s[10:11], v8, s4, v[2:3]
	v_lshlrev_b32_e32 v4, 2, v7
	v_lshl_add_u64 v[10:11], v[10:11], 0, v[4:5]
	v_ashrrev_i32_e32 v9, 31, v8
	v_add_co_u32_e32 v10, vcc, 0x3000, v10
	v_lshl_add_u64 v[8:9], v[8:9], 2, s[54:55]
	s_nop 0
	v_addc_co_u32_e32 v11, vcc, 0, v11, vcc
	v_and_b32_e32 v12, -4, v44
	v_lshlrev_b32_e32 v7, 12, v7
	v_add3_u32 v7, 0, v7, v12
	s_mov_b32 s8, 0x182000
	s_mov_b32 s9, 0
	global_load_dword v48, v[8:9], off nt
	global_load_dwordx4 v[16:19], v[10:11], off nt
	v_lshl_add_u64 v[12:13], v[10:11], 0, s[8:9]
	global_load_dword v49, v[8:9], off offset:512 nt
	global_load_dwordx4 v[20:23], v[12:13], off nt
	v_lshl_add_u64 v[12:13], v[12:13], 0, s[8:9]
	global_load_dword v50, v[8:9], off offset:1024 nt
	global_load_dwordx4 v[24:27], v[12:13], off nt
	v_lshl_add_u64 v[12:13], v[12:13], 0, s[8:9]
	global_load_dword v51, v[8:9], off offset:1536 nt
	global_load_dwordx4 v[28:31], v[12:13], off nt
	v_lshl_add_u64 v[12:13], v[12:13], 0, s[8:9]
	global_load_dword v52, v[8:9], off offset:2048 nt
	global_load_dwordx4 v[32:35], v[12:13], off nt
	v_lshl_add_u64 v[12:13], v[12:13], 0, s[8:9]
	global_load_dword v53, v[8:9], off offset:2560 nt
	global_load_dwordx4 v[36:39], v[12:13], off nt
	v_lshl_add_u64 v[12:13], v[12:13], 0, s[8:9]
	global_load_dword v54, v[8:9], off offset:3072 nt
	global_load_dwordx4 v[40:43], v[12:13], off nt
	v_lshl_add_u64 v[12:13], v[12:13], 0, s[8:9]
	global_load_dword v55, v[8:9], off offset:3584 nt
	global_load_dwordx4 v[56:59], v[12:13], off nt
	s_waitcnt vmcnt(14)
	v_mul_f32_e32 v16, v16, v48
	v_mul_f32_e32 v17, v17, v48
	v_mul_f32_e32 v18, v18, v48
	v_mul_f32_e32 v19, v19, v48
	ds_write2st64_b32 v7, v16, v17 offset0:0 offset1:16
	ds_write2st64_b32 v7, v18, v19 offset0:32 offset1:48
	s_waitcnt vmcnt(12)
	v_mul_f32_e32 v20, v20, v49
	v_mul_f32_e32 v21, v21, v49
	v_mul_f32_e32 v22, v22, v49
	v_mul_f32_e32 v23, v23, v49
	ds_write2st64_b32 v7, v20, v21 offset0:2 offset1:18
	ds_write2st64_b32 v7, v22, v23 offset0:34 offset1:50
	s_waitcnt vmcnt(10)
	v_mul_f32_e32 v24, v24, v50
	v_mul_f32_e32 v25, v25, v50
	v_mul_f32_e32 v26, v26, v50
	v_mul_f32_e32 v27, v27, v50
	ds_write2st64_b32 v7, v24, v25 offset0:4 offset1:20
	ds_write2st64_b32 v7, v26, v27 offset0:36 offset1:52
	s_waitcnt vmcnt(8)
	v_mul_f32_e32 v28, v28, v51
	v_mul_f32_e32 v29, v29, v51
	v_mul_f32_e32 v30, v30, v51
	v_mul_f32_e32 v31, v31, v51
	ds_write2st64_b32 v7, v28, v29 offset0:6 offset1:22
	ds_write2st64_b32 v7, v30, v31 offset0:38 offset1:54
	s_waitcnt vmcnt(6)
	v_mul_f32_e32 v32, v32, v52
	v_mul_f32_e32 v33, v33, v52
	v_mul_f32_e32 v34, v34, v52
	v_mul_f32_e32 v35, v35, v52
	ds_write2st64_b32 v7, v32, v33 offset0:8 offset1:24
	ds_write2st64_b32 v7, v34, v35 offset0:40 offset1:56
	s_waitcnt vmcnt(4)
	v_mul_f32_e32 v36, v36, v53
	v_mul_f32_e32 v37, v37, v53
	v_mul_f32_e32 v38, v38, v53
	v_mul_f32_e32 v39, v39, v53
	ds_write2st64_b32 v7, v36, v37 offset0:10 offset1:26
	ds_write2st64_b32 v7, v38, v39 offset0:42 offset1:58
	s_waitcnt vmcnt(2)
	v_mul_f32_e32 v40, v40, v54
	v_mul_f32_e32 v41, v41, v54
	v_mul_f32_e32 v42, v42, v54
	v_mul_f32_e32 v43, v43, v54
	ds_write2st64_b32 v7, v40, v41 offset0:12 offset1:28
	ds_write2st64_b32 v7, v42, v43 offset0:44 offset1:60
	s_waitcnt vmcnt(0)
	v_mul_f32_e32 v56, v56, v55
	v_mul_f32_e32 v57, v57, v55
	v_mul_f32_e32 v58, v58, v55
	v_mul_f32_e32 v59, v59, v55
	ds_write2st64_b32 v7, v56, v57 offset0:14 offset1:30
	ds_write2st64_b32 v7, v58, v59 offset0:46 offset1:62

.LBB0_22:
	s_add_i32 s34, s26, s20
	s_cmpk_gt_i32 s34, 0x3fff
	s_cselect_b64 s[52:53], -1, 0
	s_and_b64 vcc, exec, s[52:53]
	s_cbranch_vccnz .LBB0_24
	s_ashr_i32 s35, s34, 31
	s_lshl_b64 s[60:61], s[34:35], 12
	v_lshl_add_u64 v[14:15], v[36:37], 0, s[60:61]
	global_load_dwordx4 v[2:5], v[14:15], off nt
	global_load_dwordx4 v[6:9], v[14:15], off offset:1024 nt
	global_load_dwordx4 v[10:13], v[14:15], off offset:2048 nt
	s_nop 0
	global_load_dwordx4 v[14:17], v[14:15], off offset:3072 nt

.LBB0_26:
	s_or_b64 exec, exec, s[60:61]
	v_bfe_u32 v55, v30, 16, 1
	v_add3_u32 v55, v30, v55, s19
	v_bfe_u32 v58, v31, 16, 1
	v_lshrrev_b32_e32 v55, 16, v55
	v_add3_u32 v58, v31, v58, s19
	v_and_or_b32 v58, v58, s21, v55
	v_bfe_u32 v55, v32, 16, 1
	v_add3_u32 v55, v32, v55, s19
	v_bfe_u32 v59, v33, 16, 1
	v_lshrrev_b32_e32 v55, 16, v55
	v_add3_u32 v59, v33, v59, s19
	v_lshl_add_u64 v[56:57], s[72:73], 0, v[40:41]
	v_and_or_b32 v59, v59, s21, v55
	v_bfe_u32 v55, v26, 16, 1
	v_add_co_u32_e32 v60, vcc, s33, v56
	v_add3_u32 v55, v26, v55, s19
	v_bfe_u32 v56, v27, 16, 1
	v_lshrrev_b32_e32 v55, 16, v55
	v_add3_u32 v56, v27, v56, s19
	v_and_or_b32 v56, v56, s21, v55
	v_bfe_u32 v55, v28, 16, 1
	v_addc_co_u32_e32 v61, vcc, 0, v57, vcc
	v_add3_u32 v55, v28, v55, s19
	v_bfe_u32 v57, v29, 16, 1
	v_lshrrev_b32_e32 v55, 16, v55
	v_add3_u32 v57, v29, v57, s19
	v_and_or_b32 v57, v57, s21, v55
	v_bfe_u32 v55, v22, 16, 1
	global_store_dwordx2 v[60:61], v[56:57], off offset:512
	v_add3_u32 v55, v22, v55, s19
	v_bfe_u32 v56, v23, 16, 1
	v_lshrrev_b32_e32 v55, 16, v55
	v_add3_u32 v56, v23, v56, s19
	v_and_or_b32 v56, v56, s21, v55
	v_bfe_u32 v55, v24, 16, 1
	v_add3_u32 v55, v24, v55, s19
	v_bfe_u32 v57, v25, 16, 1
	v_lshrrev_b32_e32 v55, 16, v55
	v_add3_u32 v57, v25, v57, s19
	v_and_or_b32 v57, v57, s21, v55
	v_bfe_u32 v55, v18, 16, 1
	global_store_dwordx2 v[60:61], v[56:57], off offset:1024
	v_add3_u32 v55, v18, v55, s19
	v_bfe_u32 v56, v19, 16, 1
	v_lshrrev_b32_e32 v55, 16, v55
	v_add3_u32 v56, v19, v56, s19
	v_and_or_b32 v62, v56, s21, v55
	v_bfe_u32 v55, v20, 16, 1
	v_add3_u32 v55, v20, v55, s19
	v_bfe_u32 v63, v21, 16, 1
	global_store_dwordx2 v[60:61], v[58:59], off
	v_lshrrev_b32_e32 v55, 16, v55
	ds_read_b128 v[56:59], v51
	v_add3_u32 v63, v21, v63, s19
	v_and_or_b32 v63, v63, s21, v55
	global_store_dwordx2 v[60:61], v[62:63], off offset:1536
	ds_read_b128 v[60:63], v51 offset:1024
	s_waitcnt lgkmcnt(1)
	v_mul_f32_e32 v55, v31, v57
	v_fmac_f32_e32 v55, v30, v56
	v_mul_f32_e32 v56, v33, v59
	v_fmac_f32_e32 v56, v32, v58
	s_waitcnt lgkmcnt(0)
	v_mul_f32_e32 v61, v27, v61
	v_add_f32_e32 v55, v55, v56
	v_fmac_f32_e32 v61, v26, v60
	v_mul_f32_e32 v60, v29, v63
	ds_read_b128 v[56:59], v51 offset:2048
	v_fmac_f32_e32 v60, v28, v62
	v_add_f32_e32 v55, 0, v55
	v_add_f32_e32 v60, v61, v60
	v_add_f32_e32 v55, v55, v60
	ds_read_b128 v[60:63], v51 offset:3072
	s_waitcnt lgkmcnt(1)
	v_mul_f32_e32 v57, v23, v57
	v_fmac_f32_e32 v57, v22, v56
	v_mul_f32_e32 v56, v25, v59
	v_fmac_f32_e32 v56, v24, v58
	v_add_f32_e32 v56, v57, v56
	s_waitcnt lgkmcnt(0)
	v_mul_f32_e32 v64, v19, v61
	v_mul_f32_e32 v65, v21, v63
	v_add_f32_e32 v55, v55, v56
	v_fmac_f32_e32 v64, v18, v60
	v_fmac_f32_e32 v65, v20, v62
	ds_read_b128 v[56:59], v51 offset:5120
	ds_read_b128 v[60:63], v51 offset:4096
	v_add_f32_e32 v64, v64, v65
	v_add_f32_e32 v55, v55, v64
	ds_read_b128 v[64:67], v51 offset:7168
	ds_read_b128 v[68:71], v51 offset:6144
	s_waitcnt lgkmcnt(3)
	v_mul_f32_e32 v57, v27, v57
	s_waitcnt lgkmcnt(2)
	v_mul_f32_e32 v61, v31, v61
	v_fmac_f32_e32 v61, v30, v60
	v_mul_f32_e32 v60, v33, v63
	v_fmac_f32_e32 v57, v26, v56
	v_mul_f32_e32 v56, v29, v59
	v_fmac_f32_e32 v60, v32, v62
	v_fmac_f32_e32 v56, v28, v58
	v_add_f32_e32 v60, v61, v60
	v_add_f32_e32 v56, v57, v56
	s_waitcnt lgkmcnt(0)
	v_mul_f32_e32 v57, v23, v69
	v_mul_f32_e32 v58, v25, v71
	v_add_f32_e32 v60, 0, v60
	v_fmac_f32_e32 v57, v22, v68
	v_fmac_f32_e32 v58, v24, v70
	v_add_f32_e32 v56, v60, v56
	v_add_f32_e32 v57, v57, v58
	v_add_f32_e32 v56, v56, v57
	v_mul_f32_e32 v57, v19, v65
	v_fmac_f32_e32 v57, v18, v64
	ds_read_b128 v[58:61], v51 offset:9216
	ds_read_b128 v[62:65], v51 offset:8192
	v_mul_f32_e32 v67, v21, v67
	v_fmac_f32_e32 v67, v20, v66
	v_add_f32_e32 v57, v57, v67
	v_add_f32_e32 v56, v56, v57
	ds_read_b128 v[66:69], v51 offset:11264
	ds_read_b128 v[70:73], v51 offset:10240
	s_waitcnt lgkmcnt(2)
	v_mul_f32_e32 v57, v31, v63
	v_fmac_f32_e32 v57, v30, v62
	v_mul_f32_e32 v62, v33, v65
	v_mul_f32_e32 v59, v27, v59
	v_fmac_f32_e32 v62, v32, v64
	v_fmac_f32_e32 v59, v26, v58
	v_mul_f32_e32 v58, v29, v61
	v_add_f32_e32 v57, v57, v62
	v_fmac_f32_e32 v58, v28, v60
	v_add_f32_e32 v57, 0, v57
	v_add_f32_e32 v58, v59, v58
	v_add_f32_e32 v57, v57, v58
	s_waitcnt lgkmcnt(0)
	v_mul_f32_e32 v58, v23, v71
	v_mul_f32_e32 v59, v25, v73
	v_fmac_f32_e32 v58, v22, v70
	v_fmac_f32_e32 v59, v24, v72
	v_add_f32_e32 v58, v58, v59
	v_mul_f32_e32 v67, v19, v67
	v_add_f32_e32 v57, v57, v58
	v_fmac_f32_e32 v67, v18, v66
	v_mul_f32_e32 v66, v21, v69
	ds_read_b128 v[58:61], v51 offset:13312
	ds_read_b128 v[62:65], v51 offset:12288
	v_fmac_f32_e32 v66, v20, v68
	v_add_f32_e32 v66, v67, v66
	v_add_f32_e32 v57, v57, v66
	ds_read_b128 v[66:69], v51 offset:15360
	ds_read_b128 v[70:73], v51 offset:14336
	s_waitcnt lgkmcnt(2)
	v_mul_f32_e32 v63, v31, v63
	v_mul_f32_e32 v59, v27, v59
	v_fmac_f32_e32 v63, v30, v62
	v_mul_f32_e32 v62, v33, v65
	v_fmac_f32_e32 v59, v26, v58
	v_mul_f32_e32 v58, v29, v61
	v_fmac_f32_e32 v62, v32, v64
	v_fmac_f32_e32 v58, v28, v60
	v_add_f32_e32 v62, v63, v62
	v_add_f32_e32 v58, v59, v58
	s_waitcnt lgkmcnt(0)
	v_mul_f32_e32 v59, v23, v71
	v_mul_f32_e32 v60, v25, v73
	v_add_f32_e32 v62, 0, v62
	v_fmac_f32_e32 v59, v22, v70
	v_fmac_f32_e32 v60, v24, v72
	v_add_f32_e32 v58, v62, v58
	v_add_f32_e32 v59, v59, v60
	v_add_f32_e32 v58, v58, v59
	v_mul_f32_e32 v59, v19, v67
	v_mul_f32_e32 v64, v21, v69
	ds_read_b128 v[60:63], v51 offset:16384
	v_fmac_f32_e32 v59, v18, v66
	v_fmac_f32_e32 v64, v20, v68
	v_add_f32_e32 v59, v59, v64
	ds_read_b128 v[64:67], v51 offset:17408
	v_add_f32_e32 v58, v58, v59
	s_waitcnt lgkmcnt(1)
	v_mul_f32_e32 v59, v31, v61
	v_fmac_f32_e32 v59, v30, v60
	v_mul_f32_e32 v60, v33, v63
	v_fmac_f32_e32 v60, v32, v62
	s_waitcnt lgkmcnt(0)
	v_mul_f32_e32 v65, v27, v65
	v_add_f32_e32 v59, v59, v60
	v_fmac_f32_e32 v65, v26, v64
	v_mul_f32_e32 v64, v29, v67
	ds_read_b128 v[60:63], v51 offset:18432
	v_fmac_f32_e32 v64, v28, v66
	v_add_f32_e32 v59, 0, v59
	v_add_f32_e32 v64, v65, v64
	v_add_f32_e32 v59, v59, v64
	ds_read_b128 v[64:67], v51 offset:19456
	s_waitcnt lgkmcnt(1)
	v_mul_f32_e32 v61, v23, v61
	v_fmac_f32_e32 v61, v22, v60
	v_mul_f32_e32 v60, v25, v63
	v_fmac_f32_e32 v60, v24, v62
	v_add_f32_e32 v60, v61, v60
	s_waitcnt lgkmcnt(0)
	v_mul_f32_e32 v68, v19, v65
	v_mul_f32_e32 v69, v21, v67
	v_add_f32_e32 v59, v59, v60
	v_fmac_f32_e32 v68, v18, v64
	v_fmac_f32_e32 v69, v20, v66
	ds_read_b128 v[60:63], v51 offset:21504
	ds_read_b128 v[64:67], v51 offset:20480
	v_add_f32_e32 v68, v68, v69
	v_add_f32_e32 v59, v59, v68
	ds_read_b128 v[68:71], v51 offset:23552
	ds_read_b128 v[72:75], v51 offset:22528
	s_waitcnt lgkmcnt(3)
	v_mul_f32_e32 v61, v27, v61
	s_waitcnt lgkmcnt(2)
	v_mul_f32_e32 v65, v31, v65
	v_fmac_f32_e32 v65, v30, v64
	v_mul_f32_e32 v64, v33, v67
	v_fmac_f32_e32 v61, v26, v60
	v_mul_f32_e32 v60, v29, v63
	v_fmac_f32_e32 v64, v32, v66
	v_fmac_f32_e32 v60, v28, v62
	v_add_f32_e32 v64, v65, v64
	v_add_f32_e32 v60, v61, v60
	s_waitcnt lgkmcnt(0)
	v_mul_f32_e32 v61, v23, v73
	v_mul_f32_e32 v62, v25, v75
	v_add_f32_e32 v64, 0, v64
	v_fmac_f32_e32 v61, v22, v72
	v_fmac_f32_e32 v62, v24, v74
	v_add_f32_e32 v60, v64, v60
	v_add_f32_e32 v61, v61, v62
	v_mul_f32_e32 v69, v19, v69
	v_add_f32_e32 v72, v60, v61
	v_fmac_f32_e32 v69, v18, v68
	v_mul_f32_e32 v68, v21, v71
	ds_read_b128 v[60:63], v51 offset:25600
	ds_read_b128 v[64:67], v51 offset:24576
	v_fmac_f32_e32 v68, v20, v70
	v_add_f32_e32 v68, v69, v68
	v_add_f32_e32 v76, v72, v68
	ds_read_b128 v[68:71], v51 offset:27648
	ds_read_b128 v[72:75], v51 offset:26624
	s_waitcnt lgkmcnt(2)
	v_mul_f32_e32 v65, v31, v65
	v_mul_f32_e32 v61, v27, v61
	v_fmac_f32_e32 v65, v30, v64
	v_mul_f32_e32 v64, v33, v67
	v_fmac_f32_e32 v61, v26, v60
	v_mul_f32_e32 v60, v29, v63
	v_fmac_f32_e32 v64, v32, v66
	v_fmac_f32_e32 v60, v28, v62
	v_add_f32_e32 v64, v65, v64
	v_add_f32_e32 v60, v61, v60
	s_waitcnt lgkmcnt(0)
	v_mul_f32_e32 v61, v23, v73
	v_mul_f32_e32 v62, v25, v75
	v_add_f32_e32 v64, 0, v64
	v_fmac_f32_e32 v61, v22, v72
	v_fmac_f32_e32 v62, v24, v74
	v_add_f32_e32 v60, v64, v60
	v_add_f32_e32 v61, v61, v62
	v_mul_f32_e32 v69, v19, v69
	v_add_f32_e32 v72, v60, v61
	v_fmac_f32_e32 v69, v18, v68
	v_mul_f32_e32 v68, v21, v71
	ds_read_b128 v[60:63], v51 offset:29696
	ds_read_b128 v[64:67], v51 offset:28672
	v_fmac_f32_e32 v68, v20, v70
	v_add_f32_e32 v68, v69, v68
	v_add_f32_e32 v77, v72, v68
	ds_read_b128 v[68:71], v51 offset:31744
	ds_read_b128 v[72:75], v51 offset:30720
	s_waitcnt lgkmcnt(2)
	v_mul_f32_e32 v65, v31, v65
	v_mul_f32_e32 v61, v27, v61
	v_fmac_f32_e32 v65, v30, v64
	v_mul_f32_e32 v64, v33, v67
	v_fmac_f32_e32 v61, v26, v60
	v_mul_f32_e32 v60, v29, v63
	v_fmac_f32_e32 v64, v32, v66
	v_fmac_f32_e32 v60, v28, v62
	v_add_f32_e32 v64, v65, v64
	v_add_f32_e32 v60, v61, v60
	s_waitcnt lgkmcnt(0)
	v_mul_f32_e32 v61, v23, v73
	v_mul_f32_e32 v62, v25, v75
	v_add_f32_e32 v64, 0, v64
	v_fmac_f32_e32 v61, v22, v72
	v_fmac_f32_e32 v62, v24, v74
	v_add_f32_e32 v60, v64, v60
	v_add_f32_e32 v61, v61, v62
	v_add_f32_e32 v64, v60, v61
	v_mul_f32_e32 v65, v19, v69
	v_mul_f32_e32 v66, v21, v71
	ds_read_b128 v[60:63], v51 offset:32768
	v_fmac_f32_e32 v65, v18, v68
	v_fmac_f32_e32 v66, v20, v70
	v_add_f32_e32 v65, v65, v66
	v_add_f32_e32 v78, v64, v65
	ds_read_b128 v[64:67], v51 offset:33792
	s_waitcnt lgkmcnt(1)
	v_mul_f32_e32 v61, v31, v61
	v_fmac_f32_e32 v61, v30, v60
	v_mul_f32_e32 v60, v33, v63
	v_fmac_f32_e32 v60, v32, v62
	v_add_f32_e32 v60, v61, v60
	s_waitcnt lgkmcnt(0)
	v_mul_f32_e32 v65, v27, v65
	v_add_f32_e32 v68, 0, v60
	v_fmac_f32_e32 v65, v26, v64
	v_mul_f32_e32 v64, v29, v67
	ds_read_b128 v[60:63], v51 offset:34816
	v_fmac_f32_e32 v64, v28, v66
	v_add_f32_e32 v64, v65, v64
	v_add_f32_e32 v68, v68, v64
	ds_read_b128 v[64:67], v51 offset:35840
	s_waitcnt lgkmcnt(1)
	v_mul_f32_e32 v61, v23, v61
	v_fmac_f32_e32 v61, v22, v60
	v_mul_f32_e32 v60, v25, v63
	v_fmac_f32_e32 v60, v24, v62
	v_add_f32_e32 v60, v61, v60
	s_waitcnt lgkmcnt(0)
	v_mul_f32_e32 v69, v19, v65
	v_mul_f32_e32 v70, v21, v67
	v_add_f32_e32 v68, v68, v60
	v_fmac_f32_e32 v69, v18, v64
	v_fmac_f32_e32 v70, v20, v66
	ds_read_b128 v[60:63], v51 offset:37888
	ds_read_b128 v[64:67], v51 offset:36864
	v_add_f32_e32 v69, v69, v70
	v_add_f32_e32 v79, v68, v69
	ds_read_b128 v[68:71], v51 offset:39936
	ds_read_b128 v[72:75], v51 offset:38912
	s_waitcnt lgkmcnt(3)
	v_mul_f32_e32 v61, v27, v61
	s_waitcnt lgkmcnt(2)
	v_mul_f32_e32 v65, v31, v65
	v_fmac_f32_e32 v65, v30, v64
	v_mul_f32_e32 v64, v33, v67
	v_fmac_f32_e32 v61, v26, v60
	v_mul_f32_e32 v60, v29, v63
	v_fmac_f32_e32 v64, v32, v66
	v_fmac_f32_e32 v60, v28, v62
	v_add_f32_e32 v64, v65, v64
	v_add_f32_e32 v60, v61, v60
	s_waitcnt lgkmcnt(0)
	v_mul_f32_e32 v61, v23, v73
	v_mul_f32_e32 v62, v25, v75
	v_add_f32_e32 v64, 0, v64
	v_fmac_f32_e32 v61, v22, v72
	v_fmac_f32_e32 v62, v24, v74
	v_add_f32_e32 v60, v64, v60
	v_add_f32_e32 v61, v61, v62
	v_mul_f32_e32 v69, v19, v69
	v_add_f32_e32 v72, v60, v61
	v_fmac_f32_e32 v69, v18, v68
	v_mul_f32_e32 v68, v21, v71
	ds_read_b128 v[60:63], v51 offset:41984
	ds_read_b128 v[64:67], v51 offset:40960
	v_fmac_f32_e32 v68, v20, v70
	v_add_f32_e32 v68, v69, v68
	v_add_f32_e32 v80, v72, v68
	ds_read_b128 v[68:71], v51 offset:44032
	ds_read_b128 v[72:75], v51 offset:43008
	s_waitcnt lgkmcnt(2)
	v_mul_f32_e32 v65, v31, v65
	v_mul_f32_e32 v61, v27, v61
	v_fmac_f32_e32 v65, v30, v64
	v_mul_f32_e32 v64, v33, v67
	v_fmac_f32_e32 v61, v26, v60
	v_mul_f32_e32 v60, v29, v63
	v_fmac_f32_e32 v64, v32, v66
	v_fmac_f32_e32 v60, v28, v62
	v_add_f32_e32 v64, v65, v64
	v_add_f32_e32 v60, v61, v60
	s_waitcnt lgkmcnt(0)
	v_mul_f32_e32 v61, v23, v73
	v_mul_f32_e32 v62, v25, v75
	v_add_f32_e32 v64, 0, v64
	v_fmac_f32_e32 v61, v22, v72
	v_fmac_f32_e32 v62, v24, v74
	v_add_f32_e32 v60, v64, v60
	v_add_f32_e32 v61, v61, v62
	v_mul_f32_e32 v69, v19, v69
	v_add_f32_e32 v72, v60, v61
	v_fmac_f32_e32 v69, v18, v68
	v_mul_f32_e32 v68, v21, v71
	ds_read_b128 v[60:63], v51 offset:46080
	ds_read_b128 v[64:67], v51 offset:45056
	v_fmac_f32_e32 v68, v20, v70
	v_add_f32_e32 v68, v69, v68
	v_add_f32_e32 v81, v72, v68
	ds_read_b128 v[68:71], v51 offset:48128
	ds_read_b128 v[72:75], v51 offset:47104
	s_waitcnt lgkmcnt(2)
	v_mul_f32_e32 v65, v31, v65
	v_mul_f32_e32 v61, v27, v61
	v_fmac_f32_e32 v65, v30, v64
	v_mul_f32_e32 v64, v33, v67
	v_fmac_f32_e32 v61, v26, v60
	v_mul_f32_e32 v60, v29, v63
	v_fmac_f32_e32 v64, v32, v66
	v_fmac_f32_e32 v60, v28, v62
	v_add_f32_e32 v64, v65, v64
	v_add_f32_e32 v60, v61, v60
	s_waitcnt lgkmcnt(0)
	v_mul_f32_e32 v61, v23, v73
	v_mul_f32_e32 v62, v25, v75
	v_add_f32_e32 v64, 0, v64
	v_fmac_f32_e32 v61, v22, v72
	v_fmac_f32_e32 v62, v24, v74
	v_add_f32_e32 v60, v64, v60
	v_add_f32_e32 v61, v61, v62
	v_add_f32_e32 v64, v60, v61
	v_mul_f32_e32 v65, v19, v69
	v_mul_f32_e32 v66, v21, v71
	ds_read_b128 v[60:63], v51 offset:49152
	v_fmac_f32_e32 v65, v18, v68
	v_fmac_f32_e32 v66, v20, v70
	v_add_f32_e32 v65, v65, v66
	v_add_f32_e32 v82, v64, v65
	ds_read_b128 v[64:67], v51 offset:50176
	s_waitcnt lgkmcnt(1)
	v_mul_f32_e32 v61, v31, v61
	v_fmac_f32_e32 v61, v30, v60
	v_mul_f32_e32 v60, v33, v63
	v_fmac_f32_e32 v60, v32, v62
	v_add_f32_e32 v60, v61, v60
	s_waitcnt lgkmcnt(0)
	v_mul_f32_e32 v65, v27, v65
	v_add_f32_e32 v68, 0, v60
	v_fmac_f32_e32 v65, v26, v64
	v_mul_f32_e32 v64, v29, v67
	ds_read_b128 v[60:63], v51 offset:51200
	v_fmac_f32_e32 v64, v28, v66
	v_add_f32_e32 v64, v65, v64
	v_add_f32_e32 v68, v68, v64
	ds_read_b128 v[64:67], v51 offset:52224
	s_waitcnt lgkmcnt(1)
	v_mul_f32_e32 v61, v23, v61
	v_fmac_f32_e32 v61, v22, v60
	v_mul_f32_e32 v60, v25, v63
	v_fmac_f32_e32 v60, v24, v62
	v_add_f32_e32 v60, v61, v60
	s_waitcnt lgkmcnt(0)
	v_mul_f32_e32 v69, v19, v65
	v_mul_f32_e32 v70, v21, v67
	v_add_f32_e32 v68, v68, v60
	v_fmac_f32_e32 v69, v18, v64
	v_fmac_f32_e32 v70, v20, v66
	ds_read_b128 v[60:63], v51 offset:54272
	ds_read_b128 v[64:67], v51 offset:53248
	v_add_f32_e32 v69, v69, v70
	v_add_f32_e32 v83, v68, v69
	ds_read_b128 v[68:71], v51 offset:56320
	ds_read_b128 v[72:75], v51 offset:55296
	s_waitcnt lgkmcnt(3)
	v_mul_f32_e32 v61, v27, v61
	s_waitcnt lgkmcnt(2)
	v_mul_f32_e32 v65, v31, v65
	v_fmac_f32_e32 v65, v30, v64
	v_mul_f32_e32 v64, v33, v67
	v_fmac_f32_e32 v61, v26, v60
	v_mul_f32_e32 v60, v29, v63
	v_fmac_f32_e32 v64, v32, v66
	v_fmac_f32_e32 v60, v28, v62
	v_add_f32_e32 v64, v65, v64
	v_add_f32_e32 v60, v61, v60
	s_waitcnt lgkmcnt(0)
	v_mul_f32_e32 v61, v23, v73
	v_mul_f32_e32 v62, v25, v75
	v_add_f32_e32 v64, 0, v64
	v_fmac_f32_e32 v61, v22, v72
	v_fmac_f32_e32 v62, v24, v74
	v_add_f32_e32 v60, v64, v60
	v_add_f32_e32 v61, v61, v62
	v_mul_f32_e32 v69, v19, v69
	v_add_f32_e32 v72, v60, v61
	v_fmac_f32_e32 v69, v18, v68
	v_mul_f32_e32 v68, v21, v71
	ds_read_b128 v[60:63], v51 offset:58368
	ds_read_b128 v[64:67], v51 offset:57344
	v_fmac_f32_e32 v68, v20, v70
	v_add_f32_e32 v68, v69, v68
	v_add_f32_e32 v84, v72, v68
	ds_read_b128 v[68:71], v51 offset:60416
	ds_read_b128 v[72:75], v51 offset:59392
	s_waitcnt lgkmcnt(2)
	v_mul_f32_e32 v65, v31, v65
	v_mul_f32_e32 v61, v27, v61
	v_fmac_f32_e32 v65, v30, v64
	v_mul_f32_e32 v64, v33, v67
	v_fmac_f32_e32 v61, v26, v60
	v_mul_f32_e32 v60, v29, v63
	v_fmac_f32_e32 v64, v32, v66
	v_fmac_f32_e32 v60, v28, v62
	v_add_f32_e32 v64, v65, v64
	v_add_f32_e32 v60, v61, v60
	s_waitcnt lgkmcnt(0)
	v_mul_f32_e32 v61, v23, v73
	v_mul_f32_e32 v62, v25, v75
	v_add_f32_e32 v64, 0, v64
	v_fmac_f32_e32 v61, v22, v72
	v_fmac_f32_e32 v62, v24, v74
	v_mul_f32_e32 v69, v19, v69
	v_add_f32_e32 v60, v64, v60
	v_add_f32_e32 v61, v61, v62
	v_fmac_f32_e32 v69, v18, v68
	v_mul_f32_e32 v68, v21, v71
	v_add_f32_e32 v72, v60, v61
	v_fmac_f32_e32 v68, v20, v70
	ds_read_b128 v[60:63], v51 offset:62464
	ds_read_b128 v[64:67], v51 offset:61440
	v_add_f32_e32 v68, v69, v68
	v_add_f32_e32 v85, v72, v68
	ds_read_b128 v[68:71], v51 offset:64512
	ds_read_b128 v[72:75], v51 offset:63488
	s_waitcnt lgkmcnt(3)
	v_mul_f32_e32 v27, v27, v61
	s_waitcnt lgkmcnt(2)
	v_mul_f32_e32 v31, v31, v65
	v_fmac_f32_e32 v31, v30, v64
	v_mul_f32_e32 v30, v33, v67
	v_fmac_f32_e32 v30, v32, v66
	v_fmac_f32_e32 v27, v26, v60
	v_mul_f32_e32 v26, v29, v63
	s_waitcnt lgkmcnt(0)
	v_mul_f32_e32 v23, v23, v73
	v_add_f32_e32 v30, v31, v30
	v_fmac_f32_e32 v26, v28, v62
	v_fmac_f32_e32 v23, v22, v72
	v_mul_f32_e32 v22, v25, v75
	v_mul_f32_e32 v19, v19, v69
	v_add_f32_e32 v30, 0, v30
	v_add_f32_e32 v26, v27, v26
	v_fmac_f32_e32 v22, v24, v74
	v_fmac_f32_e32 v19, v18, v68
	v_mul_f32_e32 v18, v21, v71
	v_add_f32_e32 v26, v30, v26
	v_add_f32_e32 v22, v23, v22
	v_fmac_f32_e32 v18, v20, v70
	v_cndmask_b32_e64 v20, v55, v79, s[8:9]
	v_add_f32_e32 v22, v26, v22
	v_add_f32_e32 v18, v19, v18
	ds_bpermute_b32 v20, v50, v20
	v_cndmask_b32_e64 v21, v56, v80, s[8:9]
	v_add_f32_e32 v18, v22, v18
	ds_bpermute_b32 v21, v50, v21
	v_cndmask_b32_e64 v22, v57, v81, s[8:9]
	ds_bpermute_b32 v22, v50, v22
	v_cndmask_b32_e64 v23, v58, v82, s[8:9]
	ds_bpermute_b32 v23, v50, v23
	v_cndmask_b32_e64 v24, v59, v83, s[8:9]
	v_cndmask_b32_e64 v19, v79, v55, s[8:9]
	ds_bpermute_b32 v24, v50, v24
	v_cndmask_b32_e64 v25, v76, v84, s[8:9]
	s_waitcnt lgkmcnt(4)
	v_add_f32_e32 v19, v19, v20
	v_cndmask_b32_e64 v20, v80, v56, s[8:9]
	ds_bpermute_b32 v25, v50, v25
	v_cndmask_b32_e64 v26, v77, v85, s[8:9]
	v_cndmask_b32_e64 v27, v78, v18, s[8:9]
	s_waitcnt lgkmcnt(4)
	v_add_f32_e32 v20, v20, v21
	v_cndmask_b32_e64 v21, v81, v57, s[8:9]
	ds_bpermute_b32 v26, v50, v26
	ds_bpermute_b32 v27, v50, v27
	s_waitcnt lgkmcnt(5)
	v_add_f32_e32 v21, v21, v22
	v_cndmask_b32_e64 v22, v82, v58, s[8:9]
	s_waitcnt lgkmcnt(4)
	v_add_f32_e32 v22, v22, v23
	v_cndmask_b32_e64 v23, v83, v59, s[8:9]
	s_waitcnt lgkmcnt(3)
	v_add_f32_e32 v23, v23, v24
	v_cndmask_b32_e64 v24, v84, v76, s[8:9]
	s_waitcnt lgkmcnt(2)
	v_add_f32_e32 v24, v24, v25
	v_cndmask_b32_e64 v25, v85, v77, s[8:9]
	v_cndmask_b32_e64 v18, v18, v78, s[8:9]
	s_waitcnt lgkmcnt(1)
	v_add_f32_e32 v25, v25, v26
	s_waitcnt lgkmcnt(0)
	v_add_f32_e32 v18, v18, v27
	v_cndmask_b32_e64 v28, v19, v23, s[10:11]
	v_cndmask_b32_e64 v19, v23, v19, s[10:11]
	v_cndmask_b32_e64 v23, v24, v20, s[10:11]
	v_cndmask_b32_e64 v20, v20, v24, s[10:11]
	v_cndmask_b32_e64 v24, v21, v25, s[10:11]
	v_cndmask_b32_e64 v26, v22, v18, s[10:11]
	ds_bpermute_b32 v28, v49, v28
	ds_bpermute_b32 v20, v49, v20
	ds_bpermute_b32 v24, v49, v24
	ds_bpermute_b32 v26, v49, v26
	v_cndmask_b32_e64 v21, v25, v21, s[10:11]
	v_cndmask_b32_e64 v18, v18, v22, s[10:11]
	s_waitcnt lgkmcnt(3)
	v_add_f32_e32 v19, v19, v28
	s_waitcnt lgkmcnt(2)
	v_add_f32_e32 v20, v23, v20
	s_waitcnt lgkmcnt(1)
	v_add_f32_e32 v21, v21, v24
	s_waitcnt lgkmcnt(0)
	v_add_f32_e32 v18, v18, v26
	v_cndmask_b32_e64 v22, v19, v21, s[12:13]
	v_cndmask_b32_e64 v23, v20, v18, s[12:13]
	ds_bpermute_b32 v22, v48, v22
	ds_bpermute_b32 v23, v48, v23
	v_cndmask_b32_e64 v19, v21, v19, s[12:13]
	v_cndmask_b32_e64 v18, v18, v20, s[12:13]
	s_waitcnt lgkmcnt(1)
	v_add_f32_e32 v19, v19, v22
	s_waitcnt lgkmcnt(0)
	v_add_f32_e32 v18, v18, v23
	v_cndmask_b32_e64 v20, v19, v18, s[14:15]
	ds_bpermute_b32 v20, v47, v20
	v_cndmask_b32_e64 v18, v18, v19, s[14:15]
	s_waitcnt lgkmcnt(0)
	v_add_f32_e32 v18, v18, v20
	ds_bpermute_b32 v19, v46, v18
	s_waitcnt lgkmcnt(0)
	v_add_f32_e32 v18, v18, v19
	ds_bpermute_b32 v19, v1, v18
	s_and_saveexec_b64 s[60:61], s[16:17]
	s_cbranch_execz .LBB0_21
	global_load_dword v20, v[38:39], off nt
	v_fmamk_f32 v21, v43, 0x3a800000, v34
	s_waitcnt lgkmcnt(0)
	v_add_f32_e32 v22, v18, v19
	v_mul_f32_e32 v18, 0x4b800000, v21
	v_cmp_gt_f32_e32 vcc, s74, v21
	s_ashr_i32 s35, s26, 9
	s_and_b32 s26, s26, 0x1fff
	v_cndmask_b32_e32 v18, v21, v18, vcc
	v_rsq_f32_e32 v21, v18
	v_and_or_b32 v18, s35, -16, v52
	v_ashrrev_i32_e32 v19, 31, v18
	v_lshlrev_b64 v[18:19], 15, v[18:19]
	v_mul_f32_e32 v23, 0x45800000, v21
	v_cndmask_b32_e32 v21, v21, v23, vcc
	s_lshl_b32 s26, s26, 2
	v_lshl_add_u64 v[18:19], s[24:25], 0, v[18:19]
	v_lshl_add_u64 v[18:19], v[18:19], 0, s[26:27]
	s_waitcnt vmcnt(0)
	v_fmac_f32_e32 v20, v21, v22
	v_mul_f32_e64 v21, |v20|, s75
	v_fma_f32 v22, |v20|, s75, -v21
	v_rndne_f32_e32 v23, v21
	v_fma_f32 v22, |v20|, s76, v22
	v_sub_f32_e32 v21, v21, v23
	v_add_f32_e32 v21, v21, v22
	v_cvt_i32_f32_e32 v23, v23
	v_exp_f32_e32 v21, v21
	v_cmp_ngt_f32_e64 vcc, |v20|, s77
	v_min_f32_e32 v55, 0, v20
	v_ldexp_f32 v21, v21, v23
	v_cndmask_b32_e32 v21, 0, v21, vcc
	v_cmp_nlt_f32_e64 vcc, |v20|, s80
	s_nop 1
	v_cndmask_b32_e32 v56, v54, v21, vcc
	v_add_f32_e32 v22, 1.0, v56
	v_add_f32_e32 v23, -1.0, v22
	v_frexp_mant_f32_e32 v24, v22
	v_cvt_f64_f32_e32 v[20:21], v22
	v_sub_f32_e32 v25, v23, v22
	v_frexp_exp_i32_f64_e32 v20, v[20:21]
	v_cmp_gt_f32_e32 vcc, s82, v24
	v_sub_f32_e32 v23, v56, v23
	v_add_f32_e32 v21, 1.0, v25
	v_subbrev_co_u32_e32 v20, vcc, 0, v20, vcc
	v_add_f32_e32 v21, v23, v21
	v_sub_u32_e32 v23, 0, v20
	v_ldexp_f32 v22, v22, v23
	v_add_f32_e32 v24, -1.0, v22
	v_add_f32_e32 v25, 1.0, v22
	v_ldexp_f32 v21, v21, v23
	v_add_f32_e32 v23, 1.0, v24
	v_add_f32_e32 v26, -1.0, v25
	v_sub_f32_e32 v23, v22, v23
	v_sub_f32_e32 v22, v22, v26
	v_add_f32_e32 v26, v21, v23
	v_add_f32_e32 v21, v21, v22
	v_add_f32_e32 v28, v25, v21
	v_rcp_f32_e32 v29, v28
	v_add_f32_e32 v23, v24, v26
	v_sub_f32_e32 v24, v24, v23
	v_sub_f32_e32 v22, v25, v28
	v_mul_f32_e32 v31, v23, v29
	v_add_f32_e32 v30, v26, v24
	v_mul_f32_e32 v24, v28, v31
	v_add_f32_e32 v21, v21, v22
	v_fma_f32 v26, v31, v28, -v24
	v_fmac_f32_e32 v26, v31, v21
	v_add_f32_e32 v22, v24, v26
	v_sub_f32_e32 v25, v23, v22
	v_mov_b32_e32 v27, v22
	v_pk_add_f32 v[22:23], v[22:23], v[24:25] neg_lo:[0,1] neg_hi:[0,1]
	v_cvt_f32_i32_e32 v20, v20
	v_pk_add_f32 v[22:23], v[22:23], v[26:27] neg_lo:[0,1] neg_hi:[0,1]
	v_cmp_neq_f32_e32 vcc, s81, v56
	v_add_f32_e32 v23, v30, v23
	v_add_f32_e32 v22, v22, v23
	v_add_f32_e32 v23, v25, v22
	v_mul_f32_e32 v27, v29, v23
	v_mul_f32_e32 v24, v28, v27
	v_sub_f32_e32 v25, v25, v23
	v_add_f32_e32 v32, v31, v27
	v_fma_f32 v26, v27, v28, -v24
	v_add_f32_e32 v30, v22, v25
	v_sub_f32_e32 v22, v32, v31
	v_fmac_f32_e32 v26, v27, v21
	v_sub_f32_e32 v21, v27, v22
	v_add_f32_e32 v22, v24, v26
	v_sub_f32_e32 v25, v23, v22
	v_mov_b32_e32 v27, v22
	v_pk_add_f32 v[22:23], v[22:23], v[24:25] neg_lo:[0,1] neg_hi:[0,1]
	s_nop 0
	v_pk_add_f32 v[22:23], v[22:23], v[26:27] neg_lo:[0,1] neg_hi:[0,1]
	s_nop 0
	v_add_f32_e32 v23, v30, v23
	v_add_f32_e32 v22, v22, v23
	v_add_f32_e32 v22, v25, v22
	v_mul_f32_e32 v22, v29, v22
	v_add_f32_e32 v21, v21, v22
	v_add_f32_e32 v22, v32, v21
	v_mul_f32_e32 v24, v22, v22
	v_sub_f32_e32 v25, v22, v32
	v_fmamk_f32 v26, v24, 0x3e9b6dac, v53
	v_sub_f32_e32 v25, v21, v25
	v_mul_f32_e32 v21, v22, v24
	v_fmaak_f32 v43, v24, v26, 0x3f2aaada
	v_ldexp_f32 v27, v25, 1
	v_pk_mul_f32 v[24:25], v[20:21], v[42:43]
	v_ldexp_f32 v23, v22, 1
	v_fma_f32 v22, v20, s83, -v24
	v_fmac_f32_e32 v22, 0xb102e308, v20
	v_pk_add_f32 v[20:21], v[24:25], v[22:23]
	v_mov_b32_e32 v26, v24
	v_sub_f32_e32 v30, v21, v23
	v_pk_add_f32 v[28:29], v[20:21], v[24:25] neg_lo:[0,1] neg_hi:[0,1]
	v_sub_f32_e32 v24, v25, v30
	v_add_f32_e32 v27, v27, v24
	v_pk_add_f32 v[24:25], v[20:21], v[26:27]
	v_mov_b32_e32 v23, v20
	v_mov_b32_e32 v29, v25
	v_pk_add_f32 v[32:33], v[22:23], v[28:29] neg_lo:[0,1] neg_hi:[0,1]
	v_pk_add_f32 v[22:23], v[22:23], v[28:29]
	v_mov_b32_e32 v31, v20
	v_pk_add_f32 v[28:29], v[22:23], v[20:21] op_sel:[1,0] op_sel_hi:[0,1] neg_lo:[0,1] neg_hi:[0,1]
	v_mov_b32_e32 v30, v27
	v_mov_b32_e32 v26, v25
	v_mov_b32_e32 v27, v23
	v_pk_mov_b32 v[20:21], v[20:21], v[28:29] op_sel:[1,0]
	v_pk_add_f32 v[24:25], v[24:25], v[28:29] op_sel_hi:[1,0] neg_lo:[0,1] neg_hi:[0,1]
	v_pk_add_f32 v[20:21], v[26:27], v[20:21] neg_lo:[0,1] neg_hi:[0,1]
	v_mov_b32_e32 v24, v32
	v_pk_add_f32 v[20:21], v[30:31], v[20:21] neg_lo:[0,1] neg_hi:[0,1]
	v_mov_b32_e32 v33, v23
	v_pk_add_f32 v[24:25], v[24:25], v[20:21]
	s_nop 0
	v_pk_add_f32 v[26:27], v[24:25], v[24:25] op_sel:[0,1] op_sel_hi:[1,0]
	s_nop 0
	v_pk_add_f32 v[22:23], v[22:23], v[26:27] op_sel:[1,0] op_sel_hi:[0,1]
	v_mov_b32_e32 v25, v22
	v_mov_b32_e32 v21, v26
	v_pk_add_f32 v[26:27], v[24:25], v[32:33] neg_lo:[0,1] neg_hi:[0,1]
	s_nop 0
	v_sub_f32_e32 v23, v24, v26
	v_pk_add_f32 v[20:21], v[20:21], v[26:27] neg_lo:[0,1] neg_hi:[0,1]
	v_sub_f32_e32 v23, v32, v23
	v_add_f32_e32 v20, v20, v23
	v_add_f32_e32 v20, v20, v21
	v_add_f32_e32 v20, v22, v20
	v_cndmask_b32_e32 v20, v54, v20, vcc
	v_cmp_lt_f32_e64 vcc, |v56|, s85
	s_nop 1
	v_cndmask_b32_e32 v20, v20, v56, vcc
	v_sub_f32_e32 v20, v55, v20
	global_store_dword v[18:19], v20, off
	s_branch .LBB0_21

.LBB0_35:
	s_cmpk_gt_i32 s18, 0x5ff
	s_mov_b64 s[28:29], -1
	s_cbranch_scc0 .LBB0_102
	s_cmpk_gt_u32 s18, 0x7ff
	s_cbranch_scc0 .LBB0_99
	s_cmpk_gt_u32 s18, 0x97f
	s_cbranch_scc0 .LBB0_80
	s_cmpk_gt_u32 s18, 0xa7f
	s_cbranch_scc0 .LBB0_74
	s_cmpk_gt_u32 s18, 0xb9f
	s_cbranch_scc0 .LBB0_64
	s_cmpk_gt_u32 s18, 0xd9f
	s_cbranch_scc0 .LBB0_60
	s_cmpk_gt_u32 s18, 0x159f
	s_cbranch_scc0 .LBB0_54
	s_cmpk_gt_u32 s18, 0x1d9f
	s_cbranch_scc0 .LBB0_50
	s_cmpk_gt_u32 s18, 0x259f
	s_cbranch_scc0 .LBB0_47
	s_andn2_b64 vcc, exec, s[78:79]
	s_cbranch_vccnz .LBB0_46
	s_and_b32 s5, s21, 0x7fffffc0
	s_and_b32 s4, s3, 0x3e0
	v_or_b32_e32 v10, s5, v48
	v_or_b32_e32 v4, s4, v1
	v_lshlrev_b64 v[2:3], 12, v[10:11]
	v_lshl_add_u64 v[2:3], s[6:7], 0, v[2:3]
	v_lshlrev_b32_e32 v10, 2, v4
	v_lshl_add_u64 v[2:3], v[2:3], 0, v[10:11]
	v_add_co_u32_e32 v4, vcc, 0x2000, v2
	s_lshl_b32 s26, s5, 1
	s_nop 0
	v_addc_co_u32_e32 v5, vcc, 0, v3, vcc
	v_add_co_u32_e32 v6, vcc, 0x4000, v2
	s_nop 1
	v_addc_co_u32_e32 v7, vcc, 0, v3, vcc
	v_add_co_u32_e32 v8, vcc, 0x6000, v2
	s_nop 1
	v_addc_co_u32_e32 v9, vcc, 0, v3, vcc
	v_add_co_u32_e32 v46, vcc, 0x8000, v2
	s_nop 1
	v_addc_co_u32_e32 v47, vcc, 0, v3, vcc
	v_add_co_u32_e32 v64, vcc, 0xa000, v2
	s_nop 1
	v_addc_co_u32_e32 v65, vcc, 0, v3, vcc
	v_add_co_u32_e32 v66, vcc, 0xc000, v2
	s_nop 1
	v_addc_co_u32_e32 v67, vcc, 0, v3, vcc
	v_add_co_u32_e32 v68, vcc, 0xe000, v2
	s_nop 1
	v_addc_co_u32_e32 v69, vcc, 0, v3, vcc
	global_load_dword v10, v[2:3], off nt
	global_load_dword v72, v[4:5], off nt
	global_load_dword v73, v[6:7], off nt
	global_load_dword v74, v[8:9], off nt
	global_load_dword v75, v[46:47], off nt
	global_load_dword v76, v[64:65], off nt
	global_load_dword v77, v[66:67], off nt
	global_load_dword v78, v[68:69], off nt
	v_add_co_u32_e32 v4, vcc, 0x10000, v2
	s_nop 1
	v_addc_co_u32_e32 v5, vcc, 0, v3, vcc
	v_add_co_u32_e32 v6, vcc, 0x12000, v2
	s_nop 1
	v_addc_co_u32_e32 v7, vcc, 0, v3, vcc
	v_add_co_u32_e32 v8, vcc, 0x14000, v2
	s_nop 1
	v_addc_co_u32_e32 v9, vcc, 0, v3, vcc
	v_add_co_u32_e32 v46, vcc, 0x16000, v2
	s_nop 1
	v_addc_co_u32_e32 v47, vcc, 0, v3, vcc
	v_add_co_u32_e32 v64, vcc, 0x18000, v2
	s_nop 1
	v_addc_co_u32_e32 v65, vcc, 0, v3, vcc
	v_add_co_u32_e32 v66, vcc, 0x1a000, v2
	s_nop 1
	v_addc_co_u32_e32 v67, vcc, 0, v3, vcc
	v_add_co_u32_e32 v68, vcc, 0x1c000, v2
	s_nop 1
	v_addc_co_u32_e32 v69, vcc, 0, v3, vcc
	v_add_co_u32_e32 v70, vcc, 0x1e000, v2
	s_nop 1
	v_addc_co_u32_e32 v71, vcc, 0, v3, vcc
	global_load_dword v79, v[4:5], off nt
	global_load_dword v80, v[6:7], off nt
	global_load_dword v81, v[8:9], off nt
	global_load_dword v82, v[46:47], off nt
	global_load_dword v83, v[64:65], off nt
	global_load_dword v84, v[66:67], off nt
	global_load_dword v85, v[68:69], off nt
	global_load_dword v86, v[70:71], off nt
	v_add_co_u32_e32 v4, vcc, 0x20000, v2
	s_nop 1
	v_addc_co_u32_e32 v5, vcc, 0, v3, vcc
	v_add_co_u32_e32 v6, vcc, 0x22000, v2
	s_nop 1
	v_addc_co_u32_e32 v7, vcc, 0, v3, vcc
	v_add_co_u32_e32 v8, vcc, 0x24000, v2
	s_nop 1
	v_addc_co_u32_e32 v9, vcc, 0, v3, vcc
	v_add_co_u32_e32 v46, vcc, 0x26000, v2
	s_nop 1
	v_addc_co_u32_e32 v47, vcc, 0, v3, vcc
	v_add_co_u32_e32 v64, vcc, 0x28000, v2
	s_nop 1
	v_addc_co_u32_e32 v65, vcc, 0, v3, vcc
	v_add_co_u32_e32 v66, vcc, 0x2a000, v2
	s_nop 1
	v_addc_co_u32_e32 v67, vcc, 0, v3, vcc
	v_add_co_u32_e32 v68, vcc, 0x2c000, v2
	s_nop 1
	v_addc_co_u32_e32 v69, vcc, 0, v3, vcc
	v_add_co_u32_e32 v70, vcc, 0x2e000, v2
	s_nop 1
	v_addc_co_u32_e32 v71, vcc, 0, v3, vcc
	global_load_dword v87, v[4:5], off nt
	global_load_dword v88, v[6:7], off nt
	global_load_dword v89, v[8:9], off nt
	global_load_dword v90, v[46:47], off nt
	global_load_dword v91, v[64:65], off nt
	global_load_dword v92, v[66:67], off nt
	global_load_dword v93, v[68:69], off nt
	s_nop 0
	global_load_dword v70, v[70:71], off nt
	v_add_co_u32_e32 v4, vcc, 0x30000, v2
	s_nop 1
	v_addc_co_u32_e32 v5, vcc, 0, v3, vcc
	v_add_co_u32_e32 v6, vcc, 0x32000, v2
	s_nop 1
	v_addc_co_u32_e32 v7, vcc, 0, v3, vcc
	v_add_co_u32_e32 v8, vcc, 0x34000, v2
	s_nop 1
	v_addc_co_u32_e32 v9, vcc, 0, v3, vcc
	v_add_co_u32_e32 v46, vcc, 0x36000, v2
	s_nop 1
	v_addc_co_u32_e32 v47, vcc, 0, v3, vcc
	v_add_co_u32_e32 v64, vcc, 0x38000, v2
	s_nop 1
	v_addc_co_u32_e32 v65, vcc, 0, v3, vcc
	v_add_co_u32_e32 v66, vcc, 0x3a000, v2
	s_nop 1
	v_addc_co_u32_e32 v67, vcc, 0, v3, vcc
	v_add_co_u32_e32 v68, vcc, 0x3c000, v2
	s_nop 1
	v_addc_co_u32_e32 v69, vcc, 0, v3, vcc
	v_add_co_u32_e32 v2, vcc, 0x3e000, v2
	s_nop 1
	v_addc_co_u32_e32 v3, vcc, 0, v3, vcc
	global_load_dword v4, v[4:5], off nt
	s_nop 0
	global_load_dword v5, v[6:7], off nt
	s_nop 0
	global_load_dword v6, v[8:9], off nt
	global_load_dword v7, v[46:47], off nt
	s_nop 0
	global_load_dword v8, v[64:65], off nt
	global_load_dword v9, v[66:67], off nt
	global_load_dword v46, v[68:69], off nt
	s_nop 0
	global_load_dword v2, v[2:3], off nt
	s_waitcnt vmcnt(30)
	ds_write2_b32 v49, v10, v72 offset1:66
	s_waitcnt vmcnt(28)
	ds_write2_b32 v49, v73, v74 offset0:132 offset1:198
	s_waitcnt vmcnt(26)
	ds_write2_b32 v57, v75, v76 offset0:8 offset1:74
	s_waitcnt vmcnt(24)
	ds_write2_b32 v57, v77, v78 offset0:140 offset1:206
	s_waitcnt vmcnt(22)
	ds_write2_b32 v58, v79, v80 offset0:16 offset1:82
	s_waitcnt vmcnt(20)
	ds_write2_b32 v58, v81, v82 offset0:148 offset1:214
	s_waitcnt vmcnt(18)
	ds_write2_b32 v59, v83, v84 offset0:24 offset1:90
	s_waitcnt vmcnt(16)
	ds_write2_b32 v59, v85, v86 offset0:156 offset1:222
	s_waitcnt vmcnt(14)
	ds_write2_b32 v60, v87, v88 offset0:32 offset1:98
	s_waitcnt vmcnt(12)
	ds_write2_b32 v60, v89, v90 offset0:164 offset1:230
	s_waitcnt vmcnt(10)
	ds_write2_b32 v61, v91, v92 offset0:40 offset1:106
	s_waitcnt vmcnt(8)
	ds_write2_b32 v61, v93, v70 offset0:172 offset1:238
	s_waitcnt vmcnt(6)
	ds_write2_b32 v62, v4, v5 offset0:48 offset1:114
	s_waitcnt vmcnt(4)
	ds_write2_b32 v62, v6, v7 offset0:180 offset1:246
	s_waitcnt vmcnt(2)
	ds_write2_b32 v63, v8, v9 offset0:56 offset1:122
	s_waitcnt vmcnt(0)
	ds_write2_b32 v63, v46, v2 offset0:188 offset1:254
	s_waitcnt lgkmcnt(0)
	ds_read2_b32 v[6:7], v51 offset1:8
	ds_read2_b32 v[46:47], v51 offset0:33 offset1:41
	ds_read2_b32 v[64:65], v51 offset0:66 offset1:74
	ds_read2_b32 v[66:67], v51 offset0:99 offset1:107
	ds_read2_b32 v[68:69], v51 offset0:132 offset1:140
	s_waitcnt lgkmcnt(4)
	v_bfe_u32 v2, v6, 16, 1
	v_add3_u32 v2, v6, v2, s89
	s_waitcnt lgkmcnt(3)
	v_bfe_u32 v3, v46, 16, 1
	v_lshrrev_b32_e32 v2, 16, v2
	v_add3_u32 v3, v46, v3, s89
	ds_read2_b32 v[70:71], v51 offset0:165 offset1:173
	v_and_or_b32 v2, v3, s90, v2
	s_waitcnt lgkmcnt(3)
	v_bfe_u32 v3, v64, 16, 1
	v_add3_u32 v3, v64, v3, s89
	s_waitcnt lgkmcnt(2)
	v_bfe_u32 v4, v66, 16, 1
	ds_read2_b32 v[72:73], v51 offset0:198 offset1:206
	v_lshrrev_b32_e32 v3, 16, v3
	v_add3_u32 v4, v66, v4, s89
	ds_read2_b32 v[74:75], v51 offset0:231 offset1:239
	v_and_or_b32 v3, v4, s90, v3
	s_waitcnt lgkmcnt(3)
	v_bfe_u32 v4, v68, 16, 1
	v_add3_u32 v4, v68, v4, s89
	s_waitcnt lgkmcnt(2)
	v_bfe_u32 v5, v70, 16, 1
	v_lshrrev_b32_e32 v4, 16, v4
	v_add3_u32 v5, v70, v5, s89
	v_and_or_b32 v4, v5, s90, v4
	s_waitcnt lgkmcnt(1)
	v_bfe_u32 v5, v72, 16, 1
	v_add3_u32 v5, v72, v5, s89
	s_waitcnt lgkmcnt(0)
	v_bfe_u32 v6, v74, 16, 1
	v_lshrrev_b32_e32 v5, 16, v5
	v_add3_u32 v6, v74, v6, s89
	v_and_or_b32 v5, v6, s90, v5
	v_or_b32_e32 v6, s4, v50
	v_lshl_add_u64 v[8:9], v[12:13], 0, s[26:27]
	v_lshlrev_b32_e32 v10, 13, v6
	v_lshl_add_u64 v[76:77], v[8:9], 0, v[10:11]
	global_store_dwordx4 v[76:77], v[2:5], off
	v_bfe_u32 v6, v75, 16, 1
	v_or_b32_e32 v10, s4, v52
	v_bfe_u32 v2, v7, 16, 1
	v_add3_u32 v2, v7, v2, s89
	v_bfe_u32 v3, v47, 16, 1
	v_lshrrev_b32_e32 v2, 16, v2
	v_add3_u32 v3, v47, v3, s89
	v_and_or_b32 v2, v3, s90, v2
	v_bfe_u32 v3, v65, 16, 1
	v_add3_u32 v3, v65, v3, s89
	v_bfe_u32 v4, v67, 16, 1
	v_lshrrev_b32_e32 v3, 16, v3
	v_add3_u32 v4, v67, v4, s89
	v_and_or_b32 v3, v4, s90, v3
	v_bfe_u32 v4, v69, 16, 1
	v_add3_u32 v4, v69, v4, s89
	v_bfe_u32 v5, v71, 16, 1
	v_lshrrev_b32_e32 v4, 16, v4
	v_add3_u32 v5, v71, v5, s89
	v_and_or_b32 v4, v5, s90, v4
	v_bfe_u32 v5, v73, 16, 1
	v_add3_u32 v5, v73, v5, s89
	v_lshrrev_b32_e32 v5, 16, v5
	v_add3_u32 v6, v75, v6, s89
	v_lshlrev_b32_e32 v10, 13, v10
	v_and_or_b32 v5, v6, s90, v5
	ds_read2_b32 v[6:7], v51 offset0:16 offset1:24
	v_lshl_add_u64 v[46:47], v[8:9], 0, v[10:11]
	global_store_dwordx4 v[46:47], v[2:5], off
	ds_read2_b32 v[46:47], v51 offset0:49 offset1:57
	ds_read2_b32 v[64:65], v51 offset0:82 offset1:90
	ds_read2_b32 v[66:67], v51 offset0:115 offset1:123
	s_waitcnt lgkmcnt(3)
	v_bfe_u32 v2, v6, 16, 1
	v_add3_u32 v2, v6, v2, s89
	s_waitcnt lgkmcnt(2)
	v_bfe_u32 v3, v46, 16, 1
	ds_read2_b32 v[68:69], v51 offset0:148 offset1:156
	v_lshrrev_b32_e32 v2, 16, v2
	v_add3_u32 v3, v46, v3, s89
	ds_read2_b32 v[70:71], v51 offset0:181 offset1:189
	v_and_or_b32 v2, v3, s90, v2
	s_waitcnt lgkmcnt(3)
	v_bfe_u32 v3, v64, 16, 1
	v_add3_u32 v3, v64, v3, s89
	s_waitcnt lgkmcnt(2)
	v_bfe_u32 v4, v66, 16, 1
	ds_read2_b32 v[72:73], v51 offset0:214 offset1:222
	v_lshrrev_b32_e32 v3, 16, v3
	v_add3_u32 v4, v66, v4, s89
	ds_read2_b32 v[74:75], v51 offset0:247 offset1:255
	v_and_or_b32 v3, v4, s90, v3
	s_waitcnt lgkmcnt(3)
	v_bfe_u32 v4, v68, 16, 1
	v_add3_u32 v4, v68, v4, s89
	s_waitcnt lgkmcnt(2)
	v_bfe_u32 v5, v70, 16, 1
	v_lshrrev_b32_e32 v4, 16, v4
	v_add3_u32 v5, v70, v5, s89
	v_and_or_b32 v4, v5, s90, v4
	s_waitcnt lgkmcnt(1)
	v_bfe_u32 v5, v72, 16, 1
	v_add3_u32 v5, v72, v5, s89
	s_waitcnt lgkmcnt(0)
	v_bfe_u32 v6, v74, 16, 1
	v_lshrrev_b32_e32 v5, 16, v5
	v_add3_u32 v6, v74, v6, s89
	v_and_or_b32 v5, v6, s90, v5
	v_or_b32_e32 v6, s4, v53
	v_lshlrev_b32_e32 v10, 13, v6
	v_lshl_add_u64 v[76:77], v[8:9], 0, v[10:11]
	global_store_dwordx4 v[76:77], v[2:5], off
	v_bfe_u32 v6, v75, 16, 1
	v_add3_u32 v6, v75, v6, s89
	v_bfe_u32 v2, v7, 16, 1
	v_add3_u32 v2, v7, v2, s89
	v_bfe_u32 v3, v47, 16, 1
	v_lshrrev_b32_e32 v2, 16, v2
	v_add3_u32 v3, v47, v3, s89
	v_and_or_b32 v2, v3, s90, v2
	v_bfe_u32 v3, v65, 16, 1
	v_add3_u32 v3, v65, v3, s89
	v_bfe_u32 v4, v67, 16, 1
	v_lshrrev_b32_e32 v3, 16, v3
	v_add3_u32 v4, v67, v4, s89
	v_and_or_b32 v3, v4, s90, v3
	v_bfe_u32 v4, v69, 16, 1
	v_add3_u32 v4, v69, v4, s89
	v_bfe_u32 v5, v71, 16, 1
	v_lshrrev_b32_e32 v4, 16, v4
	v_add3_u32 v5, v71, v5, s89
	v_and_or_b32 v4, v5, s90, v4
	v_bfe_u32 v5, v73, 16, 1
	v_add3_u32 v5, v73, v5, s89
	v_lshrrev_b32_e32 v5, 16, v5
	v_and_or_b32 v5, v6, s90, v5
	v_or_b32_e32 v6, s4, v54
	v_lshlrev_b32_e32 v10, 13, v6
	v_lshl_add_u64 v[6:7], v[8:9], 0, v[10:11]
	global_store_dwordx4 v[6:7], v[2:5], off
	s_waitcnt lgkmcnt(0)

.LBB0_47:
	s_andn2_b64 vcc, exec, s[28:29]
	s_cbranch_vccnz .LBB0_49
	s_add_i32 s4, s21, 0x1000
	s_and_b32 s5, s4, 0x7fffffc0
	s_and_b32 s4, s3, 0x3e0
	v_or_b32_e32 v10, s5, v48
	v_or_b32_e32 v4, s4, v1
	v_lshlrev_b64 v[2:3], 12, v[10:11]
	v_lshl_add_u64 v[2:3], s[50:51], 0, v[2:3]
	v_lshlrev_b32_e32 v10, 2, v4
	v_lshl_add_u64 v[2:3], v[2:3], 0, v[10:11]
	v_add_co_u32_e32 v4, vcc, 0x2000, v2
	s_lshl_b32 s26, s5, 1
	s_nop 0
	v_addc_co_u32_e32 v5, vcc, 0, v3, vcc
	v_add_co_u32_e32 v6, vcc, 0x4000, v2
	s_nop 1
	v_addc_co_u32_e32 v7, vcc, 0, v3, vcc
	v_add_co_u32_e32 v8, vcc, 0x6000, v2
	s_nop 1
	v_addc_co_u32_e32 v9, vcc, 0, v3, vcc
	v_add_co_u32_e32 v46, vcc, 0x8000, v2
	s_nop 1
	v_addc_co_u32_e32 v47, vcc, 0, v3, vcc
	v_add_co_u32_e32 v64, vcc, 0xa000, v2
	s_nop 1
	v_addc_co_u32_e32 v65, vcc, 0, v3, vcc
	v_add_co_u32_e32 v66, vcc, 0xc000, v2
	s_nop 1
	v_addc_co_u32_e32 v67, vcc, 0, v3, vcc
	v_add_co_u32_e32 v68, vcc, 0xe000, v2
	s_nop 1
	v_addc_co_u32_e32 v69, vcc, 0, v3, vcc
	global_load_dword v10, v[2:3], off nt
	global_load_dword v72, v[4:5], off nt
	global_load_dword v73, v[6:7], off nt
	global_load_dword v74, v[8:9], off nt
	global_load_dword v75, v[46:47], off nt
	global_load_dword v76, v[64:65], off nt
	global_load_dword v77, v[66:67], off nt
	global_load_dword v78, v[68:69], off nt
	v_add_co_u32_e32 v4, vcc, 0x10000, v2
	s_nop 1
	v_addc_co_u32_e32 v5, vcc, 0, v3, vcc
	v_add_co_u32_e32 v6, vcc, 0x12000, v2
	s_nop 1
	v_addc_co_u32_e32 v7, vcc, 0, v3, vcc
	v_add_co_u32_e32 v8, vcc, 0x14000, v2
	s_nop 1
	v_addc_co_u32_e32 v9, vcc, 0, v3, vcc
	v_add_co_u32_e32 v46, vcc, 0x16000, v2
	s_nop 1
	v_addc_co_u32_e32 v47, vcc, 0, v3, vcc
	v_add_co_u32_e32 v64, vcc, 0x18000, v2
	s_nop 1
	v_addc_co_u32_e32 v65, vcc, 0, v3, vcc
	v_add_co_u32_e32 v66, vcc, 0x1a000, v2
	s_nop 1
	v_addc_co_u32_e32 v67, vcc, 0, v3, vcc
	v_add_co_u32_e32 v68, vcc, 0x1c000, v2
	s_nop 1
	v_addc_co_u32_e32 v69, vcc, 0, v3, vcc
	v_add_co_u32_e32 v70, vcc, 0x1e000, v2
	s_nop 1
	v_addc_co_u32_e32 v71, vcc, 0, v3, vcc
	global_load_dword v79, v[4:5], off nt
	global_load_dword v80, v[6:7], off nt
	global_load_dword v81, v[8:9], off nt
	global_load_dword v82, v[46:47], off nt
	global_load_dword v83, v[64:65], off nt
	global_load_dword v84, v[66:67], off nt
	global_load_dword v85, v[68:69], off nt
	global_load_dword v86, v[70:71], off nt
	v_add_co_u32_e32 v4, vcc, 0x20000, v2
	s_nop 1
	v_addc_co_u32_e32 v5, vcc, 0, v3, vcc
	v_add_co_u32_e32 v6, vcc, 0x22000, v2
	s_nop 1
	v_addc_co_u32_e32 v7, vcc, 0, v3, vcc
	v_add_co_u32_e32 v8, vcc, 0x24000, v2
	s_nop 1
	v_addc_co_u32_e32 v9, vcc, 0, v3, vcc
	v_add_co_u32_e32 v46, vcc, 0x26000, v2
	s_nop 1
	v_addc_co_u32_e32 v47, vcc, 0, v3, vcc
	v_add_co_u32_e32 v64, vcc, 0x28000, v2
	s_nop 1
	v_addc_co_u32_e32 v65, vcc, 0, v3, vcc
	v_add_co_u32_e32 v66, vcc, 0x2a000, v2
	s_nop 1
	v_addc_co_u32_e32 v67, vcc, 0, v3, vcc
	v_add_co_u32_e32 v68, vcc, 0x2c000, v2
	s_nop 1
	v_addc_co_u32_e32 v69, vcc, 0, v3, vcc
	v_add_co_u32_e32 v70, vcc, 0x2e000, v2
	s_nop 1
	v_addc_co_u32_e32 v71, vcc, 0, v3, vcc
	global_load_dword v87, v[4:5], off nt
	global_load_dword v88, v[6:7], off nt
	global_load_dword v89, v[8:9], off nt
	global_load_dword v90, v[46:47], off nt
	global_load_dword v91, v[64:65], off nt
	global_load_dword v92, v[66:67], off nt
	global_load_dword v93, v[68:69], off nt
	s_nop 0
	global_load_dword v70, v[70:71], off nt
	v_add_co_u32_e32 v4, vcc, 0x30000, v2
	s_nop 1
	v_addc_co_u32_e32 v5, vcc, 0, v3, vcc
	v_add_co_u32_e32 v6, vcc, 0x32000, v2
	s_nop 1
	v_addc_co_u32_e32 v7, vcc, 0, v3, vcc
	v_add_co_u32_e32 v8, vcc, 0x34000, v2
	s_nop 1
	v_addc_co_u32_e32 v9, vcc, 0, v3, vcc
	v_add_co_u32_e32 v46, vcc, 0x36000, v2
	s_nop 1
	v_addc_co_u32_e32 v47, vcc, 0, v3, vcc
	v_add_co_u32_e32 v64, vcc, 0x38000, v2
	s_nop 1
	v_addc_co_u32_e32 v65, vcc, 0, v3, vcc
	v_add_co_u32_e32 v66, vcc, 0x3a000, v2
	s_nop 1
	v_addc_co_u32_e32 v67, vcc, 0, v3, vcc
	v_add_co_u32_e32 v68, vcc, 0x3c000, v2
	s_nop 1
	v_addc_co_u32_e32 v69, vcc, 0, v3, vcc
	v_add_co_u32_e32 v2, vcc, 0x3e000, v2
	s_nop 1
	v_addc_co_u32_e32 v3, vcc, 0, v3, vcc
	global_load_dword v4, v[4:5], off nt
	s_nop 0
	global_load_dword v5, v[6:7], off nt
	s_nop 0
	global_load_dword v6, v[8:9], off nt
	global_load_dword v7, v[46:47], off nt
	s_nop 0
	global_load_dword v8, v[64:65], off nt
	global_load_dword v9, v[66:67], off nt
	global_load_dword v46, v[68:69], off nt
	s_nop 0
	global_load_dword v2, v[2:3], off nt
	s_waitcnt vmcnt(30)
	ds_write2_b32 v49, v10, v72 offset1:66
	s_waitcnt vmcnt(28)
	ds_write2_b32 v49, v73, v74 offset0:132 offset1:198
	s_waitcnt vmcnt(26)
	ds_write2_b32 v57, v75, v76 offset0:8 offset1:74
	s_waitcnt vmcnt(24)
	ds_write2_b32 v57, v77, v78 offset0:140 offset1:206
	s_waitcnt vmcnt(22)
	ds_write2_b32 v58, v79, v80 offset0:16 offset1:82
	s_waitcnt vmcnt(20)
	ds_write2_b32 v58, v81, v82 offset0:148 offset1:214
	s_waitcnt vmcnt(18)
	ds_write2_b32 v59, v83, v84 offset0:24 offset1:90
	s_waitcnt vmcnt(16)
	ds_write2_b32 v59, v85, v86 offset0:156 offset1:222
	s_waitcnt vmcnt(14)
	ds_write2_b32 v60, v87, v88 offset0:32 offset1:98
	s_waitcnt vmcnt(12)
	ds_write2_b32 v60, v89, v90 offset0:164 offset1:230
	s_waitcnt vmcnt(10)
	ds_write2_b32 v61, v91, v92 offset0:40 offset1:106
	s_waitcnt vmcnt(8)
	ds_write2_b32 v61, v93, v70 offset0:172 offset1:238
	s_waitcnt vmcnt(6)
	ds_write2_b32 v62, v4, v5 offset0:48 offset1:114
	s_waitcnt vmcnt(4)
	ds_write2_b32 v62, v6, v7 offset0:180 offset1:246
	s_waitcnt vmcnt(2)
	ds_write2_b32 v63, v8, v9 offset0:56 offset1:122
	s_waitcnt vmcnt(0)
	ds_write2_b32 v63, v46, v2 offset0:188 offset1:254
	s_waitcnt lgkmcnt(0)
	ds_read2_b32 v[6:7], v51 offset1:8
	ds_read2_b32 v[46:47], v51 offset0:33 offset1:41
	ds_read2_b32 v[64:65], v51 offset0:66 offset1:74
	ds_read2_b32 v[66:67], v51 offset0:99 offset1:107
	ds_read2_b32 v[68:69], v51 offset0:132 offset1:140
	s_waitcnt lgkmcnt(4)
	v_bfe_u32 v2, v6, 16, 1
	v_add3_u32 v2, v6, v2, s89
	s_waitcnt lgkmcnt(3)
	v_bfe_u32 v3, v46, 16, 1
	v_lshrrev_b32_e32 v2, 16, v2
	v_add3_u32 v3, v46, v3, s89
	ds_read2_b32 v[70:71], v51 offset0:165 offset1:173
	v_and_or_b32 v2, v3, s90, v2
	s_waitcnt lgkmcnt(3)
	v_bfe_u32 v3, v64, 16, 1
	v_add3_u32 v3, v64, v3, s89
	s_waitcnt lgkmcnt(2)
	v_bfe_u32 v4, v66, 16, 1
	ds_read2_b32 v[72:73], v51 offset0:198 offset1:206
	v_lshrrev_b32_e32 v3, 16, v3
	v_add3_u32 v4, v66, v4, s89
	ds_read2_b32 v[74:75], v51 offset0:231 offset1:239
	v_and_or_b32 v3, v4, s90, v3
	s_waitcnt lgkmcnt(3)
	v_bfe_u32 v4, v68, 16, 1
	v_add3_u32 v4, v68, v4, s89
	s_waitcnt lgkmcnt(2)
	v_bfe_u32 v5, v70, 16, 1
	v_lshrrev_b32_e32 v4, 16, v4
	v_add3_u32 v5, v70, v5, s89
	v_and_or_b32 v4, v5, s90, v4
	s_waitcnt lgkmcnt(1)
	v_bfe_u32 v5, v72, 16, 1
	v_add3_u32 v5, v72, v5, s89
	s_waitcnt lgkmcnt(0)
	v_bfe_u32 v6, v74, 16, 1
	v_lshrrev_b32_e32 v5, 16, v5
	v_add3_u32 v6, v74, v6, s89
	v_and_or_b32 v5, v6, s90, v5
	v_or_b32_e32 v6, s4, v50
	v_lshl_add_u64 v[8:9], v[14:15], 0, s[26:27]
	v_lshlrev_b32_e32 v10, 13, v6
	v_lshl_add_u64 v[76:77], v[8:9], 0, v[10:11]
	global_store_dwordx4 v[76:77], v[2:5], off
	v_bfe_u32 v6, v75, 16, 1
	v_or_b32_e32 v10, s4, v52
	v_bfe_u32 v2, v7, 16, 1
	v_add3_u32 v2, v7, v2, s89
	v_bfe_u32 v3, v47, 16, 1
	v_lshrrev_b32_e32 v2, 16, v2
	v_add3_u32 v3, v47, v3, s89
	v_and_or_b32 v2, v3, s90, v2
	v_bfe_u32 v3, v65, 16, 1
	v_add3_u32 v3, v65, v3, s89
	v_bfe_u32 v4, v67, 16, 1
	v_lshrrev_b32_e32 v3, 16, v3
	v_add3_u32 v4, v67, v4, s89
	v_and_or_b32 v3, v4, s90, v3
	v_bfe_u32 v4, v69, 16, 1
	v_add3_u32 v4, v69, v4, s89
	v_bfe_u32 v5, v71, 16, 1
	v_lshrrev_b32_e32 v4, 16, v4
	v_add3_u32 v5, v71, v5, s89
	v_and_or_b32 v4, v5, s90, v4
	v_bfe_u32 v5, v73, 16, 1
	v_add3_u32 v5, v73, v5, s89
	v_lshrrev_b32_e32 v5, 16, v5
	v_add3_u32 v6, v75, v6, s89
	v_lshlrev_b32_e32 v10, 13, v10
	v_and_or_b32 v5, v6, s90, v5
	ds_read2_b32 v[6:7], v51 offset0:16 offset1:24
	v_lshl_add_u64 v[46:47], v[8:9], 0, v[10:11]
	global_store_dwordx4 v[46:47], v[2:5], off
	ds_read2_b32 v[46:47], v51 offset0:49 offset1:57
	ds_read2_b32 v[64:65], v51 offset0:82 offset1:90
	ds_read2_b32 v[66:67], v51 offset0:115 offset1:123
	s_waitcnt lgkmcnt(3)
	v_bfe_u32 v2, v6, 16, 1
	v_add3_u32 v2, v6, v2, s89
	s_waitcnt lgkmcnt(2)
	v_bfe_u32 v3, v46, 16, 1
	ds_read2_b32 v[68:69], v51 offset0:148 offset1:156
	v_lshrrev_b32_e32 v2, 16, v2
	v_add3_u32 v3, v46, v3, s89
	ds_read2_b32 v[70:71], v51 offset0:181 offset1:189
	v_and_or_b32 v2, v3, s90, v2
	s_waitcnt lgkmcnt(3)
	v_bfe_u32 v3, v64, 16, 1
	v_add3_u32 v3, v64, v3, s89
	s_waitcnt lgkmcnt(2)
	v_bfe_u32 v4, v66, 16, 1
	ds_read2_b32 v[72:73], v51 offset0:214 offset1:222
	v_lshrrev_b32_e32 v3, 16, v3
	v_add3_u32 v4, v66, v4, s89
	ds_read2_b32 v[74:75], v51 offset0:247 offset1:255
	v_and_or_b32 v3, v4, s90, v3
	s_waitcnt lgkmcnt(3)
	v_bfe_u32 v4, v68, 16, 1
	v_add3_u32 v4, v68, v4, s89
	s_waitcnt lgkmcnt(2)
	v_bfe_u32 v5, v70, 16, 1
	v_lshrrev_b32_e32 v4, 16, v4
	v_add3_u32 v5, v70, v5, s89
	v_and_or_b32 v4, v5, s90, v4
	s_waitcnt lgkmcnt(1)
	v_bfe_u32 v5, v72, 16, 1
	v_add3_u32 v5, v72, v5, s89
	s_waitcnt lgkmcnt(0)
	v_bfe_u32 v6, v74, 16, 1
	v_lshrrev_b32_e32 v5, 16, v5
	v_add3_u32 v6, v74, v6, s89
	v_and_or_b32 v5, v6, s90, v5
	v_or_b32_e32 v6, s4, v53
	v_lshlrev_b32_e32 v10, 13, v6
	v_lshl_add_u64 v[76:77], v[8:9], 0, v[10:11]
	global_store_dwordx4 v[76:77], v[2:5], off
	v_bfe_u32 v6, v75, 16, 1
	v_add3_u32 v6, v75, v6, s89
	v_bfe_u32 v2, v7, 16, 1
	v_add3_u32 v2, v7, v2, s89
	v_bfe_u32 v3, v47, 16, 1
	v_lshrrev_b32_e32 v2, 16, v2
	v_add3_u32 v3, v47, v3, s89
	v_and_or_b32 v2, v3, s90, v2
	v_bfe_u32 v3, v65, 16, 1
	v_add3_u32 v3, v65, v3, s89
	v_bfe_u32 v4, v67, 16, 1
	v_lshrrev_b32_e32 v3, 16, v3
	v_add3_u32 v4, v67, v4, s89
	v_and_or_b32 v3, v4, s90, v3
	v_bfe_u32 v4, v69, 16, 1
	v_add3_u32 v4, v69, v4, s89
	v_bfe_u32 v5, v71, 16, 1
	v_lshrrev_b32_e32 v4, 16, v4
	v_add3_u32 v5, v71, v5, s89
	v_and_or_b32 v4, v5, s90, v4
	v_bfe_u32 v5, v73, 16, 1
	v_add3_u32 v5, v73, v5, s89
	v_lshrrev_b32_e32 v5, 16, v5
	v_and_or_b32 v5, v6, s90, v5
	v_or_b32_e32 v6, s4, v54
	v_lshlrev_b32_e32 v10, 13, v6
	v_lshl_add_u64 v[6:7], v[8:9], 0, v[10:11]
	global_store_dwordx4 v[6:7], v[2:5], off
	s_waitcnt lgkmcnt(0)

.LBB0_50:
	s_andn2_b64 vcc, exec, s[28:29]
	s_cbranch_vccnz .LBB0_53
	s_andn2_b64 vcc, exec, s[78:79]
	s_cbranch_vccnz .LBB0_53
	s_add_i32 s4, s18, 0xffffea60
	s_lshr_b32 s4, s4, 1
	s_and_b32 s26, s4, 0x7fffffc0
	s_add_i32 s4, s3, 0xfffd4c00
	s_and_b32 s4, s4, 0xfe0
	v_or_b32_e32 v10, s26, v48
	v_or_b32_e32 v4, s4, v1
	v_lshlrev_b64 v[2:3], 14, v[10:11]
	v_lshl_add_u64 v[2:3], s[8:9], 0, v[2:3]
	v_lshlrev_b32_e32 v10, 2, v4
	v_lshl_add_u64 v[2:3], v[2:3], 0, v[10:11]
	v_add_co_u32_e32 v4, vcc, 0x8000, v2
	s_nop 1
	v_addc_co_u32_e32 v5, vcc, 0, v3, vcc
	v_add_co_u32_e32 v6, vcc, 0x10000, v2
	s_nop 1
	v_addc_co_u32_e32 v7, vcc, 0, v3, vcc
	v_add_co_u32_e32 v8, vcc, 0x18000, v2
	s_nop 1
	v_addc_co_u32_e32 v9, vcc, 0, v3, vcc
	v_add_co_u32_e32 v46, vcc, 0x20000, v2
	s_nop 1
	v_addc_co_u32_e32 v47, vcc, 0, v3, vcc
	v_add_co_u32_e32 v64, vcc, 0x28000, v2
	s_nop 1
	v_addc_co_u32_e32 v65, vcc, 0, v3, vcc
	v_add_co_u32_e32 v66, vcc, 0x30000, v2
	s_nop 1
	v_addc_co_u32_e32 v67, vcc, 0, v3, vcc
	v_add_co_u32_e32 v68, vcc, 0x38000, v2
	s_nop 1
	v_addc_co_u32_e32 v69, vcc, 0, v3, vcc
	global_load_dword v10, v[2:3], off nt
	global_load_dword v72, v[4:5], off nt
	global_load_dword v73, v[6:7], off nt
	global_load_dword v74, v[8:9], off nt
	global_load_dword v75, v[46:47], off nt
	global_load_dword v76, v[64:65], off nt
	global_load_dword v77, v[66:67], off nt
	global_load_dword v78, v[68:69], off nt
	v_add_co_u32_e32 v4, vcc, 0x40000, v2
	s_nop 1
	v_addc_co_u32_e32 v5, vcc, 0, v3, vcc
	v_add_co_u32_e32 v6, vcc, 0x48000, v2
	s_nop 1
	v_addc_co_u32_e32 v7, vcc, 0, v3, vcc
	v_add_co_u32_e32 v8, vcc, 0x50000, v2
	s_nop 1
	v_addc_co_u32_e32 v9, vcc, 0, v3, vcc
	v_add_co_u32_e32 v46, vcc, 0x58000, v2
	s_nop 1
	v_addc_co_u32_e32 v47, vcc, 0, v3, vcc
	v_add_co_u32_e32 v64, vcc, 0x60000, v2
	s_nop 1
	v_addc_co_u32_e32 v65, vcc, 0, v3, vcc
	v_add_co_u32_e32 v66, vcc, 0x68000, v2
	s_nop 1
	v_addc_co_u32_e32 v67, vcc, 0, v3, vcc
	v_add_co_u32_e32 v68, vcc, 0x70000, v2
	s_nop 1
	v_addc_co_u32_e32 v69, vcc, 0, v3, vcc
	v_add_co_u32_e32 v70, vcc, 0x78000, v2
	s_nop 1
	v_addc_co_u32_e32 v71, vcc, 0, v3, vcc
	global_load_dword v79, v[4:5], off nt
	global_load_dword v80, v[6:7], off nt
	global_load_dword v81, v[8:9], off nt
	global_load_dword v82, v[46:47], off nt
	global_load_dword v83, v[64:65], off nt
	global_load_dword v84, v[66:67], off nt
	global_load_dword v85, v[68:69], off nt
	global_load_dword v86, v[70:71], off nt
	v_add_co_u32_e32 v4, vcc, 0x80000, v2
	s_nop 1
	v_addc_co_u32_e32 v5, vcc, 0, v3, vcc
	v_add_co_u32_e32 v6, vcc, 0x88000, v2
	s_nop 1
	v_addc_co_u32_e32 v7, vcc, 0, v3, vcc
	v_add_co_u32_e32 v8, vcc, 0x90000, v2
	s_nop 1
	v_addc_co_u32_e32 v9, vcc, 0, v3, vcc
	v_add_co_u32_e32 v46, vcc, 0x98000, v2
	s_nop 1
	v_addc_co_u32_e32 v47, vcc, 0, v3, vcc
	v_add_co_u32_e32 v64, vcc, 0xa0000, v2
	s_nop 1
	v_addc_co_u32_e32 v65, vcc, 0, v3, vcc
	v_add_co_u32_e32 v66, vcc, 0xa8000, v2
	s_nop 1
	v_addc_co_u32_e32 v67, vcc, 0, v3, vcc
	v_add_co_u32_e32 v68, vcc, 0xb0000, v2
	s_nop 1
	v_addc_co_u32_e32 v69, vcc, 0, v3, vcc
	v_add_co_u32_e32 v70, vcc, 0xb8000, v2
	s_nop 1
	v_addc_co_u32_e32 v71, vcc, 0, v3, vcc
	global_load_dword v87, v[4:5], off nt
	global_load_dword v88, v[6:7], off nt
	global_load_dword v89, v[8:9], off nt
	global_load_dword v90, v[46:47], off nt
	global_load_dword v91, v[64:65], off nt
	global_load_dword v92, v[66:67], off nt
	global_load_dword v93, v[68:69], off nt
	s_nop 0
	global_load_dword v70, v[70:71], off nt
	v_add_co_u32_e32 v4, vcc, 0xc0000, v2
	s_nop 1
	v_addc_co_u32_e32 v5, vcc, 0, v3, vcc
	v_add_co_u32_e32 v6, vcc, 0xc8000, v2
	s_nop 1
	v_addc_co_u32_e32 v7, vcc, 0, v3, vcc
	v_add_co_u32_e32 v8, vcc, 0xd0000, v2
	s_nop 1
	v_addc_co_u32_e32 v9, vcc, 0, v3, vcc
	v_add_co_u32_e32 v46, vcc, 0xd8000, v2
	s_nop 1
	v_addc_co_u32_e32 v47, vcc, 0, v3, vcc
	v_add_co_u32_e32 v64, vcc, 0xe0000, v2
	s_nop 1
	v_addc_co_u32_e32 v65, vcc, 0, v3, vcc
	v_add_co_u32_e32 v66, vcc, 0xe8000, v2
	s_nop 1
	v_addc_co_u32_e32 v67, vcc, 0, v3, vcc
	v_add_co_u32_e32 v68, vcc, 0xf0000, v2
	s_nop 1
	v_addc_co_u32_e32 v69, vcc, 0, v3, vcc
	v_add_co_u32_e32 v2, vcc, 0xf8000, v2
	s_nop 1
	v_addc_co_u32_e32 v3, vcc, 0, v3, vcc
	global_load_dword v71, v[4:5], off nt
	global_load_dword v94, v[6:7], off nt
	global_load_dword v95, v[8:9], off nt
	s_nop 0
	global_load_dword v46, v[46:47], off nt
	s_nop 0
	global_load_dword v47, v[64:65], off nt
	s_nop 0
	global_load_dword v64, v[66:67], off nt
	global_load_dword v65, v[68:69], off nt
	s_nop 0
	global_load_dword v66, v[2:3], off nt
	v_lshl_add_u64 v[6:7], s[26:27], 2, v[18:19]
	global_load_dwordx4 v[2:5], v[6:7], off nt
	s_nop 0
	global_load_dwordx4 v[6:9], v[6:7], off offset:16 nt
	s_waitcnt vmcnt(32)
	ds_write2_b32 v49, v10, v72 offset1:66
	s_waitcnt vmcnt(30)
	ds_write2_b32 v49, v73, v74 offset0:132 offset1:198
	s_waitcnt vmcnt(28)
	ds_write2_b32 v57, v75, v76 offset0:8 offset1:74
	s_waitcnt vmcnt(26)
	ds_write2_b32 v57, v77, v78 offset0:140 offset1:206
	s_waitcnt vmcnt(24)
	ds_write2_b32 v58, v79, v80 offset0:16 offset1:82
	s_waitcnt vmcnt(22)
	ds_write2_b32 v58, v81, v82 offset0:148 offset1:214
	s_waitcnt vmcnt(20)
	ds_write2_b32 v59, v83, v84 offset0:24 offset1:90
	s_waitcnt vmcnt(18)
	ds_write2_b32 v59, v85, v86 offset0:156 offset1:222
	s_waitcnt vmcnt(16)
	ds_write2_b32 v60, v87, v88 offset0:32 offset1:98
	s_waitcnt vmcnt(14)
	ds_write2_b32 v60, v89, v90 offset0:164 offset1:230
	s_waitcnt vmcnt(12)
	ds_write2_b32 v61, v91, v92 offset0:40 offset1:106
	s_waitcnt vmcnt(10)
	ds_write2_b32 v61, v93, v70 offset0:172 offset1:238
	s_waitcnt vmcnt(8)
	ds_write2_b32 v62, v71, v94 offset0:48 offset1:114
	s_waitcnt vmcnt(6)
	ds_write2_b32 v62, v95, v46 offset0:180 offset1:246
	s_waitcnt vmcnt(4)
	ds_write2_b32 v63, v47, v64 offset0:56 offset1:122
	s_waitcnt vmcnt(2)
	ds_write2_b32 v63, v65, v66 offset0:188 offset1:254
	s_waitcnt lgkmcnt(0)
	ds_read2_b32 v[68:69], v51 offset0:33 offset1:41
	ds_read2_b32 v[70:71], v51 offset1:8
	ds_read2_b32 v[72:73], v51 offset0:66 offset1:74
	ds_read2_b32 v[74:75], v51 offset0:99 offset1:107
	ds_read2_b32 v[78:79], v51 offset0:132 offset1:140
	ds_read2_b32 v[80:81], v51 offset0:165 offset1:173
	ds_read2_b32 v[82:83], v51 offset0:198 offset1:206
	ds_read2_b32 v[84:85], v51 offset0:231 offset1:239
	s_waitcnt vmcnt(1)
	v_mov_b32_e32 v76, v2
	v_mov_b32_e32 v77, v4
	v_mov_b32_e32 v4, v3
	s_waitcnt lgkmcnt(7)
	v_mov_b32_e32 v2, v68
	s_waitcnt lgkmcnt(4)
	v_mov_b32_e32 v3, v74
	s_waitcnt vmcnt(0)
	v_mov_b32_e32 v86, v6
	v_mov_b32_e32 v87, v8
	v_mov_b32_e32 v8, v7
	s_waitcnt lgkmcnt(2)
	v_mov_b32_e32 v6, v80
	s_waitcnt lgkmcnt(0)
	v_mov_b32_e32 v7, v84
	v_mov_b32_e32 v64, v70
	v_mov_b32_e32 v65, v72
	v_pk_mul_f32 v[2:3], v[4:5], v[2:3]
	v_mov_b32_e32 v66, v78
	v_mov_b32_e32 v67, v82
	v_pk_mul_f32 v[6:7], v[8:9], v[6:7]
	v_pk_mul_f32 v[64:65], v[76:77], v[64:65]
	v_pk_mul_f32 v[66:67], v[86:87], v[66:67]
	v_bfe_u32 v10, v7, 16, 1
	v_bfe_u32 v68, v6, 16, 1
	v_bfe_u32 v70, v3, 16, 1
	v_bfe_u32 v72, v2, 16, 1
	v_add3_u32 v2, v2, v72, s89
	v_add3_u32 v3, v3, v70, s89
	v_add3_u32 v6, v6, v68, s89
	v_add3_u32 v7, v7, v10, s89
	v_bfe_u32 v10, v64, 16, 1
	v_bfe_u32 v68, v65, 16, 1
	v_bfe_u32 v70, v66, 16, 1
	v_bfe_u32 v72, v67, 16, 1
	v_add3_u32 v67, v67, v72, s89
	v_add3_u32 v66, v66, v70, s89
	v_add3_u32 v65, v65, v68, s89
	v_add3_u32 v10, v64, v10, s89
	v_lshrrev_b32_e32 v10, 16, v10
	v_lshrrev_b32_e32 v64, 16, v65
	v_lshrrev_b32_e32 v65, 16, v66
	v_lshrrev_b32_e32 v66, 16, v67
	s_lshl_b32 s26, s26, 1
	v_and_or_b32 v67, v7, s90, v66
	v_and_or_b32 v66, v6, s90, v65
	v_and_or_b32 v65, v3, s90, v64
	v_and_or_b32 v64, v2, s90, v10
	v_or_b32_e32 v2, s4, v50
	v_lshl_add_u64 v[46:47], v[20:21], 0, s[26:27]
	v_lshlrev_b32_e32 v10, 11, v2
	v_lshl_add_u64 v[2:3], v[46:47], 0, v[10:11]
	v_mov_b32_e32 v74, v69
	v_mov_b32_e32 v84, v81
	global_store_dwordx4 v[2:3], v[64:67], off
	v_mov_b32_e32 v72, v71
	v_pk_mul_f32 v[6:7], v[4:5], v[74:75]
	v_mov_b32_e32 v82, v79
	v_pk_mul_f32 v[66:67], v[8:9], v[84:85]
	v_pk_mul_f32 v[2:3], v[76:77], v[72:73]
	v_pk_mul_f32 v[64:65], v[86:87], v[82:83]
	v_bfe_u32 v10, v67, 16, 1
	v_bfe_u32 v69, v7, 16, 1
	v_bfe_u32 v70, v6, 16, 1
	v_add3_u32 v7, v7, v69, s89
	v_add3_u32 v10, v67, v10, s89
	v_bfe_u32 v67, v2, 16, 1
	v_bfe_u32 v69, v64, 16, 1
	v_bfe_u32 v68, v66, 16, 1
	v_add3_u32 v6, v6, v70, s89
	v_bfe_u32 v70, v65, 16, 1
	v_add3_u32 v64, v64, v69, s89
	v_add3_u32 v2, v2, v67, s89
	v_add3_u32 v66, v66, v68, s89
	v_bfe_u32 v68, v3, 16, 1
	v_add3_u32 v65, v65, v70, s89
	v_lshrrev_b32_e32 v2, 16, v2
	v_lshrrev_b32_e32 v64, 16, v64
	v_add3_u32 v3, v3, v68, s89
	v_lshrrev_b32_e32 v65, 16, v65
	v_and_or_b32 v66, v66, s90, v64
	v_and_or_b32 v64, v6, s90, v2
	v_or_b32_e32 v2, s4, v52
	v_lshrrev_b32_e32 v3, 16, v3
	v_and_or_b32 v67, v10, s90, v65
	v_lshlrev_b32_e32 v10, 11, v2
	v_and_or_b32 v65, v7, s90, v3
	v_lshl_add_u64 v[2:3], v[46:47], 0, v[10:11]
	ds_read2_b32 v[6:7], v51 offset0:16 offset1:24
	ds_read2_b32 v[68:69], v51 offset0:82 offset1:90
	global_store_dwordx4 v[2:3], v[64:67], off
	ds_read2_b32 v[2:3], v51 offset0:49 offset1:57
	ds_read2_b32 v[70:71], v51 offset0:115 offset1:123
	ds_read2_b32 v[72:73], v51 offset0:148 offset1:156
	ds_read2_b32 v[74:75], v51 offset0:214 offset1:222
	ds_read2_b32 v[78:79], v51 offset0:181 offset1:189
	ds_read2_b32 v[80:81], v51 offset0:247 offset1:255
	s_waitcnt lgkmcnt(7)
	v_mov_b32_e32 v64, v6
	s_waitcnt lgkmcnt(5)
	v_mov_b32_e32 v66, v2
	s_waitcnt lgkmcnt(4)
	v_mov_b32_e32 v67, v70
	s_waitcnt lgkmcnt(3)
	v_mov_b32_e32 v82, v72
	s_waitcnt lgkmcnt(2)
	v_mov_b32_e32 v83, v74
	v_mov_b32_e32 v65, v68
	v_pk_mul_f32 v[66:67], v[4:5], v[66:67]
	v_pk_mul_f32 v[82:83], v[86:87], v[82:83]
	s_waitcnt lgkmcnt(1)
	v_mov_b32_e32 v84, v78
	s_waitcnt lgkmcnt(0)
	v_mov_b32_e32 v85, v80
	v_pk_mul_f32 v[64:65], v[76:77], v[64:65]
	v_pk_mul_f32 v[84:85], v[8:9], v[84:85]
	v_bfe_u32 v10, v67, 16, 1
	v_bfe_u32 v68, v66, 16, 1
	v_bfe_u32 v72, v83, 16, 1
	v_bfe_u32 v2, v85, 16, 1
	v_add3_u32 v68, v66, v68, s89
	v_add3_u32 v10, v67, v10, s89
	v_bfe_u32 v66, v64, 16, 1
	v_bfe_u32 v67, v65, 16, 1
	v_add3_u32 v72, v83, v72, s89
	v_add3_u32 v2, v85, v2, s89
	v_bfe_u32 v70, v82, 16, 1
	v_add3_u32 v65, v65, v67, s89
	v_add3_u32 v64, v64, v66, s89
	v_lshrrev_b32_e32 v67, 16, v72
	v_bfe_u32 v6, v84, 16, 1
	v_add3_u32 v70, v82, v70, s89
	v_lshrrev_b32_e32 v64, 16, v64
	v_lshrrev_b32_e32 v65, 16, v65
	v_and_or_b32 v67, v2, s90, v67
	v_or_b32_e32 v2, s4, v53
	v_mov_b32_e32 v80, v79
	v_add3_u32 v6, v84, v6, s89
	v_lshrrev_b32_e32 v66, 16, v70
	v_and_or_b32 v65, v10, s90, v65
	v_and_or_b32 v64, v68, s90, v64
	v_lshlrev_b32_e32 v10, 11, v2
	v_mov_b32_e32 v68, v7
	v_pk_mul_f32 v[8:9], v[8:9], v[80:81]
	v_and_or_b32 v66, v6, s90, v66
	v_lshl_add_u64 v[82:83], v[46:47], 0, v[10:11]
	v_pk_mul_f32 v[6:7], v[76:77], v[68:69]
	v_mov_b32_e32 v70, v3
	v_bfe_u32 v10, v9, 16, 1
	v_pk_mul_f32 v[2:3], v[4:5], v[70:71]
	v_mov_b32_e32 v74, v73
	v_add3_u32 v9, v9, v10, s89
	v_bfe_u32 v10, v6, 16, 1
	global_store_dwordx4 v[82:83], v[64:67], off
	v_pk_mul_f32 v[4:5], v[86:87], v[74:75]
	v_add3_u32 v6, v6, v10, s89
	v_bfe_u32 v64, v8, 16, 1
	v_bfe_u32 v65, v3, 16, 1
	v_bfe_u32 v66, v2, 16, 1
	v_add3_u32 v2, v2, v66, s89
	v_add3_u32 v3, v3, v65, s89
	v_add3_u32 v8, v8, v64, s89
	v_bfe_u32 v64, v7, 16, 1
	v_bfe_u32 v65, v4, 16, 1
	v_bfe_u32 v66, v5, 16, 1
	v_lshrrev_b32_e32 v6, 16, v6
	v_add3_u32 v5, v5, v66, s89
	v_add3_u32 v4, v4, v65, s89
	v_add3_u32 v7, v7, v64, s89
	v_and_or_b32 v2, v2, s90, v6
	v_or_b32_e32 v6, s4, v54
	v_lshrrev_b32_e32 v7, 16, v7
	v_lshrrev_b32_e32 v4, 16, v4
	v_lshrrev_b32_e32 v5, 16, v5
	v_lshlrev_b32_e32 v10, 11, v6
	v_and_or_b32 v5, v9, s90, v5
	v_and_or_b32 v4, v8, s90, v4
	v_and_or_b32 v3, v3, s90, v7
	v_lshl_add_u64 v[6:7], v[46:47], 0, v[10:11]
	global_store_dwordx4 v[6:7], v[2:5], off
	s_waitcnt lgkmcnt(0)

.LBB0_54:
	s_andn2_b64 vcc, exec, s[28:29]
	s_cbranch_vccnz .LBB0_59
	s_add_i32 s4, s18, 0xfffff260
	s_lshr_b32 s4, s4, 1
	s_and_b32 s26, s4, 0x7fffffc0
	s_add_i32 s4, s3, 0xfffe4c00
	s_and_b32 s4, s4, 0xfe0
	v_or_b32_e32 v10, s26, v48
	v_or_b32_e32 v4, s4, v1
	v_lshlrev_b64 v[2:3], 14, v[10:11]
	v_lshl_add_u64 v[2:3], s[48:49], 0, v[2:3]
	v_lshlrev_b32_e32 v10, 2, v4
	v_lshl_add_u64 v[2:3], v[2:3], 0, v[10:11]
	v_add_co_u32_e32 v4, vcc, 0x8000, v2
	s_nop 1
	v_addc_co_u32_e32 v5, vcc, 0, v3, vcc
	v_add_co_u32_e32 v6, vcc, 0x10000, v2
	s_nop 1
	v_addc_co_u32_e32 v7, vcc, 0, v3, vcc
	v_add_co_u32_e32 v8, vcc, 0x18000, v2
	s_nop 1
	v_addc_co_u32_e32 v9, vcc, 0, v3, vcc
	v_add_co_u32_e32 v46, vcc, 0x20000, v2
	s_nop 1
	v_addc_co_u32_e32 v47, vcc, 0, v3, vcc
	v_add_co_u32_e32 v64, vcc, 0x28000, v2
	s_nop 1
	v_addc_co_u32_e32 v65, vcc, 0, v3, vcc
	v_add_co_u32_e32 v66, vcc, 0x30000, v2
	s_nop 1
	v_addc_co_u32_e32 v67, vcc, 0, v3, vcc
	v_add_co_u32_e32 v68, vcc, 0x38000, v2
	s_nop 1
	v_addc_co_u32_e32 v69, vcc, 0, v3, vcc
	global_load_dword v10, v[2:3], off nt
	global_load_dword v72, v[4:5], off nt
	global_load_dword v73, v[6:7], off nt
	global_load_dword v74, v[8:9], off nt
	global_load_dword v75, v[46:47], off nt
	global_load_dword v76, v[64:65], off nt
	global_load_dword v77, v[66:67], off nt
	global_load_dword v78, v[68:69], off nt
	v_add_co_u32_e32 v4, vcc, 0x40000, v2
	s_nop 1
	v_addc_co_u32_e32 v5, vcc, 0, v3, vcc
	v_add_co_u32_e32 v6, vcc, 0x48000, v2
	s_nop 1
	v_addc_co_u32_e32 v7, vcc, 0, v3, vcc
	v_add_co_u32_e32 v8, vcc, 0x50000, v2
	s_nop 1
	v_addc_co_u32_e32 v9, vcc, 0, v3, vcc
	v_add_co_u32_e32 v46, vcc, 0x58000, v2
	s_nop 1
	v_addc_co_u32_e32 v47, vcc, 0, v3, vcc
	v_add_co_u32_e32 v64, vcc, 0x60000, v2
	s_nop 1
	v_addc_co_u32_e32 v65, vcc, 0, v3, vcc
	v_add_co_u32_e32 v66, vcc, 0x68000, v2
	s_nop 1
	v_addc_co_u32_e32 v67, vcc, 0, v3, vcc
	v_add_co_u32_e32 v68, vcc, 0x70000, v2
	s_nop 1
	v_addc_co_u32_e32 v69, vcc, 0, v3, vcc
	v_add_co_u32_e32 v70, vcc, 0x78000, v2
	s_nop 1
	v_addc_co_u32_e32 v71, vcc, 0, v3, vcc
	global_load_dword v79, v[4:5], off nt
	global_load_dword v80, v[6:7], off nt
	global_load_dword v81, v[8:9], off nt
	global_load_dword v82, v[46:47], off nt
	global_load_dword v83, v[64:65], off nt
	global_load_dword v84, v[66:67], off nt
	global_load_dword v85, v[68:69], off nt
	global_load_dword v86, v[70:71], off nt
	v_add_co_u32_e32 v4, vcc, 0x80000, v2
	s_nop 1
	v_addc_co_u32_e32 v5, vcc, 0, v3, vcc
	v_add_co_u32_e32 v6, vcc, 0x88000, v2
	s_nop 1
	v_addc_co_u32_e32 v7, vcc, 0, v3, vcc
	v_add_co_u32_e32 v8, vcc, 0x90000, v2
	s_nop 1
	v_addc_co_u32_e32 v9, vcc, 0, v3, vcc
	v_add_co_u32_e32 v46, vcc, 0x98000, v2
	s_nop 1
	v_addc_co_u32_e32 v47, vcc, 0, v3, vcc
	v_add_co_u32_e32 v64, vcc, 0xa0000, v2
	s_nop 1
	v_addc_co_u32_e32 v65, vcc, 0, v3, vcc
	v_add_co_u32_e32 v66, vcc, 0xa8000, v2
	s_nop 1
	v_addc_co_u32_e32 v67, vcc, 0, v3, vcc
	v_add_co_u32_e32 v68, vcc, 0xb0000, v2
	s_nop 1
	v_addc_co_u32_e32 v69, vcc, 0, v3, vcc
	v_add_co_u32_e32 v70, vcc, 0xb8000, v2
	s_nop 1
	v_addc_co_u32_e32 v71, vcc, 0, v3, vcc
	global_load_dword v87, v[4:5], off nt
	global_load_dword v88, v[6:7], off nt
	global_load_dword v89, v[8:9], off nt
	global_load_dword v90, v[46:47], off nt
	global_load_dword v91, v[64:65], off nt
	global_load_dword v92, v[66:67], off nt
	s_nop 0
	global_load_dword v68, v[68:69], off nt
	s_nop 0
	global_load_dword v69, v[70:71], off nt
	v_add_co_u32_e32 v4, vcc, 0xc0000, v2
	s_nop 1
	v_addc_co_u32_e32 v5, vcc, 0, v3, vcc
	v_add_co_u32_e32 v6, vcc, 0xc8000, v2
	s_nop 1
	v_addc_co_u32_e32 v7, vcc, 0, v3, vcc
	v_add_co_u32_e32 v8, vcc, 0xd0000, v2
	s_nop 1
	v_addc_co_u32_e32 v9, vcc, 0, v3, vcc
	v_add_co_u32_e32 v46, vcc, 0xd8000, v2
	s_nop 1
	v_addc_co_u32_e32 v47, vcc, 0, v3, vcc
	v_add_co_u32_e32 v64, vcc, 0xe0000, v2
	s_nop 1
	v_addc_co_u32_e32 v65, vcc, 0, v3, vcc
	v_add_co_u32_e32 v66, vcc, 0xe8000, v2
	s_nop 1
	v_addc_co_u32_e32 v67, vcc, 0, v3, vcc
	global_load_dword v70, v[4:5], off nt
	s_nop 0
	global_load_dword v6, v[6:7], off nt
	s_nop 0
	global_load_dword v7, v[8:9], off nt
	s_nop 0
	global_load_dword v8, v[46:47], off nt
	global_load_dword v9, v[64:65], off nt
	s_nop 0
	global_load_dword v46, v[66:67], off nt
	v_add_co_u32_e32 v4, vcc, 0xf0000, v2
	s_nop 1
	v_addc_co_u32_e32 v5, vcc, 0, v3, vcc
	v_add_co_u32_e32 v2, vcc, 0xf8000, v2
	s_nop 1
	v_addc_co_u32_e32 v3, vcc, 0, v3, vcc
	global_load_dword v4, v[4:5], off nt
	s_nop 0
	global_load_dword v2, v[2:3], off nt
	s_andn2_b64 vcc, exec, s[10:11]
	s_waitcnt vmcnt(30)
	ds_write2_b32 v49, v10, v72 offset1:66
	s_waitcnt vmcnt(28)
	ds_write2_b32 v49, v73, v74 offset0:132 offset1:198
	s_waitcnt vmcnt(26)
	ds_write2_b32 v57, v75, v76 offset0:8 offset1:74
	s_waitcnt vmcnt(24)
	ds_write2_b32 v57, v77, v78 offset0:140 offset1:206
	s_waitcnt vmcnt(22)
	ds_write2_b32 v58, v79, v80 offset0:16 offset1:82
	s_waitcnt vmcnt(20)
	ds_write2_b32 v58, v81, v82 offset0:148 offset1:214
	s_waitcnt vmcnt(18)
	ds_write2_b32 v59, v83, v84 offset0:24 offset1:90
	s_waitcnt vmcnt(16)
	ds_write2_b32 v59, v85, v86 offset0:156 offset1:222
	s_waitcnt vmcnt(14)
	ds_write2_b32 v60, v87, v88 offset0:32 offset1:98
	s_waitcnt vmcnt(12)
	ds_write2_b32 v60, v89, v90 offset0:164 offset1:230
	s_waitcnt vmcnt(10)
	ds_write2_b32 v61, v91, v92 offset0:40 offset1:106
	s_waitcnt vmcnt(8)
	ds_write2_b32 v61, v68, v69 offset0:172 offset1:238
	s_waitcnt vmcnt(6)
	ds_write2_b32 v62, v70, v6 offset0:48 offset1:114
	s_waitcnt vmcnt(4)
	ds_write2_b32 v62, v7, v8 offset0:180 offset1:246
	s_waitcnt vmcnt(2)
	ds_write2_b32 v63, v9, v46 offset0:56 offset1:122
	s_waitcnt vmcnt(0)
	ds_write2_b32 v63, v4, v2 offset0:188 offset1:254
	s_cbranch_vccnz .LBB0_57
	v_lshl_add_u64 v[6:7], s[26:27], 2, v[16:17]
	global_load_dwordx4 v[2:5], v[6:7], off nt
	s_nop 0
	global_load_dwordx4 v[6:9], v[6:7], off offset:16 nt
	s_waitcnt vmcnt(1)
	v_mov_b32_e32 v46, v3
	v_mov_b32_e32 v3, v4
	v_mov_b32_e32 v47, v5
	s_waitcnt vmcnt(0)
	v_mov_b32_e32 v4, v7
	v_mov_b32_e32 v7, v8
	v_mov_b32_e32 v5, v9
	s_branch .LBB0_58

.LBB0_60:
	s_andn2_b64 vcc, exec, s[28:29]
	s_cbranch_vccnz .LBB0_63
	s_andn2_b64 vcc, exec, s[78:79]
	s_cbranch_vccnz .LBB0_63
	s_add_i32 s4, s21, 0x3400
	s_and_b32 s5, s4, 0x7fffffc0
	s_and_b32 s4, s3, 0x3e0
	v_or_b32_e32 v10, s5, v48
	v_or_b32_e32 v4, s4, v1
	v_lshlrev_b64 v[2:3], 12, v[10:11]
	v_lshl_add_u64 v[2:3], s[46:47], 0, v[2:3]
	v_lshlrev_b32_e32 v10, 2, v4
	v_lshl_add_u64 v[2:3], v[2:3], 0, v[10:11]
	v_add_co_u32_e32 v4, vcc, 0x2000, v2
	s_lshl_b32 s26, s5, 1
	s_nop 0
	v_addc_co_u32_e32 v5, vcc, 0, v3, vcc
	v_add_co_u32_e32 v6, vcc, 0x4000, v2
	s_nop 1
	v_addc_co_u32_e32 v7, vcc, 0, v3, vcc
	v_add_co_u32_e32 v8, vcc, 0x6000, v2
	s_nop 1
	v_addc_co_u32_e32 v9, vcc, 0, v3, vcc
	v_add_co_u32_e32 v46, vcc, 0x8000, v2
	s_nop 1
	v_addc_co_u32_e32 v47, vcc, 0, v3, vcc
	v_add_co_u32_e32 v64, vcc, 0xa000, v2
	s_nop 1
	v_addc_co_u32_e32 v65, vcc, 0, v3, vcc
	v_add_co_u32_e32 v66, vcc, 0xc000, v2
	s_nop 1
	v_addc_co_u32_e32 v67, vcc, 0, v3, vcc
	v_add_co_u32_e32 v68, vcc, 0xe000, v2
	s_nop 1
	v_addc_co_u32_e32 v69, vcc, 0, v3, vcc
	global_load_dword v10, v[2:3], off nt
	global_load_dword v72, v[4:5], off nt
	global_load_dword v73, v[6:7], off nt
	global_load_dword v74, v[8:9], off nt
	global_load_dword v75, v[46:47], off nt
	global_load_dword v76, v[64:65], off nt
	global_load_dword v77, v[66:67], off nt
	global_load_dword v78, v[68:69], off nt
	v_add_co_u32_e32 v4, vcc, 0x10000, v2
	s_nop 1
	v_addc_co_u32_e32 v5, vcc, 0, v3, vcc
	v_add_co_u32_e32 v6, vcc, 0x12000, v2
	s_nop 1
	v_addc_co_u32_e32 v7, vcc, 0, v3, vcc
	v_add_co_u32_e32 v8, vcc, 0x14000, v2
	s_nop 1
	v_addc_co_u32_e32 v9, vcc, 0, v3, vcc
	v_add_co_u32_e32 v46, vcc, 0x16000, v2
	s_nop 1
	v_addc_co_u32_e32 v47, vcc, 0, v3, vcc
	v_add_co_u32_e32 v64, vcc, 0x18000, v2
	s_nop 1
	v_addc_co_u32_e32 v65, vcc, 0, v3, vcc
	v_add_co_u32_e32 v66, vcc, 0x1a000, v2
	s_nop 1
	v_addc_co_u32_e32 v67, vcc, 0, v3, vcc
	v_add_co_u32_e32 v68, vcc, 0x1c000, v2
	s_nop 1
	v_addc_co_u32_e32 v69, vcc, 0, v3, vcc
	v_add_co_u32_e32 v70, vcc, 0x1e000, v2
	s_nop 1
	v_addc_co_u32_e32 v71, vcc, 0, v3, vcc
	global_load_dword v79, v[4:5], off nt
	global_load_dword v80, v[6:7], off nt
	global_load_dword v81, v[8:9], off nt
	global_load_dword v82, v[46:47], off nt
	global_load_dword v83, v[64:65], off nt
	global_load_dword v84, v[66:67], off nt
	global_load_dword v85, v[68:69], off nt
	global_load_dword v86, v[70:71], off nt
	v_add_co_u32_e32 v4, vcc, 0x20000, v2
	s_nop 1
	v_addc_co_u32_e32 v5, vcc, 0, v3, vcc
	v_add_co_u32_e32 v6, vcc, 0x22000, v2
	s_nop 1
	v_addc_co_u32_e32 v7, vcc, 0, v3, vcc
	v_add_co_u32_e32 v8, vcc, 0x24000, v2
	s_nop 1
	v_addc_co_u32_e32 v9, vcc, 0, v3, vcc
	v_add_co_u32_e32 v46, vcc, 0x26000, v2
	s_nop 1
	v_addc_co_u32_e32 v47, vcc, 0, v3, vcc
	v_add_co_u32_e32 v64, vcc, 0x28000, v2
	s_nop 1
	v_addc_co_u32_e32 v65, vcc, 0, v3, vcc
	v_add_co_u32_e32 v66, vcc, 0x2a000, v2
	s_nop 1
	v_addc_co_u32_e32 v67, vcc, 0, v3, vcc
	v_add_co_u32_e32 v68, vcc, 0x2c000, v2
	s_nop 1
	v_addc_co_u32_e32 v69, vcc, 0, v3, vcc
	v_add_co_u32_e32 v70, vcc, 0x2e000, v2
	s_nop 1
	v_addc_co_u32_e32 v71, vcc, 0, v3, vcc
	global_load_dword v87, v[4:5], off nt
	global_load_dword v88, v[6:7], off nt
	global_load_dword v89, v[8:9], off nt
	global_load_dword v90, v[46:47], off nt
	global_load_dword v91, v[64:65], off nt
	global_load_dword v92, v[66:67], off nt
	global_load_dword v93, v[68:69], off nt
	s_nop 0
	global_load_dword v70, v[70:71], off nt
	v_add_co_u32_e32 v4, vcc, 0x30000, v2
	s_nop 1
	v_addc_co_u32_e32 v5, vcc, 0, v3, vcc
	v_add_co_u32_e32 v6, vcc, 0x32000, v2
	s_nop 1
	v_addc_co_u32_e32 v7, vcc, 0, v3, vcc
	v_add_co_u32_e32 v8, vcc, 0x34000, v2
	s_nop 1
	v_addc_co_u32_e32 v9, vcc, 0, v3, vcc
	v_add_co_u32_e32 v46, vcc, 0x36000, v2
	s_nop 1
	v_addc_co_u32_e32 v47, vcc, 0, v3, vcc
	v_add_co_u32_e32 v64, vcc, 0x38000, v2
	s_nop 1
	v_addc_co_u32_e32 v65, vcc, 0, v3, vcc
	v_add_co_u32_e32 v66, vcc, 0x3a000, v2
	s_nop 1
	v_addc_co_u32_e32 v67, vcc, 0, v3, vcc
	v_add_co_u32_e32 v68, vcc, 0x3c000, v2
	s_nop 1
	v_addc_co_u32_e32 v69, vcc, 0, v3, vcc
	v_add_co_u32_e32 v2, vcc, 0x3e000, v2
	s_nop 1
	v_addc_co_u32_e32 v3, vcc, 0, v3, vcc
	global_load_dword v4, v[4:5], off nt
	s_nop 0
	global_load_dword v5, v[6:7], off nt
	s_nop 0
	global_load_dword v6, v[8:9], off nt
	global_load_dword v7, v[46:47], off nt
	s_nop 0
	global_load_dword v8, v[64:65], off nt
	global_load_dword v9, v[66:67], off nt
	global_load_dword v46, v[68:69], off nt
	s_nop 0
	global_load_dword v2, v[2:3], off nt
	s_waitcnt vmcnt(30)
	ds_write2_b32 v49, v10, v72 offset1:66
	s_waitcnt vmcnt(28)
	ds_write2_b32 v49, v73, v74 offset0:132 offset1:198
	s_waitcnt vmcnt(26)
	ds_write2_b32 v57, v75, v76 offset0:8 offset1:74
	s_waitcnt vmcnt(24)
	ds_write2_b32 v57, v77, v78 offset0:140 offset1:206
	s_waitcnt vmcnt(22)
	ds_write2_b32 v58, v79, v80 offset0:16 offset1:82
	s_waitcnt vmcnt(20)
	ds_write2_b32 v58, v81, v82 offset0:148 offset1:214
	s_waitcnt vmcnt(18)
	ds_write2_b32 v59, v83, v84 offset0:24 offset1:90
	s_waitcnt vmcnt(16)
	ds_write2_b32 v59, v85, v86 offset0:156 offset1:222
	s_waitcnt vmcnt(14)
	ds_write2_b32 v60, v87, v88 offset0:32 offset1:98
	s_waitcnt vmcnt(12)
	ds_write2_b32 v60, v89, v90 offset0:164 offset1:230
	s_waitcnt vmcnt(10)
	ds_write2_b32 v61, v91, v92 offset0:40 offset1:106
	s_waitcnt vmcnt(8)
	ds_write2_b32 v61, v93, v70 offset0:172 offset1:238
	s_waitcnt vmcnt(6)
	ds_write2_b32 v62, v4, v5 offset0:48 offset1:114
	s_waitcnt vmcnt(4)
	ds_write2_b32 v62, v6, v7 offset0:180 offset1:246
	s_waitcnt vmcnt(2)
	ds_write2_b32 v63, v8, v9 offset0:56 offset1:122
	s_waitcnt vmcnt(0)
	ds_write2_b32 v63, v46, v2 offset0:188 offset1:254
	s_waitcnt lgkmcnt(0)
	ds_read2_b32 v[6:7], v51 offset1:8
	ds_read2_b32 v[46:47], v51 offset0:33 offset1:41
	ds_read2_b32 v[64:65], v51 offset0:66 offset1:74
	ds_read2_b32 v[66:67], v51 offset0:99 offset1:107
	ds_read2_b32 v[68:69], v51 offset0:132 offset1:140
	s_waitcnt lgkmcnt(4)
	v_bfe_u32 v2, v6, 16, 1
	v_add3_u32 v2, v6, v2, s89
	s_waitcnt lgkmcnt(3)
	v_bfe_u32 v3, v46, 16, 1
	v_lshrrev_b32_e32 v2, 16, v2
	v_add3_u32 v3, v46, v3, s89
	ds_read2_b32 v[70:71], v51 offset0:165 offset1:173
	v_and_or_b32 v2, v3, s90, v2
	s_waitcnt lgkmcnt(3)
	v_bfe_u32 v3, v64, 16, 1
	v_add3_u32 v3, v64, v3, s89
	s_waitcnt lgkmcnt(2)
	v_bfe_u32 v4, v66, 16, 1
	ds_read2_b32 v[72:73], v51 offset0:198 offset1:206
	v_lshrrev_b32_e32 v3, 16, v3
	v_add3_u32 v4, v66, v4, s89
	ds_read2_b32 v[74:75], v51 offset0:231 offset1:239
	v_and_or_b32 v3, v4, s90, v3
	s_waitcnt lgkmcnt(3)
	v_bfe_u32 v4, v68, 16, 1
	v_add3_u32 v4, v68, v4, s89
	s_waitcnt lgkmcnt(2)
	v_bfe_u32 v5, v70, 16, 1
	v_lshrrev_b32_e32 v4, 16, v4
	v_add3_u32 v5, v70, v5, s89
	v_and_or_b32 v4, v5, s90, v4
	s_waitcnt lgkmcnt(1)
	v_bfe_u32 v5, v72, 16, 1
	v_add3_u32 v5, v72, v5, s89
	s_waitcnt lgkmcnt(0)
	v_bfe_u32 v6, v74, 16, 1
	v_lshrrev_b32_e32 v5, 16, v5
	v_add3_u32 v6, v74, v6, s89
	v_and_or_b32 v5, v6, s90, v5
	v_or_b32_e32 v6, s4, v50
	v_lshl_add_u64 v[8:9], v[22:23], 0, s[26:27]
	v_lshlrev_b32_e32 v10, 11, v6
	v_lshl_add_u64 v[76:77], v[8:9], 0, v[10:11]
	global_store_dwordx4 v[76:77], v[2:5], off
	v_bfe_u32 v6, v75, 16, 1
	v_or_b32_e32 v10, s4, v52
	v_bfe_u32 v2, v7, 16, 1
	v_add3_u32 v2, v7, v2, s89
	v_bfe_u32 v3, v47, 16, 1
	v_lshrrev_b32_e32 v2, 16, v2
	v_add3_u32 v3, v47, v3, s89
	v_and_or_b32 v2, v3, s90, v2
	v_bfe_u32 v3, v65, 16, 1
	v_add3_u32 v3, v65, v3, s89
	v_bfe_u32 v4, v67, 16, 1
	v_lshrrev_b32_e32 v3, 16, v3
	v_add3_u32 v4, v67, v4, s89
	v_and_or_b32 v3, v4, s90, v3
	v_bfe_u32 v4, v69, 16, 1
	v_add3_u32 v4, v69, v4, s89
	v_bfe_u32 v5, v71, 16, 1
	v_lshrrev_b32_e32 v4, 16, v4
	v_add3_u32 v5, v71, v5, s89
	v_and_or_b32 v4, v5, s90, v4
	v_bfe_u32 v5, v73, 16, 1
	v_add3_u32 v5, v73, v5, s89
	v_lshrrev_b32_e32 v5, 16, v5
	v_add3_u32 v6, v75, v6, s89
	v_lshlrev_b32_e32 v10, 11, v10
	v_and_or_b32 v5, v6, s90, v5
	ds_read2_b32 v[6:7], v51 offset0:16 offset1:24
	v_lshl_add_u64 v[46:47], v[8:9], 0, v[10:11]
	global_store_dwordx4 v[46:47], v[2:5], off
	ds_read2_b32 v[46:47], v51 offset0:49 offset1:57
	ds_read2_b32 v[64:65], v51 offset0:82 offset1:90
	ds_read2_b32 v[66:67], v51 offset0:115 offset1:123
	s_waitcnt lgkmcnt(3)
	v_bfe_u32 v2, v6, 16, 1
	v_add3_u32 v2, v6, v2, s89
	s_waitcnt lgkmcnt(2)
	v_bfe_u32 v3, v46, 16, 1
	ds_read2_b32 v[68:69], v51 offset0:148 offset1:156
	v_lshrrev_b32_e32 v2, 16, v2
	v_add3_u32 v3, v46, v3, s89
	ds_read2_b32 v[70:71], v51 offset0:181 offset1:189
	v_and_or_b32 v2, v3, s90, v2
	s_waitcnt lgkmcnt(3)
	v_bfe_u32 v3, v64, 16, 1
	v_add3_u32 v3, v64, v3, s89
	s_waitcnt lgkmcnt(2)
	v_bfe_u32 v4, v66, 16, 1
	ds_read2_b32 v[72:73], v51 offset0:214 offset1:222
	v_lshrrev_b32_e32 v3, 16, v3
	v_add3_u32 v4, v66, v4, s89
	ds_read2_b32 v[74:75], v51 offset0:247 offset1:255
	v_and_or_b32 v3, v4, s90, v3
	s_waitcnt lgkmcnt(3)
	v_bfe_u32 v4, v68, 16, 1
	v_add3_u32 v4, v68, v4, s89
	s_waitcnt lgkmcnt(2)
	v_bfe_u32 v5, v70, 16, 1
	v_lshrrev_b32_e32 v4, 16, v4
	v_add3_u32 v5, v70, v5, s89
	v_and_or_b32 v4, v5, s90, v4
	s_waitcnt lgkmcnt(1)
	v_bfe_u32 v5, v72, 16, 1
	v_add3_u32 v5, v72, v5, s89
	s_waitcnt lgkmcnt(0)
	v_bfe_u32 v6, v74, 16, 1
	v_lshrrev_b32_e32 v5, 16, v5
	v_add3_u32 v6, v74, v6, s89
	v_and_or_b32 v5, v6, s90, v5
	v_or_b32_e32 v6, s4, v53
	v_lshlrev_b32_e32 v10, 11, v6
	v_lshl_add_u64 v[76:77], v[8:9], 0, v[10:11]
	global_store_dwordx4 v[76:77], v[2:5], off
	v_bfe_u32 v6, v75, 16, 1
	v_add3_u32 v6, v75, v6, s89
	v_bfe_u32 v2, v7, 16, 1
	v_add3_u32 v2, v7, v2, s89
	v_bfe_u32 v3, v47, 16, 1
	v_lshrrev_b32_e32 v2, 16, v2
	v_add3_u32 v3, v47, v3, s89
	v_and_or_b32 v2, v3, s90, v2
	v_bfe_u32 v3, v65, 16, 1
	v_add3_u32 v3, v65, v3, s89
	v_bfe_u32 v4, v67, 16, 1
	v_lshrrev_b32_e32 v3, 16, v3
	v_add3_u32 v4, v67, v4, s89
	v_and_or_b32 v3, v4, s90, v3
	v_bfe_u32 v4, v69, 16, 1
	v_add3_u32 v4, v69, v4, s89
	v_bfe_u32 v5, v71, 16, 1
	v_lshrrev_b32_e32 v4, 16, v4
	v_add3_u32 v5, v71, v5, s89
	v_and_or_b32 v4, v5, s90, v4
	v_bfe_u32 v5, v73, 16, 1
	v_add3_u32 v5, v73, v5, s89
	v_lshrrev_b32_e32 v5, 16, v5
	v_and_or_b32 v5, v6, s90, v5
	v_or_b32_e32 v6, s4, v54
	v_lshlrev_b32_e32 v10, 11, v6
	v_lshl_add_u64 v[6:7], v[8:9], 0, v[10:11]
	global_store_dwordx4 v[6:7], v[2:5], off
	s_waitcnt lgkmcnt(0)

.LBB0_69:
	s_and_b32 s5, 0xffff, s5
	s_lshl_b32 s5, s5, 6
	v_or_b32_e32 v3, s5, v48
	v_mul_u32_u24_e32 v3, 0x600, v3
	v_lshlrev_b32_e32 v10, 2, v3
	v_lshl_add_u64 v[4:5], s[44:45], 0, v[10:11]
	v_mov_b32_e32 v3, v11
	v_lshl_add_u64 v[2:3], v[2:3], 2, v[4:5]
	v_add_co_u32_e32 v4, vcc, 0x3000, v2
	s_nop 1
	v_addc_co_u32_e32 v5, vcc, 0, v3, vcc
	v_add_co_u32_e32 v6, vcc, s35, v2
	s_nop 1
	v_addc_co_u32_e32 v7, vcc, 0, v3, vcc
	v_add_co_u32_e32 v8, vcc, 0x9000, v2
	s_nop 1
	v_addc_co_u32_e32 v9, vcc, 0, v3, vcc
	v_add_co_u32_e32 v46, vcc, s42, v2
	s_nop 1
	v_addc_co_u32_e32 v47, vcc, 0, v3, vcc
	v_add_co_u32_e32 v64, vcc, 0xf000, v2
	s_nop 1
	v_addc_co_u32_e32 v65, vcc, 0, v3, vcc
	v_add_co_u32_e32 v66, vcc, s53, v2
	s_nop 1
	v_addc_co_u32_e32 v67, vcc, 0, v3, vcc
	v_add_co_u32_e32 v68, vcc, 0x15000, v2
	s_nop 1
	v_addc_co_u32_e32 v69, vcc, 0, v3, vcc
	global_load_dword v10, v[2:3], off nt
	global_load_dword v72, v[4:5], off nt
	global_load_dword v73, v[6:7], off nt
	global_load_dword v74, v[8:9], off nt
	global_load_dword v75, v[46:47], off nt
	global_load_dword v76, v[64:65], off nt
	global_load_dword v77, v[66:67], off nt
	global_load_dword v78, v[68:69], off nt
	v_add_co_u32_e32 v4, vcc, s54, v2
	s_nop 1
	v_addc_co_u32_e32 v5, vcc, 0, v3, vcc
	v_add_co_u32_e32 v6, vcc, 0x1b000, v2
	s_nop 1
	v_addc_co_u32_e32 v7, vcc, 0, v3, vcc
	v_add_co_u32_e32 v8, vcc, s55, v2
	s_nop 1
	v_addc_co_u32_e32 v9, vcc, 0, v3, vcc
	v_add_co_u32_e32 v46, vcc, 0x21000, v2
	s_nop 1
	v_addc_co_u32_e32 v47, vcc, 0, v3, vcc
	v_add_co_u32_e32 v64, vcc, s60, v2
	s_nop 1
	v_addc_co_u32_e32 v65, vcc, 0, v3, vcc
	v_add_co_u32_e32 v66, vcc, 0x27000, v2
	s_nop 1
	v_addc_co_u32_e32 v67, vcc, 0, v3, vcc
	v_add_co_u32_e32 v68, vcc, s61, v2
	s_nop 1
	v_addc_co_u32_e32 v69, vcc, 0, v3, vcc
	v_add_co_u32_e32 v70, vcc, 0x2d000, v2
	s_nop 1
	v_addc_co_u32_e32 v71, vcc, 0, v3, vcc
	global_load_dword v79, v[4:5], off nt
	global_load_dword v80, v[6:7], off nt
	global_load_dword v81, v[8:9], off nt
	global_load_dword v82, v[46:47], off nt
	global_load_dword v83, v[64:65], off nt
	global_load_dword v84, v[66:67], off nt
	global_load_dword v85, v[68:69], off nt
	global_load_dword v86, v[70:71], off nt
	v_add_co_u32_e32 v4, vcc, s64, v2
	s_nop 1
	v_addc_co_u32_e32 v5, vcc, 0, v3, vcc
	v_add_co_u32_e32 v6, vcc, 0x33000, v2
	s_nop 1
	v_addc_co_u32_e32 v7, vcc, 0, v3, vcc
	v_add_co_u32_e32 v8, vcc, s65, v2
	s_nop 1
	v_addc_co_u32_e32 v9, vcc, 0, v3, vcc
	v_add_co_u32_e32 v46, vcc, 0x39000, v2
	s_nop 1
	v_addc_co_u32_e32 v47, vcc, 0, v3, vcc
	v_add_co_u32_e32 v64, vcc, s88, v2
	s_nop 1
	v_addc_co_u32_e32 v65, vcc, 0, v3, vcc
	v_add_co_u32_e32 v66, vcc, 0x3f000, v2
	s_nop 1
	v_addc_co_u32_e32 v67, vcc, 0, v3, vcc
	v_add_co_u32_e32 v68, vcc, 0x42000, v2
	s_nop 1
	v_addc_co_u32_e32 v69, vcc, 0, v3, vcc
	v_add_co_u32_e32 v70, vcc, 0x45000, v2
	s_nop 1
	v_addc_co_u32_e32 v71, vcc, 0, v3, vcc
	global_load_dword v87, v[4:5], off nt
	global_load_dword v88, v[6:7], off nt
	global_load_dword v89, v[8:9], off nt
	global_load_dword v90, v[46:47], off nt
	global_load_dword v91, v[64:65], off nt
	global_load_dword v92, v[66:67], off nt
	s_nop 0
	global_load_dword v68, v[68:69], off nt
	s_nop 0
	global_load_dword v69, v[70:71], off nt
	v_add_co_u32_e32 v4, vcc, s91, v2
	s_nop 1
	v_addc_co_u32_e32 v5, vcc, 0, v3, vcc
	v_add_co_u32_e32 v6, vcc, 0x4b000, v2
	s_nop 1
	v_addc_co_u32_e32 v7, vcc, 0, v3, vcc
	v_add_co_u32_e32 v8, vcc, 0x4e000, v2
	s_nop 1
	v_addc_co_u32_e32 v9, vcc, 0, v3, vcc
	v_add_co_u32_e32 v46, vcc, 0x51000, v2
	s_nop 1
	v_addc_co_u32_e32 v47, vcc, 0, v3, vcc
	v_add_co_u32_e32 v64, vcc, 0x54000, v2
	s_nop 1
	v_addc_co_u32_e32 v65, vcc, 0, v3, vcc
	v_add_co_u32_e32 v66, vcc, 0x57000, v2
	s_nop 1
	v_addc_co_u32_e32 v67, vcc, 0, v3, vcc
	global_load_dword v70, v[4:5], off nt
	s_nop 0
	global_load_dword v6, v[6:7], off nt
	s_nop 0
	global_load_dword v7, v[8:9], off nt
	s_nop 0
	global_load_dword v8, v[46:47], off nt
	global_load_dword v9, v[64:65], off nt
	s_nop 0
	global_load_dword v46, v[66:67], off nt
	v_add_co_u32_e32 v4, vcc, 0x5a000, v2
	s_nop 1
	v_addc_co_u32_e32 v5, vcc, 0, v3, vcc
	v_add_co_u32_e32 v2, vcc, 0x5d000, v2
	s_nop 1
	v_addc_co_u32_e32 v3, vcc, 0, v3, vcc
	global_load_dword v4, v[4:5], off nt
	s_nop 0
	global_load_dword v2, v[2:3], off nt
	s_andn2_b64 vcc, exec, s[12:13]
	s_waitcnt vmcnt(30)
	ds_write2_b32 v49, v10, v72 offset1:66
	s_waitcnt vmcnt(28)
	ds_write2_b32 v49, v73, v74 offset0:132 offset1:198
	s_waitcnt vmcnt(26)
	ds_write2_b32 v57, v75, v76 offset0:8 offset1:74
	s_waitcnt vmcnt(24)
	ds_write2_b32 v57, v77, v78 offset0:140 offset1:206
	s_waitcnt vmcnt(22)
	ds_write2_b32 v58, v79, v80 offset0:16 offset1:82
	s_waitcnt vmcnt(20)
	ds_write2_b32 v58, v81, v82 offset0:148 offset1:214
	s_waitcnt vmcnt(18)
	ds_write2_b32 v59, v83, v84 offset0:24 offset1:90
	s_waitcnt vmcnt(16)
	ds_write2_b32 v59, v85, v86 offset0:156 offset1:222
	s_waitcnt vmcnt(14)
	ds_write2_b32 v60, v87, v88 offset0:32 offset1:98
	s_waitcnt vmcnt(12)
	ds_write2_b32 v60, v89, v90 offset0:164 offset1:230
	s_waitcnt vmcnt(10)
	ds_write2_b32 v61, v91, v92 offset0:40 offset1:106
	s_waitcnt vmcnt(8)
	ds_write2_b32 v61, v68, v69 offset0:172 offset1:238
	s_waitcnt vmcnt(6)
	ds_write2_b32 v62, v70, v6 offset0:48 offset1:114
	s_waitcnt vmcnt(4)
	ds_write2_b32 v62, v7, v8 offset0:180 offset1:246
	s_waitcnt vmcnt(2)
	ds_write2_b32 v63, v9, v46 offset0:56 offset1:122
	s_waitcnt vmcnt(0)
	ds_write2_b32 v63, v4, v2 offset0:188 offset1:254
	s_cbranch_vccnz .LBB0_71
	s_lshl_b32 s26, s5, 2
	v_lshl_add_u64 v[6:7], v[24:25], 0, s[26:27]
	global_load_dwordx4 v[2:5], v[6:7], off nt
	s_nop 0
	global_load_dwordx4 v[6:9], v[6:7], off offset:16 nt
	s_waitcnt vmcnt(1)
	v_mov_b32_e32 v46, v3
	v_mov_b32_e32 v3, v4
	v_mov_b32_e32 v47, v5
	s_waitcnt vmcnt(0)
	v_mov_b32_e32 v4, v7
	v_mov_b32_e32 v7, v8
	v_mov_b32_e32 v5, v9
	s_branch .LBB0_72

.LBB0_74:
	s_andn2_b64 vcc, exec, s[28:29]
	s_cbranch_vccnz .LBB0_79
	s_and_b32 s4, s18, 0xfc0
	s_add_i32 s26, s4, 0xfffff680
	s_and_b32 s4, s3, 0x7e0
	v_or_b32_e32 v10, s26, v48
	v_or_b32_e32 v4, s4, v1
	v_lshlrev_b64 v[2:3], 13, v[10:11]
	v_lshl_add_u64 v[2:3], s[38:39], 0, v[2:3]
	v_lshlrev_b32_e32 v10, 2, v4
	v_lshl_add_u64 v[2:3], v[2:3], 0, v[10:11]
	v_add_co_u32_e32 v4, vcc, 0x4000, v2
	s_nop 1
	v_addc_co_u32_e32 v5, vcc, 0, v3, vcc
	v_add_co_u32_e32 v6, vcc, 0x8000, v2
	s_nop 1
	v_addc_co_u32_e32 v7, vcc, 0, v3, vcc
	v_add_co_u32_e32 v8, vcc, 0xc000, v2
	s_nop 1
	v_addc_co_u32_e32 v9, vcc, 0, v3, vcc
	v_add_co_u32_e32 v46, vcc, 0x10000, v2
	s_nop 1
	v_addc_co_u32_e32 v47, vcc, 0, v3, vcc
	v_add_co_u32_e32 v64, vcc, 0x14000, v2
	s_nop 1
	v_addc_co_u32_e32 v65, vcc, 0, v3, vcc
	v_add_co_u32_e32 v66, vcc, 0x18000, v2
	s_nop 1
	v_addc_co_u32_e32 v67, vcc, 0, v3, vcc
	v_add_co_u32_e32 v68, vcc, 0x1c000, v2
	s_nop 1
	v_addc_co_u32_e32 v69, vcc, 0, v3, vcc
	global_load_dword v10, v[2:3], off nt
	global_load_dword v72, v[4:5], off nt
	global_load_dword v73, v[6:7], off nt
	global_load_dword v74, v[8:9], off nt
	global_load_dword v75, v[46:47], off nt
	global_load_dword v76, v[64:65], off nt
	global_load_dword v77, v[66:67], off nt
	global_load_dword v78, v[68:69], off nt
	v_add_co_u32_e32 v4, vcc, 0x20000, v2
	s_nop 1
	v_addc_co_u32_e32 v5, vcc, 0, v3, vcc
	v_add_co_u32_e32 v6, vcc, 0x24000, v2
	s_nop 1
	v_addc_co_u32_e32 v7, vcc, 0, v3, vcc
	v_add_co_u32_e32 v8, vcc, 0x28000, v2
	s_nop 1
	v_addc_co_u32_e32 v9, vcc, 0, v3, vcc
	v_add_co_u32_e32 v46, vcc, 0x2c000, v2
	s_nop 1
	v_addc_co_u32_e32 v47, vcc, 0, v3, vcc
	v_add_co_u32_e32 v64, vcc, 0x30000, v2
	s_nop 1
	v_addc_co_u32_e32 v65, vcc, 0, v3, vcc
	v_add_co_u32_e32 v66, vcc, 0x34000, v2
	s_nop 1
	v_addc_co_u32_e32 v67, vcc, 0, v3, vcc
	v_add_co_u32_e32 v68, vcc, 0x38000, v2
	s_nop 1
	v_addc_co_u32_e32 v69, vcc, 0, v3, vcc
	v_add_co_u32_e32 v70, vcc, 0x3c000, v2
	s_nop 1
	v_addc_co_u32_e32 v71, vcc, 0, v3, vcc
	global_load_dword v79, v[4:5], off nt
	global_load_dword v80, v[6:7], off nt
	global_load_dword v81, v[8:9], off nt
	global_load_dword v82, v[46:47], off nt
	global_load_dword v83, v[64:65], off nt
	global_load_dword v84, v[66:67], off nt
	global_load_dword v85, v[68:69], off nt
	global_load_dword v86, v[70:71], off nt
	v_add_co_u32_e32 v4, vcc, 0x40000, v2
	s_nop 1
	v_addc_co_u32_e32 v5, vcc, 0, v3, vcc
	v_add_co_u32_e32 v6, vcc, 0x44000, v2
	s_nop 1
	v_addc_co_u32_e32 v7, vcc, 0, v3, vcc
	v_add_co_u32_e32 v8, vcc, 0x48000, v2
	s_nop 1
	v_addc_co_u32_e32 v9, vcc, 0, v3, vcc
	v_add_co_u32_e32 v46, vcc, 0x4c000, v2
	s_nop 1
	v_addc_co_u32_e32 v47, vcc, 0, v3, vcc
	v_add_co_u32_e32 v64, vcc, 0x50000, v2
	s_nop 1
	v_addc_co_u32_e32 v65, vcc, 0, v3, vcc
	v_add_co_u32_e32 v66, vcc, 0x54000, v2
	s_nop 1
	v_addc_co_u32_e32 v67, vcc, 0, v3, vcc
	v_add_co_u32_e32 v68, vcc, 0x58000, v2
	s_nop 1
	v_addc_co_u32_e32 v69, vcc, 0, v3, vcc
	v_add_co_u32_e32 v70, vcc, 0x5c000, v2
	s_nop 1
	v_addc_co_u32_e32 v71, vcc, 0, v3, vcc
	global_load_dword v87, v[4:5], off nt
	global_load_dword v88, v[6:7], off nt
	global_load_dword v89, v[8:9], off nt
	global_load_dword v90, v[46:47], off nt
	global_load_dword v91, v[64:65], off nt
	global_load_dword v92, v[66:67], off nt
	s_nop 0
	global_load_dword v68, v[68:69], off nt
	s_nop 0
	global_load_dword v69, v[70:71], off nt
	v_add_co_u32_e32 v4, vcc, 0x60000, v2
	s_nop 1
	v_addc_co_u32_e32 v5, vcc, 0, v3, vcc
	v_add_co_u32_e32 v6, vcc, 0x64000, v2
	s_nop 1
	v_addc_co_u32_e32 v7, vcc, 0, v3, vcc
	v_add_co_u32_e32 v8, vcc, 0x68000, v2
	s_nop 1
	v_addc_co_u32_e32 v9, vcc, 0, v3, vcc
	v_add_co_u32_e32 v46, vcc, 0x6c000, v2
	s_nop 1
	v_addc_co_u32_e32 v47, vcc, 0, v3, vcc
	v_add_co_u32_e32 v64, vcc, 0x70000, v2
	s_nop 1
	v_addc_co_u32_e32 v65, vcc, 0, v3, vcc
	v_add_co_u32_e32 v66, vcc, 0x74000, v2
	s_nop 1
	v_addc_co_u32_e32 v67, vcc, 0, v3, vcc
	global_load_dword v70, v[4:5], off nt
	s_nop 0
	global_load_dword v6, v[6:7], off nt
	s_nop 0
	global_load_dword v7, v[8:9], off nt
	s_nop 0
	global_load_dword v8, v[46:47], off nt
	global_load_dword v9, v[64:65], off nt
	s_nop 0
	global_load_dword v46, v[66:67], off nt
	v_add_co_u32_e32 v4, vcc, 0x78000, v2
	s_nop 1
	v_addc_co_u32_e32 v5, vcc, 0, v3, vcc
	v_add_co_u32_e32 v2, vcc, 0x7c000, v2
	s_nop 1
	v_addc_co_u32_e32 v3, vcc, 0, v3, vcc
	global_load_dword v4, v[4:5], off nt
	s_nop 0
	global_load_dword v2, v[2:3], off nt
	s_andn2_b64 vcc, exec, s[14:15]
	s_waitcnt vmcnt(30)
	ds_write2_b32 v49, v10, v72 offset1:66
	s_waitcnt vmcnt(28)
	ds_write2_b32 v49, v73, v74 offset0:132 offset1:198
	s_waitcnt vmcnt(26)
	ds_write2_b32 v57, v75, v76 offset0:8 offset1:74
	s_waitcnt vmcnt(24)
	ds_write2_b32 v57, v77, v78 offset0:140 offset1:206
	s_waitcnt vmcnt(22)
	ds_write2_b32 v58, v79, v80 offset0:16 offset1:82
	s_waitcnt vmcnt(20)
	ds_write2_b32 v58, v81, v82 offset0:148 offset1:214
	s_waitcnt vmcnt(18)
	ds_write2_b32 v59, v83, v84 offset0:24 offset1:90
	s_waitcnt vmcnt(16)
	ds_write2_b32 v59, v85, v86 offset0:156 offset1:222
	s_waitcnt vmcnt(14)
	ds_write2_b32 v60, v87, v88 offset0:32 offset1:98
	s_waitcnt vmcnt(12)
	ds_write2_b32 v60, v89, v90 offset0:164 offset1:230
	s_waitcnt vmcnt(10)
	ds_write2_b32 v61, v91, v92 offset0:40 offset1:106
	s_waitcnt vmcnt(8)
	ds_write2_b32 v61, v68, v69 offset0:172 offset1:238
	s_waitcnt vmcnt(6)
	ds_write2_b32 v62, v70, v6 offset0:48 offset1:114
	s_waitcnt vmcnt(4)
	ds_write2_b32 v62, v7, v8 offset0:180 offset1:246
	s_waitcnt vmcnt(2)
	ds_write2_b32 v63, v9, v46 offset0:56 offset1:122
	s_waitcnt vmcnt(0)
	ds_write2_b32 v63, v4, v2 offset0:188 offset1:254
	s_cbranch_vccnz .LBB0_77
	v_lshl_add_u64 v[6:7], s[26:27], 2, v[26:27]
	global_load_dwordx4 v[2:5], v[6:7], off nt
	s_nop 0
	global_load_dwordx4 v[6:9], v[6:7], off offset:16 nt
	s_waitcnt vmcnt(1)
	v_mov_b32_e32 v46, v3
	v_mov_b32_e32 v3, v4
	v_mov_b32_e32 v47, v5
	s_waitcnt vmcnt(0)
	v_mov_b32_e32 v4, v7
	v_mov_b32_e32 v7, v8
	v_mov_b32_e32 v5, v9
	s_branch .LBB0_78

.LBB0_80:
	s_andn2_b64 vcc, exec, s[28:29]
	s_cbranch_vccnz .LBB0_98
	s_add_i32 s4, s18, 0xf800
	s_and_b32 s5, s4, 0xffff
	s_mul_i32 s5, s5, 0xaaab
	s_lshr_b32 s26, s5, 20
	s_lshl_b32 s5, s26, 6
	s_mul_i32 s26, s26, 24
	s_sub_i32 s26, s4, s26
	s_lshl_b32 s4, s26, 5
	s_and_b32 s4, s4, 0xffe0
	s_and_b32 s26, s26, 0xffff
	v_or_b32_e32 v64, s4, v1
	s_cmp_gt_u32 s26, 7
	s_mov_b64 s[28:29], -1
	s_cbranch_scc0 .LBB0_93
	s_cmp_gt_u32 s26, 19
	s_cbranch_scc0 .LBB0_90
	s_cmp_gt_u32 s26, 21
	s_cbranch_scc0 .LBB0_85
	v_or_b32_e32 v2, s5, v48
	v_mul_u32_u24_e32 v2, 0x140, v2
	v_lshlrev_b32_e32 v10, 2, v2
	v_lshl_add_u64 v[2:3], s[66:67], 0, v[10:11]
	v_add_co_u32_e32 v4, vcc, 0x1000, v2
	global_load_dword v65, v10, s[66:67]
	s_nop 0
	global_load_dword v10, v10, s[66:67] offset:2560
	v_addc_co_u32_e32 v5, vcc, 0, v3, vcc
	v_add_co_u32_e32 v6, vcc, 0x2000, v2
	s_lshl_b32 s26, s5, 1
	s_nop 0
	v_addc_co_u32_e32 v7, vcc, 0, v3, vcc
	v_add_co_u32_e32 v8, vcc, 0x3000, v2
	s_mov_b64 s[28:29], 0
	s_nop 0
	v_addc_co_u32_e32 v9, vcc, 0, v3, vcc
	v_add_co_u32_e32 v46, vcc, 0x4000, v2
	s_nop 1
	v_addc_co_u32_e32 v47, vcc, 0, v3, vcc
	v_add_co_u32_e32 v66, vcc, 0x5000, v2
	s_nop 1
	v_addc_co_u32_e32 v67, vcc, 0, v3, vcc
	global_load_dword v68, v[4:5], off offset:1024 nt
	global_load_dword v69, v[4:5], off offset:3584 nt
	global_load_dword v70, v[6:7], off offset:2048 nt
	global_load_dword v71, v[8:9], off offset:512 nt
	global_load_dword v72, v[8:9], off offset:3072 nt
	global_load_dword v73, v[46:47], off offset:1536 nt
	global_load_dword v74, v[66:67], off nt
	global_load_dword v75, v[66:67], off offset:2560 nt
	v_add_co_u32_e32 v4, vcc, 0x6000, v2
	s_nop 1
	v_addc_co_u32_e32 v5, vcc, 0, v3, vcc
	v_add_co_u32_e32 v6, vcc, 0x7000, v2
	s_nop 1
	v_addc_co_u32_e32 v7, vcc, 0, v3, vcc
	v_add_co_u32_e32 v8, vcc, 0x8000, v2
	s_nop 1
	v_addc_co_u32_e32 v9, vcc, 0, v3, vcc
	v_add_co_u32_e32 v46, vcc, 0x9000, v2
	s_nop 1
	v_addc_co_u32_e32 v47, vcc, 0, v3, vcc
	v_add_co_u32_e32 v66, vcc, 0xa000, v2
	s_nop 1
	v_addc_co_u32_e32 v67, vcc, 0, v3, vcc
	global_load_dword v76, v[4:5], off offset:1024 nt
	global_load_dword v77, v[4:5], off offset:3584 nt
	global_load_dword v78, v[6:7], off offset:2048 nt
	global_load_dword v79, v[8:9], off offset:512 nt
	global_load_dword v80, v[8:9], off offset:3072 nt
	global_load_dword v81, v[46:47], off offset:1536 nt
	global_load_dword v82, v[66:67], off nt
	global_load_dword v83, v[66:67], off offset:2560 nt
	v_add_co_u32_e32 v4, vcc, 0xb000, v2
	s_nop 1
	v_addc_co_u32_e32 v5, vcc, 0, v3, vcc
	v_add_co_u32_e32 v6, vcc, 0xc000, v2
	s_nop 1
	v_addc_co_u32_e32 v7, vcc, 0, v3, vcc
	v_add_co_u32_e32 v8, vcc, 0xd000, v2
	s_nop 1
	v_addc_co_u32_e32 v9, vcc, 0, v3, vcc
	v_add_co_u32_e32 v46, vcc, 0xe000, v2
	s_nop 1
	v_addc_co_u32_e32 v47, vcc, 0, v3, vcc
	v_add_co_u32_e32 v66, vcc, 0xf000, v2
	s_nop 1
	v_addc_co_u32_e32 v67, vcc, 0, v3, vcc
	global_load_dword v84, v[4:5], off offset:1024 nt
	global_load_dword v85, v[4:5], off offset:3584 nt
	global_load_dword v86, v[6:7], off offset:2048 nt
	global_load_dword v87, v[8:9], off offset:512 nt
	global_load_dword v88, v[8:9], off offset:3072 nt
	s_nop 0
	global_load_dword v46, v[46:47], off offset:1536 nt
	s_nop 0
	global_load_dword v47, v[66:67], off nt
	s_nop 0
	global_load_dword v66, v[66:67], off offset:2560 nt
	v_add_co_u32_e32 v4, vcc, 0x10000, v2
	s_nop 1
	v_addc_co_u32_e32 v5, vcc, 0, v3, vcc
	v_add_co_u32_e32 v6, vcc, 0x11000, v2
	s_nop 1
	v_addc_co_u32_e32 v7, vcc, 0, v3, vcc
	v_add_co_u32_e32 v8, vcc, 0x12000, v2
	s_nop 1
	v_addc_co_u32_e32 v9, vcc, 0, v3, vcc
	global_load_dword v67, v[4:5], off offset:1024 nt
	s_nop 0
	global_load_dword v4, v[4:5], off offset:3584 nt
	s_nop 0
	global_load_dword v5, v[6:7], off offset:2048 nt
	s_nop 0
	global_load_dword v6, v[8:9], off offset:512 nt
	v_add_co_u32_e32 v2, vcc, 0x13000, v2
	s_waitcnt vmcnt(2)
	v_mul_f32_e32 v4, 0, v4
	v_addc_co_u32_e32 v3, vcc, 0, v3, vcc
	global_load_dword v7, v[8:9], off offset:3072 nt
	s_nop 0
	global_load_dword v2, v[2:3], off offset:1536 nt
	v_mul_f32_e32 v3, 0, v65
	v_mul_f32_e32 v8, 0, v10
	ds_write2_b32 v49, v3, v8 offset1:66
	v_mul_f32_e32 v3, 0, v68
	v_mul_f32_e32 v8, 0, v69
	ds_write2_b32 v49, v3, v8 offset0:132 offset1:198
	v_mul_f32_e32 v3, 0, v70
	v_mul_f32_e32 v8, 0, v71
	ds_write2_b32 v57, v3, v8 offset0:8 offset1:74
	v_mul_f32_e32 v3, 0, v72
	v_mul_f32_e32 v8, 0, v73
	ds_write2_b32 v57, v3, v8 offset0:140 offset1:206
	v_mul_f32_e32 v3, 0, v74
	v_mul_f32_e32 v8, 0, v75
	ds_write2_b32 v58, v3, v8 offset0:16 offset1:82
	v_mul_f32_e32 v3, 0, v76
	v_mul_f32_e32 v8, 0, v77
	ds_write2_b32 v58, v3, v8 offset0:148 offset1:214
	v_mul_f32_e32 v3, 0, v78
	v_mul_f32_e32 v8, 0, v79
	ds_write2_b32 v59, v3, v8 offset0:24 offset1:90
	v_mul_f32_e32 v3, 0, v80
	v_mul_f32_e32 v8, 0, v81
	ds_write2_b32 v59, v3, v8 offset0:156 offset1:222
	v_mul_f32_e32 v3, 0, v82
	v_mul_f32_e32 v8, 0, v83
	ds_write2_b32 v60, v3, v8 offset0:32 offset1:98
	v_mul_f32_e32 v3, 0, v84
	v_mul_f32_e32 v8, 0, v85
	ds_write2_b32 v60, v3, v8 offset0:164 offset1:230
	v_mul_f32_e32 v3, 0, v86
	v_mul_f32_e32 v8, 0, v87
	ds_write2_b32 v61, v3, v8 offset0:40 offset1:106
	v_mul_f32_e32 v3, 0, v88
	v_mul_f32_e32 v8, 0, v46
	ds_write2_b32 v61, v3, v8 offset0:172 offset1:238
	v_mul_f32_e32 v3, 0, v47
	v_mul_f32_e32 v8, 0, v66
	ds_write2_b32 v62, v3, v8 offset0:48 offset1:114
	v_mul_f32_e32 v3, 0, v67
	ds_write2_b32 v62, v3, v4 offset0:180 offset1:246
	s_waitcnt vmcnt(3)
	v_mul_f32_e32 v3, 0, v5
	s_waitcnt vmcnt(2)
	v_mul_f32_e32 v4, 0, v6
	ds_write2_b32 v63, v3, v4 offset0:56 offset1:122
	v_lshl_add_u64 v[8:9], v[28:29], 0, s[26:27]
	s_waitcnt vmcnt(1)
	v_mul_f32_e32 v3, 0, v7
	s_waitcnt vmcnt(0)
	v_mul_f32_e32 v2, 0, v2
	ds_write2_b32 v63, v3, v2 offset0:188 offset1:254
	s_waitcnt lgkmcnt(0)
	ds_read2_b32 v[6:7], v51 offset1:8
	ds_read2_b32 v[46:47], v51 offset0:33 offset1:41
	ds_read2_b32 v[66:67], v51 offset0:66 offset1:74
	ds_read2_b32 v[68:69], v51 offset0:99 offset1:107
	ds_read2_b32 v[70:71], v51 offset0:132 offset1:140
	s_waitcnt lgkmcnt(4)
	v_bfe_u32 v2, v6, 16, 1
	v_add3_u32 v2, v6, v2, s89
	s_waitcnt lgkmcnt(3)
	v_bfe_u32 v3, v46, 16, 1
	v_lshrrev_b32_e32 v2, 16, v2
	v_add3_u32 v3, v46, v3, s89
	ds_read2_b32 v[72:73], v51 offset0:165 offset1:173
	v_and_or_b32 v2, v3, s90, v2
	s_waitcnt lgkmcnt(3)
	v_bfe_u32 v3, v66, 16, 1
	v_add3_u32 v3, v66, v3, s89
	s_waitcnt lgkmcnt(2)
	v_bfe_u32 v4, v68, 16, 1
	ds_read2_b32 v[74:75], v51 offset0:198 offset1:206
	v_lshrrev_b32_e32 v3, 16, v3
	v_add3_u32 v4, v68, v4, s89
	ds_read2_b32 v[76:77], v51 offset0:231 offset1:239
	v_and_or_b32 v3, v4, s90, v3
	s_waitcnt lgkmcnt(3)
	v_bfe_u32 v4, v70, 16, 1
	v_add3_u32 v4, v70, v4, s89
	s_waitcnt lgkmcnt(2)
	v_bfe_u32 v5, v72, 16, 1
	v_lshrrev_b32_e32 v4, 16, v4
	v_add3_u32 v5, v72, v5, s89
	v_and_or_b32 v4, v5, s90, v4
	s_waitcnt lgkmcnt(1)
	v_bfe_u32 v5, v74, 16, 1
	v_add3_u32 v5, v74, v5, s89
	s_waitcnt lgkmcnt(0)
	v_bfe_u32 v6, v76, 16, 1
	v_lshrrev_b32_e32 v5, 16, v5
	v_add3_u32 v6, v76, v6, s89
	v_and_or_b32 v5, v6, s90, v5
	v_or_b32_e32 v6, s4, v50
	v_lshlrev_b32_e32 v10, 11, v6
	v_lshl_add_u64 v[78:79], v[8:9], 0, v[10:11]
	global_store_dwordx4 v[78:79], v[2:5], off
	v_bfe_u32 v6, v77, 16, 1
	v_or_b32_e32 v10, s4, v52
	v_bfe_u32 v2, v7, 16, 1
	v_add3_u32 v2, v7, v2, s89
	v_bfe_u32 v3, v47, 16, 1
	v_lshrrev_b32_e32 v2, 16, v2
	v_add3_u32 v3, v47, v3, s89
	v_and_or_b32 v2, v3, s90, v2
	v_bfe_u32 v3, v67, 16, 1
	v_add3_u32 v3, v67, v3, s89
	v_bfe_u32 v4, v69, 16, 1
	v_lshrrev_b32_e32 v3, 16, v3
	v_add3_u32 v4, v69, v4, s89
	v_and_or_b32 v3, v4, s90, v3
	v_bfe_u32 v4, v71, 16, 1
	v_add3_u32 v4, v71, v4, s89
	v_bfe_u32 v5, v73, 16, 1
	v_lshrrev_b32_e32 v4, 16, v4
	v_add3_u32 v5, v73, v5, s89
	v_and_or_b32 v4, v5, s90, v4
	v_bfe_u32 v5, v75, 16, 1
	v_add3_u32 v5, v75, v5, s89
	v_lshrrev_b32_e32 v5, 16, v5
	v_add3_u32 v6, v77, v6, s89
	v_lshlrev_b32_e32 v10, 11, v10
	v_and_or_b32 v5, v6, s90, v5
	ds_read2_b32 v[6:7], v51 offset0:16 offset1:24
	v_lshl_add_u64 v[46:47], v[8:9], 0, v[10:11]
	global_store_dwordx4 v[46:47], v[2:5], off
	ds_read2_b32 v[46:47], v51 offset0:49 offset1:57
	ds_read2_b32 v[66:67], v51 offset0:82 offset1:90
	ds_read2_b32 v[68:69], v51 offset0:115 offset1:123
	s_waitcnt lgkmcnt(3)
	v_bfe_u32 v2, v6, 16, 1
	v_add3_u32 v2, v6, v2, s89
	s_waitcnt lgkmcnt(2)
	v_bfe_u32 v3, v46, 16, 1
	ds_read2_b32 v[70:71], v51 offset0:148 offset1:156
	v_lshrrev_b32_e32 v2, 16, v2
	v_add3_u32 v3, v46, v3, s89
	ds_read2_b32 v[72:73], v51 offset0:181 offset1:189
	v_and_or_b32 v2, v3, s90, v2
	s_waitcnt lgkmcnt(3)
	v_bfe_u32 v3, v66, 16, 1
	v_add3_u32 v3, v66, v3, s89
	s_waitcnt lgkmcnt(2)
	v_bfe_u32 v4, v68, 16, 1
	ds_read2_b32 v[74:75], v51 offset0:214 offset1:222
	v_lshrrev_b32_e32 v3, 16, v3
	v_add3_u32 v4, v68, v4, s89
	ds_read2_b32 v[76:77], v51 offset0:247 offset1:255
	v_and_or_b32 v3, v4, s90, v3
	s_waitcnt lgkmcnt(3)
	v_bfe_u32 v4, v70, 16, 1
	v_add3_u32 v4, v70, v4, s89
	s_waitcnt lgkmcnt(2)
	v_bfe_u32 v5, v72, 16, 1
	v_lshrrev_b32_e32 v4, 16, v4
	v_add3_u32 v5, v72, v5, s89
	v_and_or_b32 v4, v5, s90, v4
	s_waitcnt lgkmcnt(1)
	v_bfe_u32 v5, v74, 16, 1
	v_add3_u32 v5, v74, v5, s89
	s_waitcnt lgkmcnt(0)
	v_bfe_u32 v6, v76, 16, 1
	v_lshrrev_b32_e32 v5, 16, v5
	v_add3_u32 v6, v76, v6, s89
	v_and_or_b32 v5, v6, s90, v5
	v_or_b32_e32 v6, s4, v53
	v_lshlrev_b32_e32 v10, 11, v6
	v_lshl_add_u64 v[78:79], v[8:9], 0, v[10:11]
	global_store_dwordx4 v[78:79], v[2:5], off
	v_bfe_u32 v6, v77, 16, 1
	v_add3_u32 v6, v77, v6, s89
	v_bfe_u32 v2, v7, 16, 1
	v_add3_u32 v2, v7, v2, s89
	v_bfe_u32 v3, v47, 16, 1
	v_lshrrev_b32_e32 v2, 16, v2
	v_add3_u32 v3, v47, v3, s89
	v_and_or_b32 v2, v3, s90, v2
	v_bfe_u32 v3, v67, 16, 1
	v_add3_u32 v3, v67, v3, s89
	v_bfe_u32 v4, v69, 16, 1
	v_lshrrev_b32_e32 v3, 16, v3
	v_add3_u32 v4, v69, v4, s89
	v_and_or_b32 v3, v4, s90, v3
	v_bfe_u32 v4, v71, 16, 1
	v_add3_u32 v4, v71, v4, s89
	v_bfe_u32 v5, v73, 16, 1
	v_lshrrev_b32_e32 v4, 16, v4
	v_add3_u32 v5, v73, v5, s89
	v_and_or_b32 v4, v5, s90, v4
	v_bfe_u32 v5, v75, 16, 1
	v_add3_u32 v5, v75, v5, s89
	v_lshrrev_b32_e32 v5, 16, v5
	v_and_or_b32 v5, v6, s90, v5
	v_or_b32_e32 v6, s4, v54
	v_lshlrev_b32_e32 v10, 11, v6
	v_lshl_add_u64 v[6:7], v[8:9], 0, v[10:11]
	global_store_dwordx4 v[6:7], v[2:5], off
	s_waitcnt lgkmcnt(0)
.LBB0_85:
	s_andn2_b64 vcc, exec, s[28:29]
	s_cbranch_vccnz .LBB0_89
	v_add_u32_e32 v2, 0xfffffd80, v64
	v_ashrrev_i32_e32 v2, 1, v2
	v_add_u32_e32 v65, v56, v2
	v_or_b32_e32 v2, s5, v48
	v_mul_u32_u24_e32 v2, 0x140, v2
	v_lshlrev_b32_e32 v10, 2, v2
	v_max_i32_e32 v4, 0, v65
	v_lshl_add_u64 v[2:3], s[66:67], 0, v[10:11]
	v_lshlrev_b32_e32 v10, 2, v4
	v_lshl_add_u64 v[2:3], v[2:3], 0, v[10:11]
	v_add_co_u32_e32 v4, vcc, 0x1000, v2
	s_nop 1
	v_addc_co_u32_e32 v5, vcc, 0, v3, vcc
	v_add_co_u32_e32 v6, vcc, s31, v2
	s_nop 1
	v_addc_co_u32_e32 v7, vcc, 0, v3, vcc
	v_add_co_u32_e32 v8, vcc, 0x3000, v2
	s_nop 1
	v_addc_co_u32_e32 v9, vcc, 0, v3, vcc
	v_add_co_u32_e32 v46, vcc, s34, v2
	s_nop 1
	v_addc_co_u32_e32 v47, vcc, 0, v3, vcc
	global_load_dword v10, v[2:3], off nt
	global_load_dword v68, v[2:3], off offset:2560 nt
	global_load_dword v69, v[4:5], off offset:1024 nt
	global_load_dword v70, v[4:5], off offset:3584 nt
	global_load_dword v71, v[6:7], off offset:2048 nt
	global_load_dword v72, v[8:9], off offset:512 nt
	global_load_dword v73, v[8:9], off offset:3072 nt
	global_load_dword v74, v[46:47], off offset:1536 nt
	v_add_co_u32_e32 v4, vcc, 0x5000, v2
	s_nop 1
	v_addc_co_u32_e32 v5, vcc, 0, v3, vcc
	v_add_co_u32_e32 v6, vcc, s35, v2
	s_nop 1
	v_addc_co_u32_e32 v7, vcc, 0, v3, vcc
	v_add_co_u32_e32 v8, vcc, 0x7000, v2
	s_nop 1
	v_addc_co_u32_e32 v9, vcc, 0, v3, vcc
	v_add_co_u32_e32 v46, vcc, s36, v2
	s_nop 1
	v_addc_co_u32_e32 v47, vcc, 0, v3, vcc
	v_add_co_u32_e32 v66, vcc, s92, v2
	s_nop 1
	v_addc_co_u32_e32 v67, vcc, 0, v3, vcc
	global_load_dword v75, v[4:5], off nt
	global_load_dword v76, v[4:5], off offset:2560 nt
	global_load_dword v77, v[6:7], off offset:1024 nt
	global_load_dword v78, v[6:7], off offset:3584 nt
	global_load_dword v79, v[8:9], off offset:2048 nt
	global_load_dword v80, v[46:47], off offset:512 nt
	global_load_dword v81, v[46:47], off offset:3072 nt
	global_load_dword v82, v[66:67], off offset:1536 nt
	v_add_co_u32_e32 v4, vcc, s37, v2
	s_nop 1
	v_addc_co_u32_e32 v5, vcc, 0, v3, vcc
	v_add_co_u32_e32 v6, vcc, s94, v2
	s_nop 1
	v_addc_co_u32_e32 v7, vcc, 0, v3, vcc
	v_add_co_u32_e32 v8, vcc, s42, v2
	s_nop 1
	v_addc_co_u32_e32 v9, vcc, 0, v3, vcc
	v_add_co_u32_e32 v46, vcc, s95, v2
	s_nop 1
	v_addc_co_u32_e32 v47, vcc, 0, v3, vcc
	v_add_co_u32_e32 v66, vcc, s43, v2
	s_nop 1
	v_addc_co_u32_e32 v67, vcc, 0, v3, vcc
	global_load_dword v83, v[4:5], off nt
	global_load_dword v84, v[4:5], off offset:2560 nt
	global_load_dword v85, v[6:7], off offset:1024 nt
	global_load_dword v86, v[6:7], off offset:3584 nt
	global_load_dword v87, v[8:9], off offset:2048 nt
	global_load_dword v88, v[46:47], off offset:512 nt
	global_load_dword v89, v[46:47], off offset:3072 nt
	s_nop 0
	global_load_dword v66, v[66:67], off offset:1536 nt
	v_add_co_u32_e32 v4, vcc, s93, v2
	s_nop 1
	v_addc_co_u32_e32 v5, vcc, 0, v3, vcc
	v_add_co_u32_e32 v6, vcc, s52, v2
	s_nop 1
	v_addc_co_u32_e32 v7, vcc, 0, v3, vcc
	v_add_co_u32_e32 v8, vcc, s96, v2
	s_nop 1
	v_addc_co_u32_e32 v9, vcc, 0, v3, vcc
	v_add_co_u32_e32 v46, vcc, s53, v2
	s_nop 1
	v_addc_co_u32_e32 v47, vcc, 0, v3, vcc
	v_add_co_u32_e32 v2, vcc, s97, v2
	global_load_dword v67, v[4:5], off nt
	s_nop 0
	global_load_dword v4, v[4:5], off offset:2560 nt
	s_nop 0
	global_load_dword v5, v[6:7], off offset:1024 nt
	s_nop 0
	global_load_dword v6, v[6:7], off offset:3584 nt
	s_nop 0
	global_load_dword v7, v[8:9], off offset:2048 nt
	s_nop 0
	global_load_dword v8, v[46:47], off offset:512 nt
	v_addc_co_u32_e32 v3, vcc, 0, v3, vcc
	global_load_dword v9, v[46:47], off offset:3072 nt
	s_nop 0
	global_load_dword v3, v[2:3], off offset:1536 nt
	v_cmp_gt_i32_e32 vcc, 0, v65
	v_mov_b32_e32 v2, 1.0
	s_nop 0
	v_cndmask_b32_e64 v46, 1.0, 0, vcc
	s_waitcnt vmcnt(31)
	v_mul_f32_e32 v10, v46, v10
	s_waitcnt vmcnt(30)
	v_mul_f32_e32 v47, v46, v68
	ds_write2_b32 v49, v10, v47 offset1:66
	s_waitcnt vmcnt(29)
	v_mul_f32_e32 v10, v46, v69
	s_waitcnt vmcnt(28)
	v_mul_f32_e32 v47, v46, v70
	ds_write2_b32 v49, v10, v47 offset0:132 offset1:198
	s_waitcnt vmcnt(27)
	v_mul_f32_e32 v10, v46, v71
	s_waitcnt vmcnt(26)
	v_mul_f32_e32 v47, v46, v72
	ds_write2_b32 v57, v10, v47 offset0:8 offset1:74
	s_waitcnt vmcnt(25)
	v_mul_f32_e32 v10, v46, v73
	s_waitcnt vmcnt(24)
	v_mul_f32_e32 v47, v46, v74
	ds_write2_b32 v57, v10, v47 offset0:140 offset1:206
	s_andn2_b64 vcc, exec, s[16:17]
	s_waitcnt vmcnt(23)
	v_mul_f32_e32 v10, v46, v75
	s_waitcnt vmcnt(22)
	v_mul_f32_e32 v47, v46, v76
	ds_write2_b32 v58, v10, v47 offset0:16 offset1:82
	s_waitcnt vmcnt(21)
	v_mul_f32_e32 v10, v46, v77
	s_waitcnt vmcnt(20)
	v_mul_f32_e32 v47, v46, v78
	ds_write2_b32 v58, v10, v47 offset0:148 offset1:214
	s_waitcnt vmcnt(19)
	v_mul_f32_e32 v10, v46, v79
	s_waitcnt vmcnt(18)
	v_mul_f32_e32 v47, v46, v80
	ds_write2_b32 v59, v10, v47 offset0:24 offset1:90
	s_waitcnt vmcnt(17)
	v_mul_f32_e32 v10, v46, v81
	s_waitcnt vmcnt(16)
	v_mul_f32_e32 v47, v46, v82
	ds_write2_b32 v59, v10, v47 offset0:156 offset1:222
	s_waitcnt vmcnt(15)
	v_mul_f32_e32 v10, v46, v83
	s_waitcnt vmcnt(14)
	v_mul_f32_e32 v47, v46, v84
	ds_write2_b32 v60, v10, v47 offset0:32 offset1:98
	s_waitcnt vmcnt(13)
	v_mul_f32_e32 v10, v46, v85
	s_waitcnt vmcnt(12)
	v_mul_f32_e32 v47, v46, v86
	ds_write2_b32 v60, v10, v47 offset0:164 offset1:230
	s_waitcnt vmcnt(11)
	v_mul_f32_e32 v10, v46, v87
	s_waitcnt vmcnt(10)
	v_mul_f32_e32 v47, v46, v88
	ds_write2_b32 v61, v10, v47 offset0:40 offset1:106
	s_waitcnt vmcnt(9)
	v_mul_f32_e32 v10, v46, v89
	s_waitcnt vmcnt(8)
	v_mul_f32_e32 v47, v46, v66
	ds_write2_b32 v61, v10, v47 offset0:172 offset1:238
	v_mov_b32_e32 v47, 1.0
	s_waitcnt vmcnt(7)
	v_mul_f32_e32 v10, v46, v67
	s_waitcnt vmcnt(6)
	v_mul_f32_e32 v4, v46, v4
	ds_write2_b32 v62, v10, v4 offset0:48 offset1:114
	s_waitcnt vmcnt(5)
	v_mul_f32_e32 v4, v46, v5
	s_waitcnt vmcnt(4)
	v_mul_f32_e32 v5, v46, v6
	ds_write2_b32 v62, v4, v5 offset0:180 offset1:246
	s_waitcnt vmcnt(3)
	v_mul_f32_e32 v4, v46, v7
	s_waitcnt vmcnt(2)
	v_mul_f32_e32 v5, v46, v8
	ds_write2_b32 v63, v4, v5 offset0:56 offset1:122
	s_waitcnt vmcnt(1)
	v_mul_f32_e32 v4, v46, v9
	s_waitcnt vmcnt(0)
	v_mul_f32_e32 v3, v46, v3
	ds_write2_b32 v63, v4, v3 offset0:188 offset1:254
	v_mov_b32_e32 v46, 1.0
	v_mov_b32_e32 v3, 1.0
	v_mov_b32_e32 v6, 1.0
	v_mov_b32_e32 v4, 1.0
	v_mov_b32_e32 v7, 1.0
	v_mov_b32_e32 v5, 1.0
	s_cbranch_vccnz .LBB0_88
	s_lshl_b32 s26, s5, 2
	v_lshl_add_u64 v[6:7], v[30:31], 0, s[26:27]
	global_load_dwordx4 v[2:5], v[6:7], off nt
	s_nop 0
	global_load_dwordx4 v[6:9], v[6:7], off offset:16 nt
	s_waitcnt vmcnt(1)
	v_mov_b32_e32 v46, v3
	v_mov_b32_e32 v3, v4
	v_mov_b32_e32 v47, v5
	s_waitcnt vmcnt(0)
	v_mov_b32_e32 v4, v7
	v_mov_b32_e32 v7, v8
	v_mov_b32_e32 v5, v9

.LBB0_90:
	s_andn2_b64 vcc, exec, s[28:29]
	s_cbranch_vccnz .LBB0_92
	v_or_b32_e32 v2, s5, v48
	v_mul_u32_u24_e32 v2, 0x180, v2
	v_lshlrev_b32_e32 v10, 2, v2
	v_max_i32_e32 v4, 0x100, v64
	v_lshl_add_u64 v[2:3], s[40:41], 0, v[10:11]
	v_lshlrev_b32_e32 v10, 2, v4
	v_lshl_add_u64 v[2:3], v[2:3], 0, v[10:11]
	v_add_co_u32_e32 v4, vcc, 0x1000, v2
	s_mov_b32 s26, 0x14000
	s_nop 0
	v_addc_co_u32_e32 v5, vcc, 0, v3, vcc
	v_add_co_u32_e32 v6, vcc, s31, v2
	s_nop 1
	v_addc_co_u32_e32 v7, vcc, 0, v3, vcc
	v_add_co_u32_e32 v8, vcc, 0x3000, v2
	s_nop 1
	v_addc_co_u32_e32 v9, vcc, 0, v3, vcc
	v_add_co_u32_e32 v46, vcc, s34, v2
	s_nop 1
	v_addc_co_u32_e32 v47, vcc, 0, v3, vcc
	v_add_co_u32_e32 v66, vcc, 0x5000, v2
	s_nop 1
	v_addc_co_u32_e32 v67, vcc, 0, v3, vcc
	global_load_dword v10, v[2:3], off offset:-1024 nt
	global_load_dword v65, v[2:3], off offset:2048 nt
	global_load_dword v72, v[4:5], off offset:1024 nt
	global_load_dword v73, v[6:7], off nt
	global_load_dword v74, v[6:7], off offset:3072 nt
	global_load_dword v75, v[8:9], off offset:2048 nt
	global_load_dword v76, v[46:47], off offset:1024 nt
	global_load_dword v77, v[66:67], off nt
	v_add_co_u32_e32 v4, vcc, s35, v2
	s_nop 1
	v_addc_co_u32_e32 v5, vcc, 0, v3, vcc
	v_add_co_u32_e32 v6, vcc, 0x7000, v2
	s_nop 1
	v_addc_co_u32_e32 v7, vcc, 0, v3, vcc
	v_add_co_u32_e32 v8, vcc, s36, v2
	s_nop 1
	v_addc_co_u32_e32 v9, vcc, 0, v3, vcc
	v_add_co_u32_e32 v46, vcc, s92, v2
	s_nop 1
	v_addc_co_u32_e32 v47, vcc, 0, v3, vcc
	v_add_co_u32_e32 v68, vcc, s37, v2
	s_nop 1
	v_addc_co_u32_e32 v69, vcc, 0, v3, vcc
	v_add_co_u32_e32 v70, vcc, s94, v2
	s_nop 1
	v_addc_co_u32_e32 v71, vcc, 0, v3, vcc
	global_load_dword v78, v[66:67], off offset:3072 nt
	global_load_dword v79, v[4:5], off offset:2048 nt
	global_load_dword v80, v[6:7], off offset:1024 nt
	global_load_dword v81, v[8:9], off nt
	global_load_dword v82, v[8:9], off offset:3072 nt
	global_load_dword v83, v[46:47], off offset:2048 nt
	global_load_dword v84, v[68:69], off offset:1024 nt
	global_load_dword v85, v[70:71], off nt
	v_add_co_u32_e32 v4, vcc, s42, v2
	s_nop 1
	v_addc_co_u32_e32 v5, vcc, 0, v3, vcc
	v_add_co_u32_e32 v6, vcc, s95, v2
	s_nop 1
	v_addc_co_u32_e32 v7, vcc, 0, v3, vcc
	v_add_co_u32_e32 v8, vcc, s43, v2
	s_nop 1
	v_addc_co_u32_e32 v9, vcc, 0, v3, vcc
	v_add_co_u32_e32 v46, vcc, s93, v2
	s_nop 1
	v_addc_co_u32_e32 v47, vcc, 0, v3, vcc
	v_add_co_u32_e32 v66, vcc, s52, v2
	s_nop 1
	v_addc_co_u32_e32 v67, vcc, 0, v3, vcc
	v_add_co_u32_e32 v68, vcc, s96, v2
	s_nop 1
	v_addc_co_u32_e32 v69, vcc, 0, v3, vcc
	global_load_dword v70, v[70:71], off offset:3072 nt
	s_nop 0
	global_load_dword v71, v[4:5], off offset:2048 nt
	global_load_dword v86, v[6:7], off offset:1024 nt
	global_load_dword v87, v[8:9], off nt
	global_load_dword v88, v[8:9], off offset:3072 nt
	global_load_dword v89, v[46:47], off offset:2048 nt
	global_load_dword v90, v[66:67], off offset:1024 nt
	global_load_dword v91, v[68:69], off nt
	v_add_co_u32_e32 v4, vcc, s53, v2
	s_nop 1
	v_addc_co_u32_e32 v5, vcc, 0, v3, vcc
	v_add_co_u32_e32 v6, vcc, s97, v2
	s_nop 1
	v_addc_co_u32_e32 v7, vcc, 0, v3, vcc
	v_add_co_u32_e32 v8, vcc, s26, v2
	s_mov_b32 s26, 0x15000
	s_nop 0
	v_addc_co_u32_e32 v9, vcc, 0, v3, vcc
	v_add_co_u32_e32 v46, vcc, s26, v2
	s_mov_b32 s26, 0x16000
	s_nop 0
	v_addc_co_u32_e32 v47, vcc, 0, v3, vcc
	v_add_co_u32_e32 v66, vcc, s26, v2
	s_mov_b32 s26, 0x17000
	s_nop 0
	v_addc_co_u32_e32 v67, vcc, 0, v3, vcc
	v_add_co_u32_e32 v2, vcc, s26, v2
	s_lshl_b32 s26, s5, 2
	s_nop 0
	v_addc_co_u32_e32 v3, vcc, 0, v3, vcc
	global_load_dword v68, v[68:69], off offset:3072 nt
	s_nop 0
	global_load_dword v69, v[4:5], off offset:2048 nt
	global_load_dword v92, v[6:7], off offset:1024 nt
	global_load_dword v93, v[8:9], off nt
	global_load_dword v94, v[8:9], off offset:3072 nt
	s_nop 0
	global_load_dword v46, v[46:47], off offset:2048 nt
	s_nop 0
	global_load_dword v47, v[66:67], off offset:1024 nt
	s_nop 0
	global_load_dword v66, v[2:3], off nt
	v_lshl_add_u64 v[6:7], v[34:35], 0, s[26:27]
	global_load_dwordx4 v[2:5], v[6:7], off nt
	s_nop 0
	global_load_dwordx4 v[6:9], v[6:7], off offset:16 nt
	s_lshl_b32 s26, s5, 1
	s_waitcnt vmcnt(32)
	ds_write2_b32 v49, v10, v65 offset1:66
	s_waitcnt vmcnt(30)
	ds_write2_b32 v49, v72, v73 offset0:132 offset1:198
	s_waitcnt vmcnt(28)
	ds_write2_b32 v57, v74, v75 offset0:8 offset1:74
	s_waitcnt vmcnt(26)
	ds_write2_b32 v57, v76, v77 offset0:140 offset1:206
	s_waitcnt vmcnt(24)
	ds_write2_b32 v58, v78, v79 offset0:16 offset1:82
	s_waitcnt vmcnt(22)
	ds_write2_b32 v58, v80, v81 offset0:148 offset1:214
	s_waitcnt vmcnt(20)
	ds_write2_b32 v59, v82, v83 offset0:24 offset1:90
	s_waitcnt vmcnt(18)
	ds_write2_b32 v59, v84, v85 offset0:156 offset1:222
	s_waitcnt vmcnt(16)
	ds_write2_b32 v60, v70, v71 offset0:32 offset1:98
	s_waitcnt vmcnt(14)
	ds_write2_b32 v60, v86, v87 offset0:164 offset1:230
	s_waitcnt vmcnt(12)
	ds_write2_b32 v61, v88, v89 offset0:40 offset1:106
	s_waitcnt vmcnt(10)
	ds_write2_b32 v61, v90, v91 offset0:172 offset1:238
	s_waitcnt vmcnt(8)
	ds_write2_b32 v62, v68, v69 offset0:48 offset1:114
	s_waitcnt vmcnt(6)
	ds_write2_b32 v62, v92, v93 offset0:180 offset1:246
	s_waitcnt vmcnt(4)
	ds_write2_b32 v63, v94, v46 offset0:56 offset1:122
	s_waitcnt vmcnt(2)
	ds_write2_b32 v63, v47, v66 offset0:188 offset1:254
	s_waitcnt lgkmcnt(0)
	ds_read2_b32 v[70:71], v51 offset0:33 offset1:41
	ds_read2_b32 v[72:73], v51 offset1:8
	ds_read2_b32 v[74:75], v51 offset0:66 offset1:74
	ds_read2_b32 v[76:77], v51 offset0:99 offset1:107
	ds_read2_b32 v[80:81], v51 offset0:132 offset1:140
	ds_read2_b32 v[82:83], v51 offset0:165 offset1:173
	ds_read2_b32 v[84:85], v51 offset0:198 offset1:206
	ds_read2_b32 v[86:87], v51 offset0:231 offset1:239
	s_waitcnt vmcnt(1)
	v_mov_b32_e32 v78, v2
	v_mov_b32_e32 v79, v4
	v_mov_b32_e32 v4, v3
	s_waitcnt lgkmcnt(7)
	v_mov_b32_e32 v2, v70
	s_waitcnt lgkmcnt(4)
	v_mov_b32_e32 v3, v76
	s_waitcnt vmcnt(0)
	v_mov_b32_e32 v88, v6
	v_mov_b32_e32 v89, v8
	v_mov_b32_e32 v8, v7
	s_waitcnt lgkmcnt(2)
	v_mov_b32_e32 v6, v82
	s_waitcnt lgkmcnt(0)
	v_mov_b32_e32 v7, v86
	v_mov_b32_e32 v66, v72
	v_mov_b32_e32 v67, v74
	v_pk_mul_f32 v[2:3], v[4:5], v[2:3]
	v_mov_b32_e32 v68, v80
	v_mov_b32_e32 v69, v84
	v_pk_mul_f32 v[6:7], v[8:9], v[6:7]
	v_pk_mul_f32 v[66:67], v[78:79], v[66:67]
	v_pk_mul_f32 v[68:69], v[88:89], v[68:69]
	v_bfe_u32 v10, v7, 16, 1
	v_bfe_u32 v70, v3, 16, 1
	v_add3_u32 v3, v3, v70, s89
	v_add3_u32 v7, v7, v10, s89
	v_bfe_u32 v10, v66, 16, 1
	v_bfe_u32 v70, v68, 16, 1
	v_bfe_u32 v65, v6, 16, 1
	v_bfe_u32 v72, v2, 16, 1
	v_add3_u32 v68, v68, v70, s89
	v_add3_u32 v10, v66, v10, s89
	v_add3_u32 v2, v2, v72, s89
	v_add3_u32 v6, v6, v65, s89
	v_bfe_u32 v65, v67, 16, 1
	v_bfe_u32 v72, v69, 16, 1
	v_lshrrev_b32_e32 v10, 16, v10
	v_lshrrev_b32_e32 v66, 16, v68
	v_add3_u32 v69, v69, v72, s89
	v_add3_u32 v65, v67, v65, s89
	v_and_or_b32 v68, v6, s90, v66
	v_and_or_b32 v66, v2, s90, v10
	v_or_b32_e32 v2, s4, v50
	v_lshl_add_u64 v[46:47], v[28:29], 0, s[26:27]
	v_lshrrev_b32_e32 v65, 16, v65
	v_lshrrev_b32_e32 v67, 16, v69
	v_lshlrev_b32_e32 v10, 11, v2
	v_and_or_b32 v69, v7, s90, v67
	v_and_or_b32 v67, v3, s90, v65
	v_lshl_add_u64 v[2:3], v[46:47], 0, v[10:11]
	v_mov_b32_e32 v76, v71
	v_mov_b32_e32 v86, v83
	global_store_dwordx4 v[2:3], v[66:69], off
	v_mov_b32_e32 v74, v73
	v_pk_mul_f32 v[6:7], v[4:5], v[76:77]
	v_mov_b32_e32 v84, v81
	v_pk_mul_f32 v[68:69], v[8:9], v[86:87]
	v_pk_mul_f32 v[2:3], v[78:79], v[74:75]
	v_pk_mul_f32 v[66:67], v[88:89], v[84:85]
	v_bfe_u32 v65, v68, 16, 1
	v_bfe_u32 v70, v7, 16, 1
	v_bfe_u32 v71, v6, 16, 1
	v_add3_u32 v7, v7, v70, s89
	v_add3_u32 v65, v68, v65, s89
	v_bfe_u32 v68, v2, 16, 1
	v_bfe_u32 v70, v66, 16, 1
	v_bfe_u32 v10, v69, 16, 1
	v_add3_u32 v6, v6, v71, s89
	v_bfe_u32 v71, v67, 16, 1
	v_add3_u32 v66, v66, v70, s89
	v_add3_u32 v2, v2, v68, s89
	v_add3_u32 v10, v69, v10, s89
	v_bfe_u32 v69, v3, 16, 1
	v_add3_u32 v67, v67, v71, s89
	v_lshrrev_b32_e32 v2, 16, v2
	v_lshrrev_b32_e32 v66, 16, v66
	v_add3_u32 v3, v3, v69, s89
	v_lshrrev_b32_e32 v67, 16, v67
	v_and_or_b32 v68, v65, s90, v66
	v_and_or_b32 v66, v6, s90, v2
	v_or_b32_e32 v2, s4, v52
	v_lshrrev_b32_e32 v3, 16, v3
	v_and_or_b32 v69, v10, s90, v67
	v_lshlrev_b32_e32 v10, 11, v2
	v_and_or_b32 v67, v7, s90, v3
	v_lshl_add_u64 v[2:3], v[46:47], 0, v[10:11]
	ds_read2_b32 v[6:7], v51 offset0:16 offset1:24
	ds_read2_b32 v[70:71], v51 offset0:82 offset1:90
	global_store_dwordx4 v[2:3], v[66:69], off
	ds_read2_b32 v[2:3], v51 offset0:49 offset1:57
	ds_read2_b32 v[72:73], v51 offset0:115 offset1:123
	ds_read2_b32 v[74:75], v51 offset0:148 offset1:156
	ds_read2_b32 v[76:77], v51 offset0:214 offset1:222
	ds_read2_b32 v[80:81], v51 offset0:181 offset1:189
	ds_read2_b32 v[82:83], v51 offset0:247 offset1:255
	s_waitcnt lgkmcnt(7)
	v_mov_b32_e32 v66, v6
	s_waitcnt lgkmcnt(5)
	v_mov_b32_e32 v68, v2
	s_waitcnt lgkmcnt(4)
	v_mov_b32_e32 v69, v72
	s_waitcnt lgkmcnt(3)
	v_mov_b32_e32 v84, v74
	s_waitcnt lgkmcnt(2)
	v_mov_b32_e32 v85, v76
	v_mov_b32_e32 v67, v70
	v_pk_mul_f32 v[68:69], v[4:5], v[68:69]
	v_pk_mul_f32 v[84:85], v[88:89], v[84:85]
	s_waitcnt lgkmcnt(1)
	v_mov_b32_e32 v86, v80
	s_waitcnt lgkmcnt(0)
	v_mov_b32_e32 v87, v82
	v_pk_mul_f32 v[66:67], v[78:79], v[66:67]
	v_pk_mul_f32 v[86:87], v[8:9], v[86:87]
	v_bfe_u32 v10, v69, 16, 1
	v_bfe_u32 v72, v85, 16, 1
	v_bfe_u32 v2, v87, 16, 1
	v_add3_u32 v10, v69, v10, s89
	v_bfe_u32 v69, v67, 16, 1
	v_add3_u32 v72, v85, v72, s89
	v_bfe_u32 v65, v68, 16, 1
	v_add3_u32 v2, v87, v2, s89
	v_bfe_u32 v70, v84, 16, 1
	v_add3_u32 v67, v67, v69, s89
	v_lshrrev_b32_e32 v69, 16, v72
	v_bfe_u32 v6, v86, 16, 1
	v_add3_u32 v65, v68, v65, s89
	v_bfe_u32 v68, v66, 16, 1
	v_add3_u32 v70, v84, v70, s89
	v_lshrrev_b32_e32 v67, 16, v67
	v_and_or_b32 v69, v2, s90, v69
	v_or_b32_e32 v2, s4, v53
	v_mov_b32_e32 v82, v81
	v_add3_u32 v6, v86, v6, s89
	v_add3_u32 v66, v66, v68, s89
	v_lshrrev_b32_e32 v68, 16, v70
	v_and_or_b32 v67, v10, s90, v67
	v_lshlrev_b32_e32 v10, 11, v2
	v_mov_b32_e32 v70, v7
	v_pk_mul_f32 v[8:9], v[8:9], v[82:83]
	v_lshrrev_b32_e32 v66, 16, v66
	v_and_or_b32 v68, v6, s90, v68
	v_lshl_add_u64 v[84:85], v[46:47], 0, v[10:11]
	v_pk_mul_f32 v[6:7], v[78:79], v[70:71]
	v_mov_b32_e32 v72, v3
	v_bfe_u32 v10, v9, 16, 1
	v_and_or_b32 v66, v65, s90, v66
	v_pk_mul_f32 v[2:3], v[4:5], v[72:73]
	v_mov_b32_e32 v76, v75
	v_add3_u32 v9, v9, v10, s89
	v_bfe_u32 v10, v6, 16, 1
	global_store_dwordx4 v[84:85], v[66:69], off
	v_pk_mul_f32 v[4:5], v[88:89], v[76:77]
	v_bfe_u32 v65, v8, 16, 1
	v_bfe_u32 v66, v3, 16, 1
	v_bfe_u32 v67, v2, 16, 1
	v_add3_u32 v6, v6, v10, s89
	v_add3_u32 v2, v2, v67, s89
	v_add3_u32 v3, v3, v66, s89
	v_add3_u32 v8, v8, v65, s89
	v_bfe_u32 v65, v7, 16, 1
	v_bfe_u32 v66, v4, 16, 1
	v_bfe_u32 v67, v5, 16, 1
	v_lshrrev_b32_e32 v6, 16, v6
	v_add3_u32 v5, v5, v67, s89
	v_add3_u32 v4, v4, v66, s89
	v_add3_u32 v7, v7, v65, s89
	v_and_or_b32 v2, v2, s90, v6
	v_or_b32_e32 v6, s4, v54
	v_lshrrev_b32_e32 v7, 16, v7
	v_lshrrev_b32_e32 v4, 16, v4
	v_lshrrev_b32_e32 v5, 16, v5
	v_lshlrev_b32_e32 v10, 11, v6
	v_and_or_b32 v5, v9, s90, v5
	v_and_or_b32 v4, v8, s90, v4
	v_and_or_b32 v3, v3, s90, v7
	v_lshl_add_u64 v[6:7], v[46:47], 0, v[10:11]
	global_store_dwordx4 v[6:7], v[2:5], off
	s_waitcnt lgkmcnt(0)

.LBB0_93:
	s_andn2_b64 vcc, exec, s[28:29]
	s_cbranch_vccnz .LBB0_98
	v_or_b32_e32 v2, s5, v48
	v_mul_u32_u24_e32 v2, 0x140, v2
	v_lshlrev_b32_e32 v10, 2, v2
	v_lshl_add_u64 v[2:3], s[66:67], 0, v[10:11]
	v_lshlrev_b32_e32 v10, 2, v64
	v_lshl_add_u64 v[2:3], v[2:3], 0, v[10:11]
	v_add_co_u32_e32 v4, vcc, 0x1000, v2
	s_nop 1
	v_addc_co_u32_e32 v5, vcc, 0, v3, vcc
	v_add_co_u32_e32 v6, vcc, s31, v2
	s_nop 1
	v_addc_co_u32_e32 v7, vcc, 0, v3, vcc
	v_add_co_u32_e32 v8, vcc, 0x3000, v2
	s_nop 1
	v_addc_co_u32_e32 v9, vcc, 0, v3, vcc
	v_add_co_u32_e32 v46, vcc, s34, v2
	s_nop 1
	v_addc_co_u32_e32 v47, vcc, 0, v3, vcc
	global_load_dword v10, v[2:3], off nt
	global_load_dword v66, v[2:3], off offset:2560 nt
	global_load_dword v67, v[4:5], off offset:1024 nt
	global_load_dword v68, v[4:5], off offset:3584 nt
	global_load_dword v69, v[6:7], off offset:2048 nt
	global_load_dword v70, v[8:9], off offset:512 nt
	global_load_dword v71, v[8:9], off offset:3072 nt
	global_load_dword v72, v[46:47], off offset:1536 nt
	v_add_co_u32_e32 v4, vcc, 0x5000, v2
	s_nop 1
	v_addc_co_u32_e32 v5, vcc, 0, v3, vcc
	v_add_co_u32_e32 v6, vcc, s35, v2
	s_nop 1
	v_addc_co_u32_e32 v7, vcc, 0, v3, vcc
	v_add_co_u32_e32 v8, vcc, 0x7000, v2
	s_nop 1
	v_addc_co_u32_e32 v9, vcc, 0, v3, vcc
	v_add_co_u32_e32 v46, vcc, s36, v2
	s_nop 1
	v_addc_co_u32_e32 v47, vcc, 0, v3, vcc
	v_add_co_u32_e32 v64, vcc, s92, v2
	s_nop 1
	v_addc_co_u32_e32 v65, vcc, 0, v3, vcc
	global_load_dword v73, v[4:5], off nt
	global_load_dword v74, v[4:5], off offset:2560 nt
	global_load_dword v75, v[6:7], off offset:1024 nt
	global_load_dword v76, v[6:7], off offset:3584 nt
	global_load_dword v77, v[8:9], off offset:2048 nt
	global_load_dword v78, v[46:47], off offset:512 nt
	global_load_dword v79, v[46:47], off offset:3072 nt
	global_load_dword v80, v[64:65], off offset:1536 nt
	v_add_co_u32_e32 v4, vcc, s37, v2
	s_nop 1
	v_addc_co_u32_e32 v5, vcc, 0, v3, vcc
	v_add_co_u32_e32 v6, vcc, s94, v2
	s_nop 1
	v_addc_co_u32_e32 v7, vcc, 0, v3, vcc
	v_add_co_u32_e32 v8, vcc, s42, v2
	s_nop 1
	v_addc_co_u32_e32 v9, vcc, 0, v3, vcc
	v_add_co_u32_e32 v46, vcc, s95, v2
	s_nop 1
	v_addc_co_u32_e32 v47, vcc, 0, v3, vcc
	v_add_co_u32_e32 v64, vcc, s43, v2
	s_nop 1
	v_addc_co_u32_e32 v65, vcc, 0, v3, vcc
	global_load_dword v81, v[4:5], off nt
	global_load_dword v82, v[4:5], off offset:2560 nt
	global_load_dword v83, v[6:7], off offset:1024 nt
	global_load_dword v84, v[6:7], off offset:3584 nt
	global_load_dword v85, v[8:9], off offset:2048 nt
	global_load_dword v86, v[46:47], off offset:512 nt
	global_load_dword v87, v[46:47], off offset:3072 nt
	s_nop 0
	global_load_dword v64, v[64:65], off offset:1536 nt
	v_add_co_u32_e32 v4, vcc, s93, v2
	s_nop 1
	v_addc_co_u32_e32 v5, vcc, 0, v3, vcc
	v_add_co_u32_e32 v6, vcc, s52, v2
	s_nop 1
	v_addc_co_u32_e32 v7, vcc, 0, v3, vcc
	v_add_co_u32_e32 v8, vcc, s96, v2
	s_nop 1
	v_addc_co_u32_e32 v9, vcc, 0, v3, vcc
	v_add_co_u32_e32 v46, vcc, s53, v2
	s_nop 1
	v_addc_co_u32_e32 v47, vcc, 0, v3, vcc
	v_add_co_u32_e32 v2, vcc, s97, v2
	global_load_dword v65, v[4:5], off nt
	s_nop 0
	global_load_dword v4, v[4:5], off offset:2560 nt
	s_nop 0
	global_load_dword v5, v[6:7], off offset:1024 nt
	s_nop 0
	global_load_dword v6, v[6:7], off offset:3584 nt
	s_nop 0
	global_load_dword v7, v[8:9], off offset:2048 nt
	s_nop 0
	global_load_dword v8, v[46:47], off offset:512 nt
	v_addc_co_u32_e32 v3, vcc, 0, v3, vcc
	global_load_dword v9, v[46:47], off offset:3072 nt
	s_nop 0
	global_load_dword v2, v[2:3], off offset:1536 nt
	s_andn2_b64 vcc, exec, s[16:17]
	s_waitcnt vmcnt(30)
	ds_write2_b32 v49, v10, v66 offset1:66
	s_waitcnt vmcnt(28)
	ds_write2_b32 v49, v67, v68 offset0:132 offset1:198
	s_waitcnt vmcnt(26)
	ds_write2_b32 v57, v69, v70 offset0:8 offset1:74
	s_waitcnt vmcnt(24)
	ds_write2_b32 v57, v71, v72 offset0:140 offset1:206
	s_waitcnt vmcnt(22)
	ds_write2_b32 v58, v73, v74 offset0:16 offset1:82
	s_waitcnt vmcnt(20)
	ds_write2_b32 v58, v75, v76 offset0:148 offset1:214
	s_waitcnt vmcnt(18)
	ds_write2_b32 v59, v77, v78 offset0:24 offset1:90
	s_waitcnt vmcnt(16)
	ds_write2_b32 v59, v79, v80 offset0:156 offset1:222
	s_waitcnt vmcnt(14)
	ds_write2_b32 v60, v81, v82 offset0:32 offset1:98
	s_waitcnt vmcnt(12)
	ds_write2_b32 v60, v83, v84 offset0:164 offset1:230
	s_waitcnt vmcnt(10)
	ds_write2_b32 v61, v85, v86 offset0:40 offset1:106
	s_waitcnt vmcnt(8)
	ds_write2_b32 v61, v87, v64 offset0:172 offset1:238
	s_waitcnt vmcnt(6)
	ds_write2_b32 v62, v65, v4 offset0:48 offset1:114
	s_waitcnt vmcnt(4)
	ds_write2_b32 v62, v5, v6 offset0:180 offset1:246
	s_waitcnt vmcnt(2)
	ds_write2_b32 v63, v7, v8 offset0:56 offset1:122
	s_waitcnt vmcnt(0)
	ds_write2_b32 v63, v9, v2 offset0:188 offset1:254
	s_cbranch_vccnz .LBB0_96
	s_lshl_b32 s26, s5, 2
	v_lshl_add_u64 v[6:7], v[30:31], 0, s[26:27]
	global_load_dwordx4 v[2:5], v[6:7], off nt
	s_nop 0
	global_load_dwordx4 v[6:9], v[6:7], off offset:16 nt
	s_waitcnt vmcnt(1)
	v_mov_b32_e32 v46, v3
	v_mov_b32_e32 v3, v4
	v_mov_b32_e32 v47, v5
	s_waitcnt vmcnt(0)
	v_mov_b32_e32 v4, v7
	v_mov_b32_e32 v7, v8
	v_mov_b32_e32 v5, v9
	s_branch .LBB0_97

.LBB0_99:
	s_andn2_b64 vcc, exec, s[28:29]
	s_cbranch_vccnz .LBB0_101
	s_add_i32 s4, s21, 0x3f40
	s_and_b32 s5, s4, 0x7fffffc0
	s_and_b32 s4, s3, 0x3e0
	v_or_b32_e32 v10, s5, v48
	v_or_b32_e32 v4, s4, v1
	v_lshlrev_b64 v[2:3], 12, v[10:11]
	v_lshl_add_u64 v[2:3], s[62:63], 0, v[2:3]
	v_lshlrev_b32_e32 v10, 2, v4
	v_lshl_add_u64 v[2:3], v[2:3], 0, v[10:11]
	v_add_co_u32_e32 v4, vcc, 0x2000, v2
	s_lshl_b32 s26, s5, 1
	s_nop 0
	v_addc_co_u32_e32 v5, vcc, 0, v3, vcc
	v_add_co_u32_e32 v6, vcc, 0x4000, v2
	s_nop 1
	v_addc_co_u32_e32 v7, vcc, 0, v3, vcc
	v_add_co_u32_e32 v8, vcc, 0x6000, v2
	s_nop 1
	v_addc_co_u32_e32 v9, vcc, 0, v3, vcc
	v_add_co_u32_e32 v46, vcc, 0x8000, v2
	s_nop 1
	v_addc_co_u32_e32 v47, vcc, 0, v3, vcc
	v_add_co_u32_e32 v64, vcc, 0xa000, v2
	s_nop 1
	v_addc_co_u32_e32 v65, vcc, 0, v3, vcc
	v_add_co_u32_e32 v66, vcc, 0xc000, v2
	s_nop 1
	v_addc_co_u32_e32 v67, vcc, 0, v3, vcc
	v_add_co_u32_e32 v68, vcc, 0xe000, v2
	s_nop 1
	v_addc_co_u32_e32 v69, vcc, 0, v3, vcc
	global_load_dword v10, v[2:3], off nt
	global_load_dword v72, v[4:5], off nt
	global_load_dword v73, v[6:7], off nt
	global_load_dword v74, v[8:9], off nt
	global_load_dword v75, v[46:47], off nt
	global_load_dword v76, v[64:65], off nt
	global_load_dword v77, v[66:67], off nt
	global_load_dword v78, v[68:69], off nt
	v_add_co_u32_e32 v4, vcc, 0x10000, v2
	s_nop 1
	v_addc_co_u32_e32 v5, vcc, 0, v3, vcc
	v_add_co_u32_e32 v6, vcc, 0x12000, v2
	s_nop 1
	v_addc_co_u32_e32 v7, vcc, 0, v3, vcc
	v_add_co_u32_e32 v8, vcc, 0x14000, v2
	s_nop 1
	v_addc_co_u32_e32 v9, vcc, 0, v3, vcc
	v_add_co_u32_e32 v46, vcc, 0x16000, v2
	s_nop 1
	v_addc_co_u32_e32 v47, vcc, 0, v3, vcc
	v_add_co_u32_e32 v64, vcc, 0x18000, v2
	s_nop 1
	v_addc_co_u32_e32 v65, vcc, 0, v3, vcc
	v_add_co_u32_e32 v66, vcc, 0x1a000, v2
	s_nop 1
	v_addc_co_u32_e32 v67, vcc, 0, v3, vcc
	v_add_co_u32_e32 v68, vcc, 0x1c000, v2
	s_nop 1
	v_addc_co_u32_e32 v69, vcc, 0, v3, vcc
	v_add_co_u32_e32 v70, vcc, 0x1e000, v2
	s_nop 1
	v_addc_co_u32_e32 v71, vcc, 0, v3, vcc
	global_load_dword v79, v[4:5], off nt
	global_load_dword v80, v[6:7], off nt
	global_load_dword v81, v[8:9], off nt
	global_load_dword v82, v[46:47], off nt
	global_load_dword v83, v[64:65], off nt
	global_load_dword v84, v[66:67], off nt
	global_load_dword v85, v[68:69], off nt
	global_load_dword v86, v[70:71], off nt
	v_add_co_u32_e32 v4, vcc, 0x20000, v2
	s_nop 1
	v_addc_co_u32_e32 v5, vcc, 0, v3, vcc
	v_add_co_u32_e32 v6, vcc, 0x22000, v2
	s_nop 1
	v_addc_co_u32_e32 v7, vcc, 0, v3, vcc
	v_add_co_u32_e32 v8, vcc, 0x24000, v2
	s_nop 1
	v_addc_co_u32_e32 v9, vcc, 0, v3, vcc
	v_add_co_u32_e32 v46, vcc, 0x26000, v2
	s_nop 1
	v_addc_co_u32_e32 v47, vcc, 0, v3, vcc
	v_add_co_u32_e32 v64, vcc, 0x28000, v2
	s_nop 1
	v_addc_co_u32_e32 v65, vcc, 0, v3, vcc
	v_add_co_u32_e32 v66, vcc, 0x2a000, v2
	s_nop 1
	v_addc_co_u32_e32 v67, vcc, 0, v3, vcc
	v_add_co_u32_e32 v68, vcc, 0x2c000, v2
	s_nop 1
	v_addc_co_u32_e32 v69, vcc, 0, v3, vcc
	v_add_co_u32_e32 v70, vcc, 0x2e000, v2
	s_nop 1
	v_addc_co_u32_e32 v71, vcc, 0, v3, vcc
	global_load_dword v87, v[4:5], off nt
	global_load_dword v88, v[6:7], off nt
	global_load_dword v89, v[8:9], off nt
	global_load_dword v90, v[46:47], off nt
	global_load_dword v91, v[64:65], off nt
	global_load_dword v92, v[66:67], off nt
	global_load_dword v93, v[68:69], off nt
	s_nop 0
	global_load_dword v70, v[70:71], off nt
	v_add_co_u32_e32 v4, vcc, 0x30000, v2
	s_nop 1
	v_addc_co_u32_e32 v5, vcc, 0, v3, vcc
	v_add_co_u32_e32 v6, vcc, 0x32000, v2
	s_nop 1
	v_addc_co_u32_e32 v7, vcc, 0, v3, vcc
	v_add_co_u32_e32 v8, vcc, 0x34000, v2
	s_nop 1
	v_addc_co_u32_e32 v9, vcc, 0, v3, vcc
	v_add_co_u32_e32 v46, vcc, 0x36000, v2
	s_nop 1
	v_addc_co_u32_e32 v47, vcc, 0, v3, vcc
	v_add_co_u32_e32 v64, vcc, 0x38000, v2
	s_nop 1
	v_addc_co_u32_e32 v65, vcc, 0, v3, vcc
	v_add_co_u32_e32 v66, vcc, 0x3a000, v2
	s_nop 1
	v_addc_co_u32_e32 v67, vcc, 0, v3, vcc
	v_add_co_u32_e32 v68, vcc, 0x3c000, v2
	s_nop 1
	v_addc_co_u32_e32 v69, vcc, 0, v3, vcc
	v_add_co_u32_e32 v2, vcc, 0x3e000, v2
	s_nop 1
	v_addc_co_u32_e32 v3, vcc, 0, v3, vcc
	global_load_dword v4, v[4:5], off nt
	s_nop 0
	global_load_dword v5, v[6:7], off nt
	s_nop 0
	global_load_dword v6, v[8:9], off nt
	global_load_dword v7, v[46:47], off nt
	s_nop 0
	global_load_dword v8, v[64:65], off nt
	global_load_dword v9, v[66:67], off nt
	global_load_dword v46, v[68:69], off nt
	s_nop 0
	global_load_dword v2, v[2:3], off nt
	s_waitcnt vmcnt(30)
	ds_write2_b32 v49, v10, v72 offset1:66
	s_waitcnt vmcnt(28)
	ds_write2_b32 v49, v73, v74 offset0:132 offset1:198
	s_waitcnt vmcnt(26)
	ds_write2_b32 v57, v75, v76 offset0:8 offset1:74
	s_waitcnt vmcnt(24)
	ds_write2_b32 v57, v77, v78 offset0:140 offset1:206
	s_waitcnt vmcnt(22)
	ds_write2_b32 v58, v79, v80 offset0:16 offset1:82
	s_waitcnt vmcnt(20)
	ds_write2_b32 v58, v81, v82 offset0:148 offset1:214
	s_waitcnt vmcnt(18)
	ds_write2_b32 v59, v83, v84 offset0:24 offset1:90
	s_waitcnt vmcnt(16)
	ds_write2_b32 v59, v85, v86 offset0:156 offset1:222
	s_waitcnt vmcnt(14)
	ds_write2_b32 v60, v87, v88 offset0:32 offset1:98
	s_waitcnt vmcnt(12)
	ds_write2_b32 v60, v89, v90 offset0:164 offset1:230
	s_waitcnt vmcnt(10)
	ds_write2_b32 v61, v91, v92 offset0:40 offset1:106
	s_waitcnt vmcnt(8)
	ds_write2_b32 v61, v93, v70 offset0:172 offset1:238
	s_waitcnt vmcnt(6)
	ds_write2_b32 v62, v4, v5 offset0:48 offset1:114
	s_waitcnt vmcnt(4)
	ds_write2_b32 v62, v6, v7 offset0:180 offset1:246
	s_waitcnt vmcnt(2)
	ds_write2_b32 v63, v8, v9 offset0:56 offset1:122
	s_waitcnt vmcnt(0)
	ds_write2_b32 v63, v46, v2 offset0:188 offset1:254
	s_waitcnt lgkmcnt(0)
	ds_read2_b32 v[6:7], v51 offset1:8
	ds_read2_b32 v[46:47], v51 offset0:33 offset1:41
	ds_read2_b32 v[64:65], v51 offset0:66 offset1:74
	ds_read2_b32 v[66:67], v51 offset0:99 offset1:107
	ds_read2_b32 v[68:69], v51 offset0:132 offset1:140
	s_waitcnt lgkmcnt(4)
	v_bfe_u32 v2, v6, 16, 1
	v_add3_u32 v2, v6, v2, s89
	s_waitcnt lgkmcnt(3)
	v_bfe_u32 v3, v46, 16, 1
	v_lshrrev_b32_e32 v2, 16, v2
	v_add3_u32 v3, v46, v3, s89
	ds_read2_b32 v[70:71], v51 offset0:165 offset1:173
	v_and_or_b32 v2, v3, s90, v2
	s_waitcnt lgkmcnt(3)
	v_bfe_u32 v3, v64, 16, 1
	v_add3_u32 v3, v64, v3, s89
	s_waitcnt lgkmcnt(2)
	v_bfe_u32 v4, v66, 16, 1
	ds_read2_b32 v[72:73], v51 offset0:198 offset1:206
	v_lshrrev_b32_e32 v3, 16, v3
	v_add3_u32 v4, v66, v4, s89
	ds_read2_b32 v[74:75], v51 offset0:231 offset1:239
	v_and_or_b32 v3, v4, s90, v3
	s_waitcnt lgkmcnt(3)
	v_bfe_u32 v4, v68, 16, 1
	v_add3_u32 v4, v68, v4, s89
	s_waitcnt lgkmcnt(2)
	v_bfe_u32 v5, v70, 16, 1
	v_lshrrev_b32_e32 v4, 16, v4
	v_add3_u32 v5, v70, v5, s89
	v_and_or_b32 v4, v5, s90, v4
	s_waitcnt lgkmcnt(1)
	v_bfe_u32 v5, v72, 16, 1
	v_add3_u32 v5, v72, v5, s89
	s_waitcnt lgkmcnt(0)
	v_bfe_u32 v6, v74, 16, 1
	v_lshrrev_b32_e32 v5, 16, v5
	v_add3_u32 v6, v74, v6, s89
	v_and_or_b32 v5, v6, s90, v5
	v_or_b32_e32 v6, s4, v50
	v_lshl_add_u64 v[8:9], v[36:37], 0, s[26:27]
	v_lshlrev_b32_e32 v10, 11, v6
	v_lshl_add_u64 v[76:77], v[8:9], 0, v[10:11]
	global_store_dwordx4 v[76:77], v[2:5], off
	v_bfe_u32 v6, v75, 16, 1
	v_or_b32_e32 v10, s4, v52
	v_bfe_u32 v2, v7, 16, 1
	v_add3_u32 v2, v7, v2, s89
	v_bfe_u32 v3, v47, 16, 1
	v_lshrrev_b32_e32 v2, 16, v2
	v_add3_u32 v3, v47, v3, s89
	v_and_or_b32 v2, v3, s90, v2
	v_bfe_u32 v3, v65, 16, 1
	v_add3_u32 v3, v65, v3, s89
	v_bfe_u32 v4, v67, 16, 1
	v_lshrrev_b32_e32 v3, 16, v3
	v_add3_u32 v4, v67, v4, s89
	v_and_or_b32 v3, v4, s90, v3
	v_bfe_u32 v4, v69, 16, 1
	v_add3_u32 v4, v69, v4, s89
	v_bfe_u32 v5, v71, 16, 1
	v_lshrrev_b32_e32 v4, 16, v4
	v_add3_u32 v5, v71, v5, s89
	v_and_or_b32 v4, v5, s90, v4
	v_bfe_u32 v5, v73, 16, 1
	v_add3_u32 v5, v73, v5, s89
	v_lshrrev_b32_e32 v5, 16, v5
	v_add3_u32 v6, v75, v6, s89
	v_lshlrev_b32_e32 v10, 11, v10
	v_and_or_b32 v5, v6, s90, v5
	ds_read2_b32 v[6:7], v51 offset0:16 offset1:24
	v_lshl_add_u64 v[46:47], v[8:9], 0, v[10:11]
	global_store_dwordx4 v[46:47], v[2:5], off
	ds_read2_b32 v[46:47], v51 offset0:49 offset1:57
	ds_read2_b32 v[64:65], v51 offset0:82 offset1:90
	ds_read2_b32 v[66:67], v51 offset0:115 offset1:123
	s_waitcnt lgkmcnt(3)
	v_bfe_u32 v2, v6, 16, 1
	v_add3_u32 v2, v6, v2, s89
	s_waitcnt lgkmcnt(2)
	v_bfe_u32 v3, v46, 16, 1
	ds_read2_b32 v[68:69], v51 offset0:148 offset1:156
	v_lshrrev_b32_e32 v2, 16, v2
	v_add3_u32 v3, v46, v3, s89
	ds_read2_b32 v[70:71], v51 offset0:181 offset1:189
	v_and_or_b32 v2, v3, s90, v2
	s_waitcnt lgkmcnt(3)
	v_bfe_u32 v3, v64, 16, 1
	v_add3_u32 v3, v64, v3, s89
	s_waitcnt lgkmcnt(2)
	v_bfe_u32 v4, v66, 16, 1
	ds_read2_b32 v[72:73], v51 offset0:214 offset1:222
	v_lshrrev_b32_e32 v3, 16, v3
	v_add3_u32 v4, v66, v4, s89
	ds_read2_b32 v[74:75], v51 offset0:247 offset1:255
	v_and_or_b32 v3, v4, s90, v3
	s_waitcnt lgkmcnt(3)
	v_bfe_u32 v4, v68, 16, 1
	v_add3_u32 v4, v68, v4, s89
	s_waitcnt lgkmcnt(2)
	v_bfe_u32 v5, v70, 16, 1
	v_lshrrev_b32_e32 v4, 16, v4
	v_add3_u32 v5, v70, v5, s89
	v_and_or_b32 v4, v5, s90, v4
	s_waitcnt lgkmcnt(1)
	v_bfe_u32 v5, v72, 16, 1
	v_add3_u32 v5, v72, v5, s89
	s_waitcnt lgkmcnt(0)
	v_bfe_u32 v6, v74, 16, 1
	v_lshrrev_b32_e32 v5, 16, v5
	v_add3_u32 v6, v74, v6, s89
	v_and_or_b32 v5, v6, s90, v5
	v_or_b32_e32 v6, s4, v53
	v_lshlrev_b32_e32 v10, 11, v6
	v_lshl_add_u64 v[76:77], v[8:9], 0, v[10:11]
	global_store_dwordx4 v[76:77], v[2:5], off
	v_bfe_u32 v6, v75, 16, 1
	v_add3_u32 v6, v75, v6, s89
	v_bfe_u32 v2, v7, 16, 1
	v_add3_u32 v2, v7, v2, s89
	v_bfe_u32 v3, v47, 16, 1
	v_lshrrev_b32_e32 v2, 16, v2
	v_add3_u32 v3, v47, v3, s89
	v_and_or_b32 v2, v3, s90, v2
	v_bfe_u32 v3, v65, 16, 1
	v_add3_u32 v3, v65, v3, s89
	v_bfe_u32 v4, v67, 16, 1
	v_lshrrev_b32_e32 v3, 16, v3
	v_add3_u32 v4, v67, v4, s89
	v_and_or_b32 v3, v4, s90, v3
	v_bfe_u32 v4, v69, 16, 1
	v_add3_u32 v4, v69, v4, s89
	v_bfe_u32 v5, v71, 16, 1
	v_lshrrev_b32_e32 v4, 16, v4
	v_add3_u32 v5, v71, v5, s89
	v_and_or_b32 v4, v5, s90, v4
	v_bfe_u32 v5, v73, 16, 1
	v_add3_u32 v5, v73, v5, s89
	v_lshrrev_b32_e32 v5, 16, v5
	v_and_or_b32 v5, v6, s90, v5
	v_or_b32_e32 v6, s4, v54
	v_lshlrev_b32_e32 v10, 11, v6
	v_lshl_add_u64 v[6:7], v[8:9], 0, v[10:11]
	global_store_dwordx4 v[6:7], v[2:5], off
	s_waitcnt lgkmcnt(0)

.LBB0_102:
	s_andn2_b64 vcc, exec, s[28:29]
	s_cbranch_vccnz .LBB0_34
	s_mul_hi_i32 s4, s18, 0x2aaaaaab
	s_lshr_b32 s5, s4, 31
	s_ashr_i32 s4, s4, 4
	s_add_i32 s5, s4, s5
	s_mul_i32 s4, s5, 0xfffff400
	s_lshl_b32 s28, s5, 6
	s_add_i32 s4, s4, s3
	v_add_u32_e32 v4, s4, v1
	v_or_b32_e32 v5, s28, v48
	v_mov_b64_e32 v[2:3], s[58:59]
	s_movk_i32 s26, 0x3040
	v_mad_i64_i32 v[2:3], s[74:75], v5, s26, v[2:3]
	v_max_i32_e32 v10, 0, v4
	v_lshl_add_u64 v[2:3], v[10:11], 2, v[2:3]
	v_add_co_u32_e32 v4, vcc, s35, v2
	s_mov_b32 s26, 0x42000
	s_nop 0
	v_addc_co_u32_e32 v5, vcc, 0, v3, vcc
	v_add_co_u32_e32 v6, vcc, s42, v2
	s_mulk_i32 s5, 0xffa0
	s_nop 0
	v_addc_co_u32_e32 v7, vcc, 0, v3, vcc
	v_add_co_u32_e32 v8, vcc, s53, v2
	s_add_i32 s5, s18, s5
	s_nop 0
	v_addc_co_u32_e32 v9, vcc, 0, v3, vcc
	v_add_co_u32_e32 v46, vcc, s54, v2
	s_cmp_lt_i32 s5, 0
	s_nop 0
	v_addc_co_u32_e32 v47, vcc, 0, v3, vcc
	v_add_co_u32_e32 v64, vcc, s55, v2
	s_cselect_b64 s[74:75], -1, 0
	s_nop 0
	v_addc_co_u32_e32 v65, vcc, 0, v3, vcc
	v_add_co_u32_e32 v66, vcc, s60, v2
	s_ashr_i32 s29, s28, 31
	s_nop 0
	v_addc_co_u32_e32 v67, vcc, 0, v3, vcc
	v_add_co_u32_e32 v68, vcc, s61, v2
	s_nop 1
	v_addc_co_u32_e32 v69, vcc, 0, v3, vcc
	global_load_dword v10, v[2:3], off nt
	global_load_dword v72, v[4:5], off offset:128 nt
	global_load_dword v73, v[6:7], off offset:256 nt
	global_load_dword v74, v[8:9], off offset:384 nt
	global_load_dword v75, v[46:47], off offset:512 nt
	global_load_dword v76, v[64:65], off offset:640 nt
	global_load_dword v77, v[66:67], off offset:768 nt
	global_load_dword v78, v[68:69], off offset:896 nt
	v_add_co_u32_e32 v4, vcc, s64, v2
	s_nop 1
	v_addc_co_u32_e32 v5, vcc, 0, v3, vcc
	v_add_co_u32_e32 v6, vcc, s65, v2
	s_nop 1
	v_addc_co_u32_e32 v7, vcc, 0, v3, vcc
	v_add_co_u32_e32 v8, vcc, s88, v2
	s_nop 1
	v_addc_co_u32_e32 v9, vcc, 0, v3, vcc
	v_add_co_u32_e32 v46, vcc, s26, v2
	s_mov_b32 s26, 0x4e000
	s_nop 0
	v_addc_co_u32_e32 v47, vcc, 0, v3, vcc
	v_add_co_u32_e32 v64, vcc, s91, v2
	s_nop 1
	v_addc_co_u32_e32 v65, vcc, 0, v3, vcc
	v_add_co_u32_e32 v66, vcc, s26, v2
	s_mov_b32 s26, 0x54000
	s_nop 0
	v_addc_co_u32_e32 v67, vcc, 0, v3, vcc
	v_add_co_u32_e32 v68, vcc, s26, v2
	s_mov_b32 s26, 0x5a000
	s_nop 0
	v_addc_co_u32_e32 v69, vcc, 0, v3, vcc
	v_add_co_u32_e32 v70, vcc, s26, v2
	s_mov_b32 s26, 0x60000
	s_nop 0
	v_addc_co_u32_e32 v71, vcc, 0, v3, vcc
	global_load_dword v79, v[4:5], off offset:1024 nt
	global_load_dword v80, v[6:7], off offset:1152 nt
	global_load_dword v81, v[8:9], off offset:1280 nt
	global_load_dword v82, v[46:47], off offset:1408 nt
	global_load_dword v83, v[64:65], off offset:1536 nt
	global_load_dword v84, v[66:67], off offset:1664 nt
	global_load_dword v85, v[68:69], off offset:1792 nt
	global_load_dword v86, v[70:71], off offset:1920 nt
	v_add_co_u32_e32 v4, vcc, s26, v2
	s_mov_b32 s26, 0x66000
	s_nop 0
	v_addc_co_u32_e32 v5, vcc, 0, v3, vcc
	v_add_co_u32_e32 v6, vcc, s26, v2
	s_mov_b32 s26, 0x6c000
	s_nop 0
	v_addc_co_u32_e32 v7, vcc, 0, v3, vcc
	v_add_co_u32_e32 v8, vcc, s26, v2
	s_mov_b32 s26, 0x72000
	s_nop 0
	v_addc_co_u32_e32 v9, vcc, 0, v3, vcc
	v_add_co_u32_e32 v46, vcc, s26, v2
	s_mov_b32 s26, 0x78000
	s_nop 0
	v_addc_co_u32_e32 v47, vcc, 0, v3, vcc
	v_add_co_u32_e32 v64, vcc, s26, v2
	s_mov_b32 s26, 0x7e000
	s_nop 0
	v_addc_co_u32_e32 v65, vcc, 0, v3, vcc
	v_add_co_u32_e32 v66, vcc, s26, v2
	s_mov_b32 s26, 0x84000
	s_nop 0
	v_addc_co_u32_e32 v67, vcc, 0, v3, vcc
	v_add_co_u32_e32 v68, vcc, s26, v2
	s_mov_b32 s26, 0x8a000
	s_nop 0
	v_addc_co_u32_e32 v69, vcc, 0, v3, vcc
	v_add_co_u32_e32 v70, vcc, s26, v2
	s_mov_b32 s26, 0x90000
	s_nop 0
	v_addc_co_u32_e32 v71, vcc, 0, v3, vcc
	global_load_dword v87, v[4:5], off offset:2048 nt
	global_load_dword v88, v[6:7], off offset:2176 nt
	global_load_dword v89, v[8:9], off offset:2304 nt
	global_load_dword v90, v[46:47], off offset:2432 nt
	global_load_dword v91, v[64:65], off offset:2560 nt
	global_load_dword v92, v[66:67], off offset:2688 nt
	s_nop 0
	global_load_dword v68, v[68:69], off offset:2816 nt
	s_nop 0
	global_load_dword v69, v[70:71], off offset:2944 nt
	v_add_co_u32_e32 v4, vcc, s26, v2
	s_mov_b32 s26, 0x96000
	s_nop 0
	v_addc_co_u32_e32 v5, vcc, 0, v3, vcc
	v_add_co_u32_e32 v6, vcc, s26, v2
	s_mov_b32 s26, 0x9c000
	s_nop 0
	v_addc_co_u32_e32 v7, vcc, 0, v3, vcc
	v_add_co_u32_e32 v8, vcc, s26, v2
	s_mov_b32 s26, 0xa2000
	s_nop 0
	v_addc_co_u32_e32 v9, vcc, 0, v3, vcc
	v_add_co_u32_e32 v46, vcc, s26, v2
	s_mov_b32 s26, 0xa8000
	s_nop 0
	v_addc_co_u32_e32 v47, vcc, 0, v3, vcc
	v_add_co_u32_e32 v64, vcc, s26, v2
	s_mov_b32 s26, 0xae000
	s_nop 0
	v_addc_co_u32_e32 v65, vcc, 0, v3, vcc
	v_add_co_u32_e32 v66, vcc, s26, v2
	s_mov_b32 s26, 0xb4000
	s_nop 0
	v_addc_co_u32_e32 v67, vcc, 0, v3, vcc
	global_load_dword v70, v[4:5], off offset:3072 nt
	s_nop 0
	global_load_dword v6, v[6:7], off offset:3200 nt
	s_nop 0
	global_load_dword v7, v[8:9], off offset:3328 nt
	s_nop 0
	global_load_dword v8, v[46:47], off offset:3456 nt
	global_load_dword v9, v[64:65], off offset:3584 nt
	s_nop 0
	global_load_dword v46, v[66:67], off offset:3712 nt
	v_add_co_u32_e32 v4, vcc, s26, v2
	s_nop 1
	v_addc_co_u32_e32 v5, vcc, 0, v3, vcc
	v_add_co_u32_e32 v2, vcc, s85, v2
	s_nop 1
	v_addc_co_u32_e32 v3, vcc, 0, v3, vcc
	global_load_dword v4, v[4:5], off offset:3840 nt
	s_nop 0
	global_load_dword v3, v[2:3], off offset:3968 nt
	v_cndmask_b32_e64 v5, 1.0, 0, s[74:75]
	s_waitcnt vmcnt(31)
	v_mul_f32_e32 v10, v5, v10
	s_waitcnt vmcnt(30)
	v_mul_f32_e32 v47, v5, v72
	ds_write2_b32 v49, v10, v47 offset1:66
	s_waitcnt vmcnt(29)
	v_mul_f32_e32 v10, v5, v73
	s_waitcnt vmcnt(28)
	v_mul_f32_e32 v47, v5, v74
	ds_write2_b32 v49, v10, v47 offset0:132 offset1:198
	s_waitcnt vmcnt(27)
	v_mul_f32_e32 v10, v5, v75
	s_waitcnt vmcnt(26)
	v_mul_f32_e32 v47, v5, v76
	ds_write2_b32 v57, v10, v47 offset0:8 offset1:74
	s_waitcnt vmcnt(25)
	v_mul_f32_e32 v10, v5, v77
	s_waitcnt vmcnt(24)
	v_mul_f32_e32 v47, v5, v78
	ds_write2_b32 v57, v10, v47 offset0:140 offset1:206
	s_waitcnt vmcnt(23)
	v_mul_f32_e32 v10, v5, v79
	s_waitcnt vmcnt(22)
	v_mul_f32_e32 v47, v5, v80
	ds_write2_b32 v58, v10, v47 offset0:16 offset1:82
	s_waitcnt vmcnt(21)
	v_mul_f32_e32 v10, v5, v81
	s_waitcnt vmcnt(20)
	v_mul_f32_e32 v47, v5, v82
	ds_write2_b32 v58, v10, v47 offset0:148 offset1:214
	s_waitcnt vmcnt(19)
	v_mul_f32_e32 v10, v5, v83
	s_waitcnt vmcnt(18)
	v_mul_f32_e32 v47, v5, v84
	ds_write2_b32 v59, v10, v47 offset0:24 offset1:90
	s_waitcnt vmcnt(17)
	v_mul_f32_e32 v10, v5, v85
	s_waitcnt vmcnt(16)
	v_mul_f32_e32 v47, v5, v86
	ds_write2_b32 v59, v10, v47 offset0:156 offset1:222
	v_mov_b32_e32 v2, 1.0
	s_andn2_b64 vcc, exec, s[24:25]
	s_waitcnt vmcnt(15)
	v_mul_f32_e32 v10, v5, v87
	s_waitcnt vmcnt(14)
	v_mul_f32_e32 v47, v5, v88
	ds_write2_b32 v60, v10, v47 offset0:32 offset1:98
	s_waitcnt vmcnt(13)
	v_mul_f32_e32 v10, v5, v89
	s_waitcnt vmcnt(12)
	v_mul_f32_e32 v47, v5, v90
	ds_write2_b32 v60, v10, v47 offset0:164 offset1:230
	s_waitcnt vmcnt(11)
	v_mul_f32_e32 v10, v5, v91
	s_waitcnt vmcnt(10)
	v_mul_f32_e32 v47, v5, v92
	ds_write2_b32 v61, v10, v47 offset0:40 offset1:106
	s_waitcnt vmcnt(9)
	v_mul_f32_e32 v10, v5, v68
	s_waitcnt vmcnt(8)
	v_mul_f32_e32 v47, v5, v69
	ds_write2_b32 v61, v10, v47 offset0:172 offset1:238
	v_mov_b32_e32 v47, 1.0
	s_waitcnt vmcnt(7)
	v_mul_f32_e32 v10, v5, v70
	s_waitcnt vmcnt(6)
	v_mul_f32_e32 v6, v5, v6
	ds_write2_b32 v62, v10, v6 offset0:48 offset1:114
	s_waitcnt vmcnt(5)
	v_mul_f32_e32 v6, v5, v7
	s_waitcnt vmcnt(4)
	v_mul_f32_e32 v7, v5, v8
	ds_write2_b32 v62, v6, v7 offset0:180 offset1:246
	s_waitcnt vmcnt(3)
	v_mul_f32_e32 v6, v5, v9
	s_waitcnt vmcnt(2)
	v_mul_f32_e32 v7, v5, v46
	ds_write2_b32 v63, v6, v7 offset0:56 offset1:122
	v_mov_b32_e32 v46, 1.0
	v_mov_b32_e32 v6, 1.0
	v_mov_b32_e32 v7, 1.0
	s_waitcnt vmcnt(1)
	v_mul_f32_e32 v4, v5, v4
	s_waitcnt vmcnt(0)
	v_mul_f32_e32 v3, v5, v3
	ds_write2_b32 v63, v4, v3 offset0:188 offset1:254
	v_mov_b32_e32 v3, 1.0
	v_mov_b32_e32 v4, 1.0
	v_mov_b32_e32 v5, 1.0
	s_cbranch_vccnz .LBB0_33
	v_lshl_add_u64 v[6:7], s[28:29], 2, v[32:33]
	global_load_dwordx4 v[2:5], v[6:7], off
	s_nop 0
	global_load_dwordx4 v[6:9], v[6:7], off offset:16
	s_waitcnt vmcnt(1)
	v_mov_b32_e32 v46, v3
	v_mov_b32_e32 v3, v4
	v_mov_b32_e32 v47, v5
	s_waitcnt vmcnt(0)
	v_mov_b32_e32 v4, v7
	v_mov_b32_e32 v7, v8
	v_mov_b32_e32 v5, v9
	s_branch .LBB0_33
